# mode-1 out-proj epilogue rewritten: LN stats preloaded, 4 batches of 8 residual loads in flight, stores asynchronous (was 32 serialized round trips per tile)
# speedup vs baseline: 1.0392x; 1.0188x over previous
; #define PG8_STAGE(bufoff, gbase, voff) do { _Pragma("unroll") for (int _i = 0; _i < 2; ++_i) \
;         __builtin_amdgcn_global_load_lds((const unsigned*)((const char*)(gbase) + (voff)[_i]), (LAS unsigned*)(lds + (bufoff) + ldsw + _i * 8192), 16, 0, 0); } while (0)
; #define PG8_LDA(dst, b, h) do { _Pragma("unroll") for (int m = 0; m < 4; ++m) _Pragma("unroll") for (int k = 0; k < 2; ++k) dst[m][k] = *(const LAS bf16x8*)(lds + PG8_SA(b, h) + aoff + m * 2048 + k * 1024); } while (0)
; #define PG8_LDB(dst, b, h) do { _Pragma("unroll") for (int n = 0; n < 2; ++n) _Pragma("unroll") for (int k = 0; k < 2; ++k) dst[n][k] = *(const LAS bf16x8*)(lds + PG8_SB(b, h) + boff + n * 2048 + k * 1024); } while (0)
; #define PG8_MMA(ai, bj, At, Bt) do { __builtin_amdgcn_s_setprio(1); _Pragma("unroll") for (int m = 0; m < 4; ++m) _Pragma("unroll") for (int n = 0; n < 2; ++n) _Pragma("unroll") for (int k = 0; k < 2; ++k) \
;         acc[ai][bj][m][n] = __builtin_amdgcn_mfma_f32_16x16x32_bf16(Bt[n][k], At[m][k], acc[ai][bj][m][n], 0, 0, 0); __builtin_amdgcn_s_setprio(0); } while (0)
; #define PG8_WAIT_V(n) asm volatile("s_waitcnt vmcnt(" #n ")" ::: "memory")
; template <class Epi>
; DI void gemm_phase(LAS unsigned char* lds, const Gemm g, const StaticOrder& S, const Epi& E) {
;     ...
;         for (int t = 0; t < nt; t += 2) {
;             const bool last = (t == nt - 2);
;             const char* a1 = cA + (size_t)(t + 1) * kstep;
;             const char* a2 = last ? nA : cA + (size_t)(t + 2) * kstep; const char* b2 = last ? nB : cB + (size_t)(t + 2) * kstep;
;             const char* a3 = a2 + kstep; const char* b3 = b2 + kstep;
;             PG8_LDB(B0, 0, 0); PG8_SCHED; PG8_LDA(At, 0, 0); PG8_STAGE(PG8_SA(1, 1), a1 + hstepA, voffA);
;             PG8_WAIT_L(8); PG8_BAR; PG8_WAIT_L(0); PG8_MMA(0, 0, At, B0); PG8_BAR; PG8_SCHED;
;             PG8_LDB(B1, 0, 1); PG8_STAGE(PG8_SB(0, 0), b2, voffB);
;             PG8_BAR; PG8_WAIT_L(0); PG8_MMA(0, 1, At, B1); PG8_BAR;
;             PG8_LDA(At, 0, 1); PG8_STAGE(PG8_SA(0, 0), a2, voffA);
;             PG8_BAR; PG8_WAIT_L(0); PG8_MMA(1, 0, At, B0); PG8_BAR; PG8_SCHED;
;             PG8_STAGE(PG8_SB(0, 1), b2 + hstepB, voffB);
;             PG8_WAIT_V(6); PG8_BAR; PG8_MMA(1, 1, At, B1); PG8_BAR;
;             PG8_LDB(B0, 1, 0); PG8_SCHED; PG8_LDA(At, 1, 0); PG8_STAGE(PG8_SA(0, 1), a2 + hstepA, voffA);
.LBB0_1292:
	ds_read_b128 v[130:133], v171
	ds_read_b128 v[134:137], v171 offset:1024
	ds_read_b128 v[138:141], v171 offset:2048
	ds_read_b128 v[142:145], v171 offset:3072
	s_add_u32 s28, s6, 0xffefc080
	s_addc_u32 s29, s7, -1
	s_cmp_eq_u32 s69, 28
	s_cselect_b32 s31, s25, s29
	s_cselect_b32 s30, s24, s28
	s_cselect_b32 s29, s23, s68
	s_cselect_b32 s28, s66, s67
	v_lshl_add_u64 v[214:215], s[6:7], 0, v[198:199]
	s_add_i32 m0, s39, 0xc000
	ds_read_b128 v[146:149], v175
	ds_read_b128 v[150:153], v175 offset:1024
	ds_read_b128 v[154:157], v175 offset:2048
	ds_read_b128 v[206:209], v175 offset:3072
	ds_read_b128 v[210:213], v175 offset:4096
	ds_read_b128 v[218:221], v175 offset:5120
	ds_read_b128 v[222:225], v175 offset:6144
	ds_read_b128 v[226:229], v175 offset:7168
	global_load_lds_dwordx4 v[214:215], off
	v_lshl_add_u64 v[214:215], s[6:7], 0, v[200:201]
	s_add_i32 m0, s39, 0xe000
	s_nop 0
	global_load_lds_dwordx4 v[214:215], off
	ds_read_b128 v[230:233], v179
	ds_read_b128 v[234:237], v179 offset:1024
	ds_read_b128 v[238:241], v179 offset:2048
	ds_read_b128 v[242:245], v179 offset:3072
	s_waitcnt lgkmcnt(0)
	s_waitcnt vmcnt(8)
	s_barrier
	s_setprio 1
	v_mfma_f32_16x16x32_bf16 v[126:129], v[130:133], v[146:149], v[126:129]
	v_mfma_f32_16x16x32_bf16 v[102:105], v[138:141], v[146:149], v[102:105]
	v_mfma_f32_16x16x32_bf16 v[122:125], v[130:133], v[154:157], v[122:125]
	v_mfma_f32_16x16x32_bf16 v[94:97], v[138:141], v[154:157], v[94:97]
	v_mfma_f32_16x16x32_bf16 v[118:121], v[130:133], v[210:213], v[118:121]
	v_mfma_f32_16x16x32_bf16 v[86:89], v[138:141], v[210:213], v[86:89]
	v_mfma_f32_16x16x32_bf16 v[114:117], v[130:133], v[222:225], v[114:117]
	v_mfma_f32_16x16x32_bf16 v[82:85], v[138:141], v[222:225], v[82:85]
	v_mfma_f32_16x16x32_bf16 v[126:129], v[134:137], v[150:153], v[126:129]
	v_mfma_f32_16x16x32_bf16 v[102:105], v[142:145], v[150:153], v[102:105]
	v_mfma_f32_16x16x32_bf16 v[122:125], v[134:137], v[206:209], v[122:125]
	v_mfma_f32_16x16x32_bf16 v[94:97], v[142:145], v[206:209], v[94:97]
	v_mfma_f32_16x16x32_bf16 v[118:121], v[134:137], v[218:221], v[118:121]
	v_mfma_f32_16x16x32_bf16 v[86:89], v[142:145], v[218:221], v[86:89]
	v_mfma_f32_16x16x32_bf16 v[114:117], v[134:137], v[226:229], v[114:117]
	v_mfma_f32_16x16x32_bf16 v[82:85], v[142:145], v[226:229], v[82:85]
	v_mfma_f32_16x16x32_bf16 v[66:69], v[230:233], v[146:149], v[66:69]
	v_mfma_f32_16x16x32_bf16 v[38:41], v[238:241], v[146:149], v[38:41]
	v_mfma_f32_16x16x32_bf16 v[58:61], v[230:233], v[154:157], v[58:61]
	v_mfma_f32_16x16x32_bf16 v[30:33], v[238:241], v[154:157], v[30:33]
	v_mfma_f32_16x16x32_bf16 v[54:57], v[230:233], v[210:213], v[54:57]
	v_mfma_f32_16x16x32_bf16 v[22:25], v[238:241], v[210:213], v[22:25]
	v_mfma_f32_16x16x32_bf16 v[50:53], v[230:233], v[222:225], v[50:53]
	v_mfma_f32_16x16x32_bf16 v[18:21], v[238:241], v[222:225], v[18:21]
	v_mfma_f32_16x16x32_bf16 v[66:69], v[234:237], v[150:153], v[66:69]
	v_mfma_f32_16x16x32_bf16 v[38:41], v[242:245], v[150:153], v[38:41]
	v_mfma_f32_16x16x32_bf16 v[58:61], v[234:237], v[206:209], v[58:61]
	v_mfma_f32_16x16x32_bf16 v[30:33], v[242:245], v[206:209], v[30:33]
	v_mfma_f32_16x16x32_bf16 v[54:57], v[234:237], v[218:221], v[54:57]
	v_mfma_f32_16x16x32_bf16 v[22:25], v[242:245], v[218:221], v[22:25]
	v_mfma_f32_16x16x32_bf16 v[50:53], v[234:237], v[226:229], v[50:53]
	v_mfma_f32_16x16x32_bf16 v[18:21], v[242:245], v[226:229], v[18:21]
	s_setprio 0
	s_barrier
	s_add_i32 s70, s60, s38
	v_lshl_add_u64 v[214:215], s[28:29], 0, v[160:161]
	s_mov_b32 m0, s70
	s_nop 0
	global_load_lds_dwordx4 v[214:215], off
	v_lshl_add_u64 v[216:217], s[28:29], 0, v[164:165]
	s_add_i32 m0, s70, 0x2000
	s_nop 0
	global_load_lds_dwordx4 v[216:217], off
	s_mov_b32 m0, s39
	v_lshl_add_u64 v[246:247], s[30:31], 0, v[158:159]
	ds_read_b128 v[146:149], v175 offset:16384
	ds_read_b128 v[150:153], v175 offset:17408
	ds_read_b128 v[154:157], v175 offset:18432
	ds_read_b128 v[206:209], v175 offset:19456
	ds_read_b128 v[210:213], v175 offset:20480
	ds_read_b128 v[218:221], v175 offset:21504
	ds_read_b128 v[222:225], v175 offset:22528
	ds_read_b128 v[226:229], v175 offset:23552
	global_load_lds_dwordx4 v[246:247], off
	v_lshl_add_u64 v[248:249], s[30:31], 0, v[162:163]
	s_mov_b32 m0, s48
	s_nop 0
	global_load_lds_dwordx4 v[248:249], off
	s_add_u32 s70, s28, 0x80000
	s_addc_u32 s71, s29, 0
	s_add_i32 s72, s61, s38
	v_lshl_add_u64 v[250:251], s[70:71], 0, v[160:161]
	s_mov_b32 m0, s72
	s_nop 0
	global_load_lds_dwordx4 v[250:251], off
	v_lshl_add_u64 v[250:251], s[70:71], 0, v[164:165]
	s_add_i32 m0, s72, 0x2000
	s_nop 0
	global_load_lds_dwordx4 v[250:251], off
	s_waitcnt lgkmcnt(0)
	s_waitcnt vmcnt(8)
	s_barrier
; #define PG8_STAGE(bufoff, gbase, voff) do { _Pragma("unroll") for (int _i = 0; _i < 2; ++_i) \
;         __builtin_amdgcn_global_load_lds((const unsigned*)((const char*)(gbase) + (voff)[_i]), (LAS unsigned*)(lds + (bufoff) + ldsw + _i * 8192), 16, 0, 0); } while (0)
; #define PG8_LDA(dst, b, h) do { _Pragma("unroll") for (int m = 0; m < 4; ++m) _Pragma("unroll") for (int k = 0; k < 2; ++k) dst[m][k] = *(const LAS bf16x8*)(lds + PG8_SA(b, h) + aoff + m * 2048 + k * 1024); } while (0)
; #define PG8_LDB(dst, b, h) do { _Pragma("unroll") for (int n = 0; n < 2; ++n) _Pragma("unroll") for (int k = 0; k < 2; ++k) dst[n][k] = *(const LAS bf16x8*)(lds + PG8_SB(b, h) + boff + n * 2048 + k * 1024); } while (0)
; #define PG8_MMA(ai, bj, At, Bt) do { __builtin_amdgcn_s_setprio(1); _Pragma("unroll") for (int m = 0; m < 4; ++m) _Pragma("unroll") for (int n = 0; n < 2; ++n) _Pragma("unroll") for (int k = 0; k < 2; ++k) \
;         acc[ai][bj][m][n] = __builtin_amdgcn_mfma_f32_16x16x32_bf16(Bt[n][k], At[m][k], acc[ai][bj][m][n], 0, 0, 0); __builtin_amdgcn_s_setprio(0); } while (0)
; #define PG8_WAIT_V(n) asm volatile("s_waitcnt vmcnt(" #n ")" ::: "memory")
; #define PG8_WAIT_L(n) asm volatile("s_waitcnt lgkmcnt(" #n ")" ::: "memory")
; #define PG8_BAR __builtin_amdgcn_s_barrier()
; #define PG8_SCHED __builtin_amdgcn_sched_barrier(0)
; template <class Epi>
; DI void gemm_phase(LAS unsigned char* lds, const Gemm g, const StaticOrder& S, const Epi& E) {
;     ...
;             PG8_BAR; PG8_WAIT_L(0); PG8_MMA(0, 1, At, B1); PG8_BAR;
;             PG8_LDA(At, 0, 1); PG8_STAGE(PG8_SA(0, 0), a2, voffA);
;             PG8_BAR; PG8_WAIT_L(0); PG8_MMA(1, 0, At, B0); PG8_BAR; PG8_SCHED;
;             PG8_STAGE(PG8_SB(0, 1), b2 + hstepB, voffB);
;             PG8_WAIT_V(6); PG8_BAR; PG8_MMA(1, 1, At, B1); PG8_BAR;
;             PG8_LDB(B0, 1, 0); PG8_SCHED; PG8_LDA(At, 1, 0); PG8_STAGE(PG8_SA(0, 1), a2 + hstepA, voffA);
;             PG8_WAIT_L(8); PG8_BAR; PG8_WAIT_L(0); PG8_MMA(0, 0, At, B0); PG8_BAR; PG8_SCHED;
;             PG8_LDB(B1, 1, 1); PG8_STAGE(PG8_SB(1, 0), b3, voffB);
;             PG8_BAR; PG8_WAIT_L(0); PG8_MMA(0, 1, At, B1); PG8_BAR;
	s_setprio 1
	v_mfma_f32_16x16x32_bf16 v[110:113], v[130:133], v[146:149], v[110:113]
	v_mfma_f32_16x16x32_bf16 v[78:81], v[138:141], v[146:149], v[78:81]
	v_mfma_f32_16x16x32_bf16 v[106:109], v[130:133], v[154:157], v[106:109]
	v_mfma_f32_16x16x32_bf16 v[74:77], v[138:141], v[154:157], v[74:77]
	v_mfma_f32_16x16x32_bf16 v[98:101], v[130:133], v[210:213], v[98:101]
	v_mfma_f32_16x16x32_bf16 v[70:73], v[138:141], v[210:213], v[70:73]
	v_mfma_f32_16x16x32_bf16 v[90:93], v[130:133], v[222:225], v[90:93]
	v_mfma_f32_16x16x32_bf16 v[62:65], v[138:141], v[222:225], v[62:65]
	v_mfma_f32_16x16x32_bf16 v[110:113], v[134:137], v[150:153], v[110:113]
	v_mfma_f32_16x16x32_bf16 v[78:81], v[142:145], v[150:153], v[78:81]
	v_mfma_f32_16x16x32_bf16 v[106:109], v[134:137], v[206:209], v[106:109]
	v_mfma_f32_16x16x32_bf16 v[74:77], v[142:145], v[206:209], v[74:77]
	v_mfma_f32_16x16x32_bf16 v[98:101], v[134:137], v[218:221], v[98:101]
	v_mfma_f32_16x16x32_bf16 v[70:73], v[142:145], v[218:221], v[70:73]
	v_mfma_f32_16x16x32_bf16 v[90:93], v[134:137], v[226:229], v[90:93]
	v_mfma_f32_16x16x32_bf16 v[62:65], v[142:145], v[226:229], v[62:65]
	v_mfma_f32_16x16x32_bf16 v[46:49], v[230:233], v[146:149], v[46:49]
	v_mfma_f32_16x16x32_bf16 v[14:17], v[238:241], v[146:149], v[14:17]
	v_mfma_f32_16x16x32_bf16 v[42:45], v[230:233], v[154:157], v[42:45]
	v_mfma_f32_16x16x32_bf16 v[10:13], v[238:241], v[154:157], v[10:13]
	v_mfma_f32_16x16x32_bf16 v[34:37], v[230:233], v[210:213], v[34:37]
	v_mfma_f32_16x16x32_bf16 v[6:9], v[238:241], v[210:213], v[6:9]
	v_mfma_f32_16x16x32_bf16 v[26:29], v[230:233], v[222:225], v[26:29]
	v_mfma_f32_16x16x32_bf16 v[2:5], v[238:241], v[222:225], v[2:5]
	v_mfma_f32_16x16x32_bf16 v[46:49], v[234:237], v[150:153], v[46:49]
	v_mfma_f32_16x16x32_bf16 v[14:17], v[242:245], v[150:153], v[14:17]
	v_mfma_f32_16x16x32_bf16 v[42:45], v[234:237], v[206:209], v[42:45]
	v_mfma_f32_16x16x32_bf16 v[10:13], v[242:245], v[206:209], v[10:13]
	v_mfma_f32_16x16x32_bf16 v[34:37], v[234:237], v[218:221], v[34:37]
	v_mfma_f32_16x16x32_bf16 v[6:9], v[242:245], v[218:221], v[6:9]
	v_mfma_f32_16x16x32_bf16 v[26:29], v[234:237], v[226:229], v[26:29]
	v_mfma_f32_16x16x32_bf16 v[2:5], v[242:245], v[226:229], v[2:5]
	s_setprio 0
	s_add_i32 s70, 0, 0x18000
	v_add_u32_e32 v142, s70, v1
	s_barrier
	ds_read_b128 v[130:133], v142
	ds_read_b128 v[134:137], v142 offset:1024
	ds_read_b128 v[138:141], v142 offset:2048
	ds_read_b128 v[142:145], v142 offset:3072
	s_add_u32 s30, s30, 0x104000
	s_addc_u32 s31, s31, 0
	s_mov_b32 m0, s49
	v_lshl_add_u64 v[230:231], s[30:31], 0, v[158:159]
	ds_read_b128 v[146:149], v175 offset:32768
	ds_read_b128 v[150:153], v175 offset:33792
	ds_read_b128 v[154:157], v175 offset:34816
	ds_read_b128 v[206:209], v175 offset:35840
	ds_read_b128 v[210:213], v175 offset:36864
	ds_read_b128 v[218:221], v175 offset:37888
	ds_read_b128 v[222:225], v175 offset:38912
	ds_read_b128 v[226:229], v175 offset:39936
	global_load_lds_dwordx4 v[230:231], off
	v_lshl_add_u64 v[230:231], s[30:31], 0, v[162:163]
	s_mov_b32 m0, s50
	s_nop 0
	global_load_lds_dwordx4 v[230:231], off
	s_add_i32 s30, 0, 0x1c000
	v_add_u32_e32 v187, s30, v1
	ds_read_b128 v[230:233], v187
	ds_read_b128 v[234:237], v187 offset:1024
	ds_read_b128 v[238:241], v187 offset:2048
	ds_read_b128 v[242:245], v187 offset:3072
	s_waitcnt lgkmcnt(0)
	s_waitcnt vmcnt(8)
	s_barrier
	s_setprio 1
	v_mfma_f32_16x16x32_bf16 v[126:129], v[130:133], v[146:149], v[126:129]
	v_mfma_f32_16x16x32_bf16 v[102:105], v[138:141], v[146:149], v[102:105]
	v_mfma_f32_16x16x32_bf16 v[122:125], v[130:133], v[154:157], v[122:125]
	v_mfma_f32_16x16x32_bf16 v[94:97], v[138:141], v[154:157], v[94:97]
	v_mfma_f32_16x16x32_bf16 v[118:121], v[130:133], v[210:213], v[118:121]
	v_mfma_f32_16x16x32_bf16 v[86:89], v[138:141], v[210:213], v[86:89]
	v_mfma_f32_16x16x32_bf16 v[114:117], v[130:133], v[222:225], v[114:117]
	v_mfma_f32_16x16x32_bf16 v[82:85], v[138:141], v[222:225], v[82:85]
	v_mfma_f32_16x16x32_bf16 v[126:129], v[134:137], v[150:153], v[126:129]
	v_mfma_f32_16x16x32_bf16 v[102:105], v[142:145], v[150:153], v[102:105]
	v_mfma_f32_16x16x32_bf16 v[122:125], v[134:137], v[206:209], v[122:125]
	v_mfma_f32_16x16x32_bf16 v[94:97], v[142:145], v[206:209], v[94:97]
	v_mfma_f32_16x16x32_bf16 v[118:121], v[134:137], v[218:221], v[118:121]
	v_mfma_f32_16x16x32_bf16 v[86:89], v[142:145], v[218:221], v[86:89]
	v_mfma_f32_16x16x32_bf16 v[114:117], v[134:137], v[226:229], v[114:117]
	v_mfma_f32_16x16x32_bf16 v[82:85], v[142:145], v[226:229], v[82:85]
	v_mfma_f32_16x16x32_bf16 v[66:69], v[230:233], v[146:149], v[66:69]
	v_mfma_f32_16x16x32_bf16 v[38:41], v[238:241], v[146:149], v[38:41]
	v_mfma_f32_16x16x32_bf16 v[58:61], v[230:233], v[154:157], v[58:61]
	v_mfma_f32_16x16x32_bf16 v[30:33], v[238:241], v[154:157], v[30:33]
	v_mfma_f32_16x16x32_bf16 v[54:57], v[230:233], v[210:213], v[54:57]
	v_mfma_f32_16x16x32_bf16 v[22:25], v[238:241], v[210:213], v[22:25]
	v_mfma_f32_16x16x32_bf16 v[50:53], v[230:233], v[222:225], v[50:53]
	v_mfma_f32_16x16x32_bf16 v[18:21], v[238:241], v[222:225], v[18:21]
	v_mfma_f32_16x16x32_bf16 v[66:69], v[234:237], v[150:153], v[66:69]
	v_mfma_f32_16x16x32_bf16 v[38:41], v[242:245], v[150:153], v[38:41]
	v_mfma_f32_16x16x32_bf16 v[58:61], v[234:237], v[206:209], v[58:61]
	v_mfma_f32_16x16x32_bf16 v[30:33], v[242:245], v[206:209], v[30:33]
	v_mfma_f32_16x16x32_bf16 v[54:57], v[234:237], v[218:221], v[54:57]
	v_mfma_f32_16x16x32_bf16 v[22:25], v[242:245], v[218:221], v[22:25]
	v_mfma_f32_16x16x32_bf16 v[50:53], v[234:237], v[226:229], v[50:53]
	v_mfma_f32_16x16x32_bf16 v[18:21], v[242:245], v[226:229], v[18:21]
	s_setprio 0
	s_barrier
; #define PG8_STAGE(bufoff, gbase, voff) do { _Pragma("unroll") for (int _i = 0; _i < 2; ++_i) \
;         __builtin_amdgcn_global_load_lds((const unsigned*)((const char*)(gbase) + (voff)[_i]), (LAS unsigned*)(lds + (bufoff) + ldsw + _i * 8192), 16, 0, 0); } while (0)
; #define PG8_LDA(dst, b, h) do { _Pragma("unroll") for (int m = 0; m < 4; ++m) _Pragma("unroll") for (int k = 0; k < 2; ++k) dst[m][k] = *(const LAS bf16x8*)(lds + PG8_SA(b, h) + aoff + m * 2048 + k * 1024); } while (0)
; #define PG8_WAIT_V(n) asm volatile("s_waitcnt vmcnt(" #n ")" ::: "memory")
; #define PG8_WAIT_L(n) asm volatile("s_waitcnt lgkmcnt(" #n ")" ::: "memory")
; #define PG8_BAR __builtin_amdgcn_s_barrier()
; template <class Epi>
; DI void gemm_phase(LAS unsigned char* lds, const Gemm g, const StaticOrder& S, const Epi& E) {
;     ...
;             PG8_BAR; PG8_WAIT_L(0); PG8_MMA(0, 1, At, B1); PG8_BAR;
;             PG8_LDA(At, 1, 1); PG8_STAGE(PG8_SA(1, 0), a3, voffA);
;             PG8_BAR; PG8_WAIT_L(0); PG8_MMA(1, 0, At, B0); PG8_BAR; PG8_SCHED;
;             PG8_STAGE(PG8_SB(1, 1), b3 + hstepB, voffB);
;             PG8_WAIT_V(6); PG8_BAR; PG8_MMA(1, 1, At, B1); PG8_BAR;
;     DI void operator()(const f32x4 (&acc)[2][2][4][2], const pg8::Unit& u, int wr, int wc, int fr, int fq) const {
;         const int rowt = row_base + u.pm * 256, col0 = u.pn * 256 + wc * 32 + 4 * fq, rl = wr * 64 + fr;
;         const int cd = cond_of_row(rowt);
;         const float* gtp = gt0 + (size_t)cd * 6144;
;         float* dbase = rowt < TL ? out + (size_t)rowt * D : ctxv + (size_t)(rowt - TL) * D;
;         const float* sbase = mode ? (const float*)dbase : (rowt < TL ? xin + (size_t)rowt * D : cin + (size_t)(rowt - TL) * D);
; #pragma unroll
;         for (int bj = 0; bj < 2; ++bj) {
;             f32x4 gv[2], gg[2], bb[2], xv[2][8];
; #pragma unroll
;             for (int n = 0; n < 2; ++n) {
;                 const int c = col0 + bj * 128 + n * 16;
;                 gv[n] = *(const f32x4*)(gtp + c);
;                 gg[n] = (f32x4){1.f, 1.f, 1.f, 1.f}; bb[n] = (f32x4){0.f, 0.f, 0.f, 0.f};
;                 if (mode) { gg[n] = *(const f32x4*)(lg + c); bb[n] = *(const f32x4*)(lb + c); }
; #pragma unroll
;                 for (int q = 0; q < 8; ++q) { const int rr = rl + (q >> 2) * 128 + (q & 3) * 16; xv[n][q] = *(const f32x4*)(sbase + (size_t)rr * D + c); }
	s_add_i32 s31, s70, s38
	v_lshl_add_u64 v[214:215], v[214:215], 0, s[18:19]
	s_mov_b32 m0, s31
	s_nop 0
	global_load_lds_dwordx4 v[214:215], off
	v_lshl_add_u64 v[214:215], v[216:217], 0, s[18:19]
	s_add_i32 m0, s31, 0x2000
	s_nop 0
	global_load_lds_dwordx4 v[214:215], off
	s_mov_b32 m0, s57
	v_lshl_add_u64 v[214:215], v[246:247], 0, s[18:19]
	ds_read_b128 v[146:149], v175 offset:49152
	ds_read_b128 v[150:153], v175 offset:50176
	ds_read_b128 v[154:157], v175 offset:51200
	ds_read_b128 v[206:209], v175 offset:52224
	ds_read_b128 v[210:213], v175 offset:53248
	ds_read_b128 v[218:221], v175 offset:54272
	ds_read_b128 v[222:225], v175 offset:55296
	ds_read_b128 v[226:229], v175 offset:56320
	global_load_lds_dwordx4 v[214:215], off
	v_lshl_add_u64 v[214:215], v[248:249], 0, s[18:19]
	s_mov_b32 m0, s58
	s_nop 0
	global_load_lds_dwordx4 v[214:215], off
	s_add_u32 s28, s28, 0x80080
	s_addc_u32 s29, s29, 0
	s_add_i32 s30, s30, s38
	v_lshl_add_u64 v[250:251], s[28:29], 0, v[160:161]
	s_mov_b32 m0, s30
	s_nop 0
	global_load_lds_dwordx4 v[250:251], off
	v_lshl_add_u64 v[250:251], s[28:29], 0, v[164:165]
	s_add_i32 m0, s30, 0x2000
	s_nop 0
	global_load_lds_dwordx4 v[250:251], off
	s_waitcnt lgkmcnt(0)
	s_waitcnt vmcnt(8)
	s_barrier
	s_setprio 1
	v_mfma_f32_16x16x32_bf16 v[110:113], v[130:133], v[146:149], v[110:113]
	v_mfma_f32_16x16x32_bf16 v[78:81], v[138:141], v[146:149], v[78:81]
	v_mfma_f32_16x16x32_bf16 v[106:109], v[130:133], v[154:157], v[106:109]
	v_mfma_f32_16x16x32_bf16 v[74:77], v[138:141], v[154:157], v[74:77]
	v_mfma_f32_16x16x32_bf16 v[98:101], v[130:133], v[210:213], v[98:101]
	v_mfma_f32_16x16x32_bf16 v[70:73], v[138:141], v[210:213], v[70:73]
	v_mfma_f32_16x16x32_bf16 v[90:93], v[130:133], v[222:225], v[90:93]
	v_mfma_f32_16x16x32_bf16 v[62:65], v[138:141], v[222:225], v[62:65]
	v_mfma_f32_16x16x32_bf16 v[110:113], v[134:137], v[150:153], v[110:113]
	v_mfma_f32_16x16x32_bf16 v[78:81], v[142:145], v[150:153], v[78:81]
	v_mfma_f32_16x16x32_bf16 v[106:109], v[134:137], v[206:209], v[106:109]
	v_mfma_f32_16x16x32_bf16 v[74:77], v[142:145], v[206:209], v[74:77]
	v_mfma_f32_16x16x32_bf16 v[98:101], v[134:137], v[218:221], v[98:101]
	v_mfma_f32_16x16x32_bf16 v[70:73], v[142:145], v[218:221], v[70:73]
	v_mfma_f32_16x16x32_bf16 v[90:93], v[134:137], v[226:229], v[90:93]
	v_mfma_f32_16x16x32_bf16 v[62:65], v[142:145], v[226:229], v[62:65]
	v_mfma_f32_16x16x32_bf16 v[46:49], v[230:233], v[146:149], v[46:49]
	v_mfma_f32_16x16x32_bf16 v[14:17], v[238:241], v[146:149], v[14:17]
	v_mfma_f32_16x16x32_bf16 v[42:45], v[230:233], v[154:157], v[42:45]
	v_mfma_f32_16x16x32_bf16 v[10:13], v[238:241], v[154:157], v[10:13]
	v_mfma_f32_16x16x32_bf16 v[34:37], v[230:233], v[210:213], v[34:37]
	v_mfma_f32_16x16x32_bf16 v[6:9], v[238:241], v[210:213], v[6:9]
	v_mfma_f32_16x16x32_bf16 v[26:29], v[230:233], v[222:225], v[26:29]
	v_mfma_f32_16x16x32_bf16 v[2:5], v[238:241], v[222:225], v[2:5]
	v_mfma_f32_16x16x32_bf16 v[46:49], v[234:237], v[150:153], v[46:49]
	v_mfma_f32_16x16x32_bf16 v[14:17], v[242:245], v[150:153], v[14:17]
	v_mfma_f32_16x16x32_bf16 v[42:45], v[234:237], v[206:209], v[42:45]
	v_mfma_f32_16x16x32_bf16 v[10:13], v[242:245], v[206:209], v[10:13]
	v_mfma_f32_16x16x32_bf16 v[34:37], v[234:237], v[218:221], v[34:37]
	v_mfma_f32_16x16x32_bf16 v[6:9], v[242:245], v[218:221], v[6:9]
	v_mfma_f32_16x16x32_bf16 v[26:29], v[234:237], v[226:229], v[26:29]
	v_mfma_f32_16x16x32_bf16 v[2:5], v[242:245], v[226:229], v[2:5]
	s_setprio 0
	s_add_i32 s69, s69, 2
	s_add_u32 s6, s6, 0x100
	s_addc_u32 s7, s7, 0
	s_add_u32 s67, s67, 0x100
	s_addc_u32 s68, s68, 0
	s_cmp_gt_u32 s69, 29
	s_barrier
	s_cbranch_scc0 .LBB0_1292
	s_lshl_b32 s6, s64, 8
	v_sub_co_u32_e32 v131, vcc, s6, v183
	s_and_b64 s[28:29], vcc, exec
	s_cselect_b32 s7, s62, 0x3000
	s_cmp_gt_i32 s64, 63
	s_cselect_b32 s7, s7, 0
	s_lshl_b32 s7, s7, 2
	s_add_u32 s28, s55, s7
	s_addc_u32 s29, s56, 0
	s_ashr_i32 s7, s6, 31
	s_cmpk_lt_i32 s64, 0x80
	v_mov_b32_e32 v132, s7
	s_cselect_b64 vcc, -1, 0
	v_cndmask_b32_e32 v133, 0, v132, vcc
	v_mov_b32_e32 v132, s6
	v_lshl_or_b32 v130, s65, 8, v167
	v_cndmask_b32_e32 v132, v131, v132, vcc
	s_cselect_b32 s31, s9, s54
	s_cselect_b32 s30, s8, s53
	v_lshlrev_b64 v[132:133], 13, v[132:133]
	v_ashrrev_i32_e32 v131, 31, v130
	v_lshl_add_u64 v[132:133], s[30:31], 0, v[132:133]
	v_lshlrev_b64 v[130:131], 2, v[130:131]
	v_lshl_add_u64 v[248:249], s[12:13], 0, v[130:131]
	v_lshl_add_u64 v[250:251], s[14:15], 0, v[130:131]
	v_lshl_add_u64 v[254:255], s[28:29], 0, v[130:131]
	v_lshl_add_u64 v[234:235], v[132:133], 0, v[130:131]
	v_add_lshl_u32 v130, s6, v170, 1
	v_ashrrev_i32_e32 v131, 31, v130
	s_mov_b32 s65, s22
	s_mov_b64 s[28:29], s[26:27]
	s_mov_b64 s[30:31], s[24:25]
	s_mov_b32 s64, s63
	s_and_b64 vcc, exec, s[4:5]
	v_add_lshl_u32 v130, s6, v166, 1
	v_ashrrev_i32_e32 v131, 31, v130
	v_lshl_add_u64 v[130:131], v[130:131], 2, s[10:11]
	global_load_dwordx2 v[134:135], v[130:131], off
	v_add_lshl_u32 v130, s6, v170, 1
	v_ashrrev_i32_e32 v131, 31, v130
	v_lshl_add_u64 v[130:131], v[130:131], 2, s[10:11]
	global_load_dwordx2 v[156:157], v[130:131], off
	v_add_lshl_u32 v130, s6, v174, 1
	v_ashrrev_i32_e32 v131, 31, v130
	v_lshl_add_u64 v[130:131], v[130:131], 2, s[10:11]
	global_load_dwordx2 v[206:207], v[130:131], off
	v_add_lshl_u32 v130, s6, v178, 1
	v_ashrrev_i32_e32 v131, 31, v130
	v_lshl_add_u64 v[130:131], v[130:131], 2, s[10:11]
	global_load_dwordx2 v[218:219], v[130:131], off
	v_add_lshl_u32 v130, s6, v182, 1
	v_ashrrev_i32_e32 v131, 31, v130
	v_lshl_add_u64 v[130:131], v[130:131], 2, s[10:11]
	global_load_dwordx2 v[232:233], v[130:131], off
	v_add_lshl_u32 v130, s6, v186, 1
;     DI void operator()(const f32x4 (&acc)[2][2][4][2], const pg8::Unit& u, int wr, int wc, int fr, int fq) const {
;     ...
;             for (int n = 0; n < 2; ++n) {
;                 const int c = col0 + bj * 128 + n * 16;
;                 gv[n] = *(const f32x4*)(gtp + c);
;                 gg[n] = (f32x4){1.f, 1.f, 1.f, 1.f}; bb[n] = (f32x4){0.f, 0.f, 0.f, 0.f};
;                 if (mode) { gg[n] = *(const f32x4*)(lg + c); bb[n] = *(const f32x4*)(lb + c); }
; #pragma unroll
;                 for (int q = 0; q < 8; ++q) { const int rr = rl + (q >> 2) * 128 + (q & 3) * 16; xv[n][q] = *(const f32x4*)(sbase + (size_t)rr * D + c); }
;             }
; #pragma unroll
;             for (int n = 0; n < 2; ++n) {
;                 const int c = col0 + bj * 128 + n * 16;
; #pragma unroll
;                 for (int q = 0; q < 8; ++q) {
;                     const int rr = rl + (q >> 2) * 128 + (q & 3) * 16;
;                     f32x4 x = xv[n][q];
;                     if (mode) { const float mu = stats[2 * (rowt + rr)], rs = stats[2 * (rowt + rr) + 1]; x = (x - mu) * rs * gg[n] + bb[n]; }
;                     *(f32x4*)(dbase + (size_t)rr * D + c) = ALPHA * x + gv[n] * acc[q >> 2][bj][q & 3][n];
	v_ashrrev_i32_e32 v131, 31, v130
	v_lshl_add_u64 v[130:131], v[130:131], 2, s[10:11]
	global_load_dwordx2 v[240:241], v[130:131], off
	v_add_lshl_u32 v130, s6, v190, 1
	v_ashrrev_i32_e32 v131, 31, v130
	v_lshl_add_u64 v[130:131], v[130:131], 2, s[10:11]
	global_load_dwordx2 v[242:243], v[130:131], off
	v_add_lshl_u32 v130, s6, v194, 1
	v_ashrrev_i32_e32 v131, 31, v130
	v_lshl_add_u64 v[130:131], v[130:131], 2, s[10:11]
	global_load_dwordx2 v[246:247], v[130:131], off
	global_load_dwordx4 v[224:227], v[248:249], off
	global_load_dwordx4 v[228:231], v[250:251], off
	global_load_dwordx4 v[236:239], v[254:255], off
	v_lshl_add_u64 v[132:133], v[234:235], 0, v[168:169]
	global_load_dwordx4 v[136:139], v[132:133], off
	v_lshl_add_u64 v[130:131], v[234:235], 0, v[172:173]
	global_load_dwordx4 v[140:143], v[130:131], off
	v_lshl_add_u64 v[132:133], v[234:235], 0, v[176:177]
	global_load_dwordx4 v[144:147], v[132:133], off
	v_lshl_add_u64 v[130:131], v[234:235], 0, v[180:181]
	global_load_dwordx4 v[148:151], v[130:131], off
	v_lshl_add_u64 v[132:133], v[234:235], 0, v[184:185]
	global_load_dwordx4 v[152:155], v[132:133], off
	v_lshl_add_u64 v[130:131], v[234:235], 0, v[188:189]
	global_load_dwordx4 v[208:211], v[130:131], off
	v_lshl_add_u64 v[132:133], v[234:235], 0, v[192:193]
	global_load_dwordx4 v[212:215], v[132:133], off
	v_lshl_add_u64 v[130:131], v[234:235], 0, v[196:197]
	global_load_dwordx4 v[220:223], v[130:131], off
	s_waitcnt vmcnt(0)
	v_sub_f32_e32 v139, v139, v134
	v_sub_f32_e32 v138, v138, v134
	v_sub_f32_e32 v137, v137, v134
	v_sub_f32_e32 v136, v136, v134
	v_pk_mul_f32 v[136:137], v[136:137], v[134:135] op_sel:[0,1]
	v_pk_mul_f32 v[138:139], v[138:139], v[134:135] op_sel:[0,1]
	v_pk_fma_f32 v[136:137], v[224:225], v[136:137], v[228:229]
	v_pk_fma_f32 v[138:139], v[226:227], v[138:139], v[230:231]
	v_pk_mul_f32 v[136:137], v[136:137], s[20:21] op_sel_hi:[1,0]
	v_pk_mul_f32 v[138:139], v[138:139], s[20:21] op_sel_hi:[1,0]
	v_pk_fma_f32 v[126:127], v[126:127], v[236:237], v[136:137]
	v_pk_fma_f32 v[128:129], v[128:129], v[238:239], v[138:139]
	v_sub_f32_e32 v143, v143, v156
	v_sub_f32_e32 v142, v142, v156
	v_sub_f32_e32 v141, v141, v156
	v_sub_f32_e32 v140, v140, v156
	v_pk_mul_f32 v[140:141], v[140:141], v[156:157] op_sel:[0,1]
	v_pk_mul_f32 v[142:143], v[142:143], v[156:157] op_sel:[0,1]
	v_pk_fma_f32 v[140:141], v[224:225], v[140:141], v[228:229]
	v_pk_fma_f32 v[142:143], v[226:227], v[142:143], v[230:231]
	v_pk_mul_f32 v[140:141], v[140:141], s[20:21] op_sel_hi:[1,0]
	v_pk_mul_f32 v[142:143], v[142:143], s[20:21] op_sel_hi:[1,0]
	v_pk_fma_f32 v[122:123], v[122:123], v[236:237], v[140:141]
	v_pk_fma_f32 v[124:125], v[124:125], v[238:239], v[142:143]
	v_sub_f32_e32 v147, v147, v206
	v_sub_f32_e32 v146, v146, v206
	v_sub_f32_e32 v145, v145, v206
	v_sub_f32_e32 v144, v144, v206
	v_pk_mul_f32 v[144:145], v[144:145], v[206:207] op_sel:[0,1]
	v_pk_mul_f32 v[146:147], v[146:147], v[206:207] op_sel:[0,1]
	v_pk_fma_f32 v[144:145], v[224:225], v[144:145], v[228:229]
	v_pk_fma_f32 v[146:147], v[226:227], v[146:147], v[230:231]
	v_pk_mul_f32 v[144:145], v[144:145], s[20:21] op_sel_hi:[1,0]
	v_pk_mul_f32 v[146:147], v[146:147], s[20:21] op_sel_hi:[1,0]
	v_pk_fma_f32 v[118:119], v[118:119], v[236:237], v[144:145]
	v_pk_fma_f32 v[120:121], v[120:121], v[238:239], v[146:147]
	v_sub_f32_e32 v151, v151, v218
	v_sub_f32_e32 v150, v150, v218
	v_sub_f32_e32 v149, v149, v218
	v_sub_f32_e32 v148, v148, v218
	v_pk_mul_f32 v[148:149], v[148:149], v[218:219] op_sel:[0,1]
	v_pk_mul_f32 v[150:151], v[150:151], v[218:219] op_sel:[0,1]
	v_pk_fma_f32 v[148:149], v[224:225], v[148:149], v[228:229]
	v_pk_fma_f32 v[150:151], v[226:227], v[150:151], v[230:231]
	v_pk_mul_f32 v[148:149], v[148:149], s[20:21] op_sel_hi:[1,0]
	v_pk_mul_f32 v[150:151], v[150:151], s[20:21] op_sel_hi:[1,0]
	v_pk_fma_f32 v[114:115], v[114:115], v[236:237], v[148:149]
	v_pk_fma_f32 v[116:117], v[116:117], v[238:239], v[150:151]
	v_sub_f32_e32 v155, v155, v232
	v_sub_f32_e32 v154, v154, v232
	v_sub_f32_e32 v153, v153, v232
	v_sub_f32_e32 v152, v152, v232
	v_pk_mul_f32 v[152:153], v[152:153], v[232:233] op_sel:[0,1]
	v_pk_mul_f32 v[154:155], v[154:155], v[232:233] op_sel:[0,1]
	v_pk_fma_f32 v[152:153], v[224:225], v[152:153], v[228:229]
	v_pk_fma_f32 v[154:155], v[226:227], v[154:155], v[230:231]
	v_pk_mul_f32 v[152:153], v[152:153], s[20:21] op_sel_hi:[1,0]
	v_pk_mul_f32 v[154:155], v[154:155], s[20:21] op_sel_hi:[1,0]
	v_pk_fma_f32 v[110:111], v[110:111], v[236:237], v[152:153]
	v_pk_fma_f32 v[112:113], v[112:113], v[238:239], v[154:155]
	v_sub_f32_e32 v211, v211, v240
	v_sub_f32_e32 v210, v210, v240
	v_sub_f32_e32 v209, v209, v240
	v_sub_f32_e32 v208, v208, v240
	v_pk_mul_f32 v[208:209], v[208:209], v[240:241] op_sel:[0,1]
	v_pk_mul_f32 v[210:211], v[210:211], v[240:241] op_sel:[0,1]
	v_pk_fma_f32 v[208:209], v[224:225], v[208:209], v[228:229]
	v_pk_fma_f32 v[210:211], v[226:227], v[210:211], v[230:231]
	v_pk_mul_f32 v[208:209], v[208:209], s[20:21] op_sel_hi:[1,0]
	v_pk_mul_f32 v[210:211], v[210:211], s[20:21] op_sel_hi:[1,0]
	v_pk_fma_f32 v[106:107], v[106:107], v[236:237], v[208:209]
	v_pk_fma_f32 v[108:109], v[108:109], v[238:239], v[210:211]
	v_sub_f32_e32 v215, v215, v242
	v_sub_f32_e32 v214, v214, v242
	v_sub_f32_e32 v213, v213, v242
	v_sub_f32_e32 v212, v212, v242
	v_pk_mul_f32 v[212:213], v[212:213], v[242:243] op_sel:[0,1]
	v_pk_mul_f32 v[214:215], v[214:215], v[242:243] op_sel:[0,1]
	v_pk_fma_f32 v[212:213], v[224:225], v[212:213], v[228:229]
	v_pk_fma_f32 v[214:215], v[226:227], v[214:215], v[230:231]
	v_pk_mul_f32 v[212:213], v[212:213], s[20:21] op_sel_hi:[1,0]
;     DI void operator()(const f32x4 (&acc)[2][2][4][2], const pg8::Unit& u, int wr, int wc, int fr, int fq) const {
;     ...
;             for (int n = 0; n < 2; ++n) {
;                 const int c = col0 + bj * 128 + n * 16;
;                 gv[n] = *(const f32x4*)(gtp + c);
;                 gg[n] = (f32x4){1.f, 1.f, 1.f, 1.f}; bb[n] = (f32x4){0.f, 0.f, 0.f, 0.f};
;                 if (mode) { gg[n] = *(const f32x4*)(lg + c); bb[n] = *(const f32x4*)(lb + c); }
; #pragma unroll
;                 for (int q = 0; q < 8; ++q) { const int rr = rl + (q >> 2) * 128 + (q & 3) * 16; xv[n][q] = *(const f32x4*)(sbase + (size_t)rr * D + c); }
;             }
; #pragma unroll
;             for (int n = 0; n < 2; ++n) {
;                 const int c = col0 + bj * 128 + n * 16;
; #pragma unroll
;                 for (int q = 0; q < 8; ++q) {
;                     const int rr = rl + (q >> 2) * 128 + (q & 3) * 16;
;                     f32x4 x = xv[n][q];
;                     if (mode) { const float mu = stats[2 * (rowt + rr)], rs = stats[2 * (rowt + rr) + 1]; x = (x - mu) * rs * gg[n] + bb[n]; }
;                     *(f32x4*)(dbase + (size_t)rr * D + c) = ALPHA * x + gv[n] * acc[q >> 2][bj][q & 3][n];
	v_pk_mul_f32 v[214:215], v[214:215], s[20:21] op_sel_hi:[1,0]
	v_pk_fma_f32 v[98:99], v[98:99], v[236:237], v[212:213]
	v_pk_fma_f32 v[100:101], v[100:101], v[238:239], v[214:215]
	v_sub_f32_e32 v223, v223, v246
	v_sub_f32_e32 v222, v222, v246
	v_sub_f32_e32 v221, v221, v246
	v_sub_f32_e32 v220, v220, v246
	v_pk_mul_f32 v[220:221], v[220:221], v[246:247] op_sel:[0,1]
	v_pk_mul_f32 v[222:223], v[222:223], v[246:247] op_sel:[0,1]
	v_pk_fma_f32 v[220:221], v[224:225], v[220:221], v[228:229]
	v_pk_fma_f32 v[222:223], v[226:227], v[222:223], v[230:231]
	v_pk_mul_f32 v[220:221], v[220:221], s[20:21] op_sel_hi:[1,0]
	v_pk_mul_f32 v[222:223], v[222:223], s[20:21] op_sel_hi:[1,0]
	v_pk_fma_f32 v[90:91], v[90:91], v[236:237], v[220:221]
	v_pk_fma_f32 v[92:93], v[92:93], v[238:239], v[222:223]
	global_load_dwordx4 v[224:227], v[248:249], off offset:64
	global_load_dwordx4 v[228:231], v[250:251], off offset:64
	global_load_dwordx4 v[236:239], v[254:255], off offset:64
	v_lshl_add_u64 v[132:133], v[234:235], 0, v[168:169]
	global_load_dwordx4 v[136:139], v[132:133], off offset:64
	v_lshl_add_u64 v[130:131], v[234:235], 0, v[172:173]
	global_load_dwordx4 v[140:143], v[130:131], off offset:64
	v_lshl_add_u64 v[132:133], v[234:235], 0, v[176:177]
	global_load_dwordx4 v[144:147], v[132:133], off offset:64
	v_lshl_add_u64 v[130:131], v[234:235], 0, v[180:181]
	global_load_dwordx4 v[148:151], v[130:131], off offset:64
	v_lshl_add_u64 v[132:133], v[234:235], 0, v[184:185]
	global_load_dwordx4 v[152:155], v[132:133], off offset:64
	v_lshl_add_u64 v[130:131], v[234:235], 0, v[188:189]
	global_load_dwordx4 v[208:211], v[130:131], off offset:64
	v_lshl_add_u64 v[132:133], v[234:235], 0, v[192:193]
	global_load_dwordx4 v[212:215], v[132:133], off offset:64
	v_lshl_add_u64 v[130:131], v[234:235], 0, v[196:197]
	global_load_dwordx4 v[220:223], v[130:131], off offset:64
	v_lshl_add_u64 v[132:133], v[234:235], 0, v[168:169]
	global_store_dwordx4 v[132:133], v[126:129], off
	v_lshl_add_u64 v[130:131], v[234:235], 0, v[172:173]
	global_store_dwordx4 v[130:131], v[122:125], off
	v_lshl_add_u64 v[132:133], v[234:235], 0, v[176:177]
	global_store_dwordx4 v[132:133], v[118:121], off
	v_lshl_add_u64 v[130:131], v[234:235], 0, v[180:181]
	global_store_dwordx4 v[130:131], v[114:117], off
	v_lshl_add_u64 v[132:133], v[234:235], 0, v[184:185]
	global_store_dwordx4 v[132:133], v[110:113], off
	v_lshl_add_u64 v[130:131], v[234:235], 0, v[188:189]
	global_store_dwordx4 v[130:131], v[106:109], off
	v_lshl_add_u64 v[132:133], v[234:235], 0, v[192:193]
	global_store_dwordx4 v[132:133], v[98:101], off
	v_lshl_add_u64 v[130:131], v[234:235], 0, v[196:197]
	global_store_dwordx4 v[130:131], v[90:93], off
	s_waitcnt vmcnt(8)
	v_sub_f32_e32 v139, v139, v134
	v_sub_f32_e32 v138, v138, v134
	v_sub_f32_e32 v137, v137, v134
	v_sub_f32_e32 v136, v136, v134
	v_pk_mul_f32 v[136:137], v[136:137], v[134:135] op_sel:[0,1]
	v_pk_mul_f32 v[138:139], v[138:139], v[134:135] op_sel:[0,1]
	v_pk_fma_f32 v[136:137], v[224:225], v[136:137], v[228:229]
	v_pk_fma_f32 v[138:139], v[226:227], v[138:139], v[230:231]
	v_pk_mul_f32 v[136:137], v[136:137], s[20:21] op_sel_hi:[1,0]
	v_pk_mul_f32 v[138:139], v[138:139], s[20:21] op_sel_hi:[1,0]
	v_pk_fma_f32 v[102:103], v[102:103], v[236:237], v[136:137]
	v_pk_fma_f32 v[104:105], v[104:105], v[238:239], v[138:139]
	v_sub_f32_e32 v143, v143, v156
	v_sub_f32_e32 v142, v142, v156
	v_sub_f32_e32 v141, v141, v156
	v_sub_f32_e32 v140, v140, v156
	v_pk_mul_f32 v[140:141], v[140:141], v[156:157] op_sel:[0,1]
	v_pk_mul_f32 v[142:143], v[142:143], v[156:157] op_sel:[0,1]
	v_pk_fma_f32 v[140:141], v[224:225], v[140:141], v[228:229]
	v_pk_fma_f32 v[142:143], v[226:227], v[142:143], v[230:231]
	v_pk_mul_f32 v[140:141], v[140:141], s[20:21] op_sel_hi:[1,0]
	v_pk_mul_f32 v[142:143], v[142:143], s[20:21] op_sel_hi:[1,0]
	v_pk_fma_f32 v[94:95], v[94:95], v[236:237], v[140:141]
	v_pk_fma_f32 v[96:97], v[96:97], v[238:239], v[142:143]
	v_sub_f32_e32 v147, v147, v206
	v_sub_f32_e32 v146, v146, v206
	v_sub_f32_e32 v145, v145, v206
	v_sub_f32_e32 v144, v144, v206
	v_pk_mul_f32 v[144:145], v[144:145], v[206:207] op_sel:[0,1]
	v_pk_mul_f32 v[146:147], v[146:147], v[206:207] op_sel:[0,1]
	v_pk_fma_f32 v[144:145], v[224:225], v[144:145], v[228:229]
	v_pk_fma_f32 v[146:147], v[226:227], v[146:147], v[230:231]
	v_pk_mul_f32 v[144:145], v[144:145], s[20:21] op_sel_hi:[1,0]
	v_pk_mul_f32 v[146:147], v[146:147], s[20:21] op_sel_hi:[1,0]
	v_pk_fma_f32 v[86:87], v[86:87], v[236:237], v[144:145]
	v_pk_fma_f32 v[88:89], v[88:89], v[238:239], v[146:147]
	v_sub_f32_e32 v151, v151, v218
	v_sub_f32_e32 v150, v150, v218
	v_sub_f32_e32 v149, v149, v218
	v_sub_f32_e32 v148, v148, v218
	v_pk_mul_f32 v[148:149], v[148:149], v[218:219] op_sel:[0,1]
	v_pk_mul_f32 v[150:151], v[150:151], v[218:219] op_sel:[0,1]
	v_pk_fma_f32 v[148:149], v[224:225], v[148:149], v[228:229]
	v_pk_fma_f32 v[150:151], v[226:227], v[150:151], v[230:231]
	v_pk_mul_f32 v[148:149], v[148:149], s[20:21] op_sel_hi:[1,0]
	v_pk_mul_f32 v[150:151], v[150:151], s[20:21] op_sel_hi:[1,0]
	v_pk_fma_f32 v[82:83], v[82:83], v[236:237], v[148:149]
	v_pk_fma_f32 v[84:85], v[84:85], v[238:239], v[150:151]
	v_sub_f32_e32 v155, v155, v232
	v_sub_f32_e32 v154, v154, v232
	v_sub_f32_e32 v153, v153, v232
	v_sub_f32_e32 v152, v152, v232
	v_pk_mul_f32 v[152:153], v[152:153], v[232:233] op_sel:[0,1]
	v_pk_mul_f32 v[154:155], v[154:155], v[232:233] op_sel:[0,1]
	v_pk_fma_f32 v[152:153], v[224:225], v[152:153], v[228:229]
	v_pk_fma_f32 v[154:155], v[226:227], v[154:155], v[230:231]
	v_pk_mul_f32 v[152:153], v[152:153], s[20:21] op_sel_hi:[1,0]
;     DI void operator()(const f32x4 (&acc)[2][2][4][2], const pg8::Unit& u, int wr, int wc, int fr, int fq) const {
;     ...
;             for (int n = 0; n < 2; ++n) {
;                 const int c = col0 + bj * 128 + n * 16;
;                 gv[n] = *(const f32x4*)(gtp + c);
;                 gg[n] = (f32x4){1.f, 1.f, 1.f, 1.f}; bb[n] = (f32x4){0.f, 0.f, 0.f, 0.f};
;                 if (mode) { gg[n] = *(const f32x4*)(lg + c); bb[n] = *(const f32x4*)(lb + c); }
; #pragma unroll
;                 for (int q = 0; q < 8; ++q) { const int rr = rl + (q >> 2) * 128 + (q & 3) * 16; xv[n][q] = *(const f32x4*)(sbase + (size_t)rr * D + c); }
;             }
; #pragma unroll
;             for (int n = 0; n < 2; ++n) {
;                 const int c = col0 + bj * 128 + n * 16;
; #pragma unroll
;                 for (int q = 0; q < 8; ++q) {
;                     const int rr = rl + (q >> 2) * 128 + (q & 3) * 16;
;                     f32x4 x = xv[n][q];
;                     if (mode) { const float mu = stats[2 * (rowt + rr)], rs = stats[2 * (rowt + rr) + 1]; x = (x - mu) * rs * gg[n] + bb[n]; }
;                     *(f32x4*)(dbase + (size_t)rr * D + c) = ALPHA * x + gv[n] * acc[q >> 2][bj][q & 3][n];
	v_pk_mul_f32 v[154:155], v[154:155], s[20:21] op_sel_hi:[1,0]
	v_pk_fma_f32 v[78:79], v[78:79], v[236:237], v[152:153]
	v_pk_fma_f32 v[80:81], v[80:81], v[238:239], v[154:155]
	v_sub_f32_e32 v211, v211, v240
	v_sub_f32_e32 v210, v210, v240
	v_sub_f32_e32 v209, v209, v240
	v_sub_f32_e32 v208, v208, v240
	v_pk_mul_f32 v[208:209], v[208:209], v[240:241] op_sel:[0,1]
	v_pk_mul_f32 v[210:211], v[210:211], v[240:241] op_sel:[0,1]
	v_pk_fma_f32 v[208:209], v[224:225], v[208:209], v[228:229]
	v_pk_fma_f32 v[210:211], v[226:227], v[210:211], v[230:231]
	v_pk_mul_f32 v[208:209], v[208:209], s[20:21] op_sel_hi:[1,0]
	v_pk_mul_f32 v[210:211], v[210:211], s[20:21] op_sel_hi:[1,0]
	v_pk_fma_f32 v[74:75], v[74:75], v[236:237], v[208:209]
	v_pk_fma_f32 v[76:77], v[76:77], v[238:239], v[210:211]
	v_sub_f32_e32 v215, v215, v242
	v_sub_f32_e32 v214, v214, v242
	v_sub_f32_e32 v213, v213, v242
	v_sub_f32_e32 v212, v212, v242
	v_pk_mul_f32 v[212:213], v[212:213], v[242:243] op_sel:[0,1]
	v_pk_mul_f32 v[214:215], v[214:215], v[242:243] op_sel:[0,1]
	v_pk_fma_f32 v[212:213], v[224:225], v[212:213], v[228:229]
	v_pk_fma_f32 v[214:215], v[226:227], v[214:215], v[230:231]
	v_pk_mul_f32 v[212:213], v[212:213], s[20:21] op_sel_hi:[1,0]
	v_pk_mul_f32 v[214:215], v[214:215], s[20:21] op_sel_hi:[1,0]
	v_pk_fma_f32 v[70:71], v[70:71], v[236:237], v[212:213]
	v_pk_fma_f32 v[72:73], v[72:73], v[238:239], v[214:215]
	v_sub_f32_e32 v223, v223, v246
	v_sub_f32_e32 v222, v222, v246
	v_sub_f32_e32 v221, v221, v246
	v_sub_f32_e32 v220, v220, v246
	v_pk_mul_f32 v[220:221], v[220:221], v[246:247] op_sel:[0,1]
	v_pk_mul_f32 v[222:223], v[222:223], v[246:247] op_sel:[0,1]
	v_pk_fma_f32 v[220:221], v[224:225], v[220:221], v[228:229]
	v_pk_fma_f32 v[222:223], v[226:227], v[222:223], v[230:231]
	v_pk_mul_f32 v[220:221], v[220:221], s[20:21] op_sel_hi:[1,0]
	v_pk_mul_f32 v[222:223], v[222:223], s[20:21] op_sel_hi:[1,0]
	v_pk_fma_f32 v[62:63], v[62:63], v[236:237], v[220:221]
	v_pk_fma_f32 v[64:65], v[64:65], v[238:239], v[222:223]
	global_load_dwordx4 v[224:227], v[248:249], off offset:512
	global_load_dwordx4 v[228:231], v[250:251], off offset:512
	global_load_dwordx4 v[236:239], v[254:255], off offset:512
	v_lshl_add_u64 v[132:133], v[234:235], 0, v[168:169]
	global_load_dwordx4 v[136:139], v[132:133], off offset:512
	v_lshl_add_u64 v[130:131], v[234:235], 0, v[172:173]
	global_load_dwordx4 v[140:143], v[130:131], off offset:512
	v_lshl_add_u64 v[132:133], v[234:235], 0, v[176:177]
	global_load_dwordx4 v[144:147], v[132:133], off offset:512
	v_lshl_add_u64 v[130:131], v[234:235], 0, v[180:181]
	global_load_dwordx4 v[148:151], v[130:131], off offset:512
	v_lshl_add_u64 v[132:133], v[234:235], 0, v[184:185]
	global_load_dwordx4 v[152:155], v[132:133], off offset:512
	v_lshl_add_u64 v[130:131], v[234:235], 0, v[188:189]
	global_load_dwordx4 v[208:211], v[130:131], off offset:512
	v_lshl_add_u64 v[132:133], v[234:235], 0, v[192:193]
	global_load_dwordx4 v[212:215], v[132:133], off offset:512
	v_lshl_add_u64 v[130:131], v[234:235], 0, v[196:197]
	global_load_dwordx4 v[220:223], v[130:131], off offset:512
	v_lshl_add_u64 v[132:133], v[234:235], 0, v[168:169]
	global_store_dwordx4 v[132:133], v[102:105], off offset:64
	v_lshl_add_u64 v[130:131], v[234:235], 0, v[172:173]
	global_store_dwordx4 v[130:131], v[94:97], off offset:64
	v_lshl_add_u64 v[132:133], v[234:235], 0, v[176:177]
	global_store_dwordx4 v[132:133], v[86:89], off offset:64
	v_lshl_add_u64 v[130:131], v[234:235], 0, v[180:181]
	global_store_dwordx4 v[130:131], v[82:85], off offset:64
	v_lshl_add_u64 v[132:133], v[234:235], 0, v[184:185]
	global_store_dwordx4 v[132:133], v[78:81], off offset:64
	v_lshl_add_u64 v[130:131], v[234:235], 0, v[188:189]
	global_store_dwordx4 v[130:131], v[74:77], off offset:64
	v_lshl_add_u64 v[132:133], v[234:235], 0, v[192:193]
	global_store_dwordx4 v[132:133], v[70:73], off offset:64
	v_lshl_add_u64 v[130:131], v[234:235], 0, v[196:197]
	global_store_dwordx4 v[130:131], v[62:65], off offset:64
	s_waitcnt vmcnt(8)
	v_sub_f32_e32 v139, v139, v134
	v_sub_f32_e32 v138, v138, v134
	v_sub_f32_e32 v137, v137, v134
	v_sub_f32_e32 v136, v136, v134
	v_pk_mul_f32 v[136:137], v[136:137], v[134:135] op_sel:[0,1]
	v_pk_mul_f32 v[138:139], v[138:139], v[134:135] op_sel:[0,1]
	v_pk_fma_f32 v[136:137], v[224:225], v[136:137], v[228:229]
	v_pk_fma_f32 v[138:139], v[226:227], v[138:139], v[230:231]
	v_pk_mul_f32 v[136:137], v[136:137], s[20:21] op_sel_hi:[1,0]
	v_pk_mul_f32 v[138:139], v[138:139], s[20:21] op_sel_hi:[1,0]
	v_pk_fma_f32 v[66:67], v[66:67], v[236:237], v[136:137]
	v_pk_fma_f32 v[68:69], v[68:69], v[238:239], v[138:139]
	v_sub_f32_e32 v143, v143, v156
	v_sub_f32_e32 v142, v142, v156
	v_sub_f32_e32 v141, v141, v156
	v_sub_f32_e32 v140, v140, v156
	v_pk_mul_f32 v[140:141], v[140:141], v[156:157] op_sel:[0,1]
	v_pk_mul_f32 v[142:143], v[142:143], v[156:157] op_sel:[0,1]
	v_pk_fma_f32 v[140:141], v[224:225], v[140:141], v[228:229]
	v_pk_fma_f32 v[142:143], v[226:227], v[142:143], v[230:231]
	v_pk_mul_f32 v[140:141], v[140:141], s[20:21] op_sel_hi:[1,0]
	v_pk_mul_f32 v[142:143], v[142:143], s[20:21] op_sel_hi:[1,0]
	v_pk_fma_f32 v[58:59], v[58:59], v[236:237], v[140:141]
	v_pk_fma_f32 v[60:61], v[60:61], v[238:239], v[142:143]
	v_sub_f32_e32 v147, v147, v206
	v_sub_f32_e32 v146, v146, v206
	v_sub_f32_e32 v145, v145, v206
	v_sub_f32_e32 v144, v144, v206
	v_pk_mul_f32 v[144:145], v[144:145], v[206:207] op_sel:[0,1]
	v_pk_mul_f32 v[146:147], v[146:147], v[206:207] op_sel:[0,1]
	v_pk_fma_f32 v[144:145], v[224:225], v[144:145], v[228:229]
	v_pk_fma_f32 v[146:147], v[226:227], v[146:147], v[230:231]
;     DI void operator()(const f32x4 (&acc)[2][2][4][2], const pg8::Unit& u, int wr, int wc, int fr, int fq) const {
;     ...
;             for (int n = 0; n < 2; ++n) {
;                 const int c = col0 + bj * 128 + n * 16;
;                 gv[n] = *(const f32x4*)(gtp + c);
;                 gg[n] = (f32x4){1.f, 1.f, 1.f, 1.f}; bb[n] = (f32x4){0.f, 0.f, 0.f, 0.f};
;                 if (mode) { gg[n] = *(const f32x4*)(lg + c); bb[n] = *(const f32x4*)(lb + c); }
; #pragma unroll
;                 for (int q = 0; q < 8; ++q) { const int rr = rl + (q >> 2) * 128 + (q & 3) * 16; xv[n][q] = *(const f32x4*)(sbase + (size_t)rr * D + c); }
;             }
; #pragma unroll
;             for (int n = 0; n < 2; ++n) {
;                 const int c = col0 + bj * 128 + n * 16;
; #pragma unroll
;                 for (int q = 0; q < 8; ++q) {
;                     const int rr = rl + (q >> 2) * 128 + (q & 3) * 16;
;                     f32x4 x = xv[n][q];
;                     if (mode) { const float mu = stats[2 * (rowt + rr)], rs = stats[2 * (rowt + rr) + 1]; x = (x - mu) * rs * gg[n] + bb[n]; }
;                     *(f32x4*)(dbase + (size_t)rr * D + c) = ALPHA * x + gv[n] * acc[q >> 2][bj][q & 3][n];
	v_pk_mul_f32 v[144:145], v[144:145], s[20:21] op_sel_hi:[1,0]
	v_pk_mul_f32 v[146:147], v[146:147], s[20:21] op_sel_hi:[1,0]
	v_pk_fma_f32 v[54:55], v[54:55], v[236:237], v[144:145]
	v_pk_fma_f32 v[56:57], v[56:57], v[238:239], v[146:147]
	v_sub_f32_e32 v151, v151, v218
	v_sub_f32_e32 v150, v150, v218
	v_sub_f32_e32 v149, v149, v218
	v_sub_f32_e32 v148, v148, v218
	v_pk_mul_f32 v[148:149], v[148:149], v[218:219] op_sel:[0,1]
	v_pk_mul_f32 v[150:151], v[150:151], v[218:219] op_sel:[0,1]
	v_pk_fma_f32 v[148:149], v[224:225], v[148:149], v[228:229]
	v_pk_fma_f32 v[150:151], v[226:227], v[150:151], v[230:231]
	v_pk_mul_f32 v[148:149], v[148:149], s[20:21] op_sel_hi:[1,0]
	v_pk_mul_f32 v[150:151], v[150:151], s[20:21] op_sel_hi:[1,0]
	v_pk_fma_f32 v[50:51], v[50:51], v[236:237], v[148:149]
	v_pk_fma_f32 v[52:53], v[52:53], v[238:239], v[150:151]
	v_sub_f32_e32 v155, v155, v232
	v_sub_f32_e32 v154, v154, v232
	v_sub_f32_e32 v153, v153, v232
	v_sub_f32_e32 v152, v152, v232
	v_pk_mul_f32 v[152:153], v[152:153], v[232:233] op_sel:[0,1]
	v_pk_mul_f32 v[154:155], v[154:155], v[232:233] op_sel:[0,1]
	v_pk_fma_f32 v[152:153], v[224:225], v[152:153], v[228:229]
	v_pk_fma_f32 v[154:155], v[226:227], v[154:155], v[230:231]
	v_pk_mul_f32 v[152:153], v[152:153], s[20:21] op_sel_hi:[1,0]
	v_pk_mul_f32 v[154:155], v[154:155], s[20:21] op_sel_hi:[1,0]
	v_pk_fma_f32 v[46:47], v[46:47], v[236:237], v[152:153]
	v_pk_fma_f32 v[48:49], v[48:49], v[238:239], v[154:155]
	v_sub_f32_e32 v211, v211, v240
	v_sub_f32_e32 v210, v210, v240
	v_sub_f32_e32 v209, v209, v240
	v_sub_f32_e32 v208, v208, v240
	v_pk_mul_f32 v[208:209], v[208:209], v[240:241] op_sel:[0,1]
	v_pk_mul_f32 v[210:211], v[210:211], v[240:241] op_sel:[0,1]
	v_pk_fma_f32 v[208:209], v[224:225], v[208:209], v[228:229]
	v_pk_fma_f32 v[210:211], v[226:227], v[210:211], v[230:231]
	v_pk_mul_f32 v[208:209], v[208:209], s[20:21] op_sel_hi:[1,0]
	v_pk_mul_f32 v[210:211], v[210:211], s[20:21] op_sel_hi:[1,0]
	v_pk_fma_f32 v[42:43], v[42:43], v[236:237], v[208:209]
	v_pk_fma_f32 v[44:45], v[44:45], v[238:239], v[210:211]
	v_sub_f32_e32 v215, v215, v242
	v_sub_f32_e32 v214, v214, v242
	v_sub_f32_e32 v213, v213, v242
	v_sub_f32_e32 v212, v212, v242
	v_pk_mul_f32 v[212:213], v[212:213], v[242:243] op_sel:[0,1]
	v_pk_mul_f32 v[214:215], v[214:215], v[242:243] op_sel:[0,1]
	v_pk_fma_f32 v[212:213], v[224:225], v[212:213], v[228:229]
	v_pk_fma_f32 v[214:215], v[226:227], v[214:215], v[230:231]
	v_pk_mul_f32 v[212:213], v[212:213], s[20:21] op_sel_hi:[1,0]
	v_pk_mul_f32 v[214:215], v[214:215], s[20:21] op_sel_hi:[1,0]
	v_pk_fma_f32 v[34:35], v[34:35], v[236:237], v[212:213]
	v_pk_fma_f32 v[36:37], v[36:37], v[238:239], v[214:215]
	v_sub_f32_e32 v223, v223, v246
	v_sub_f32_e32 v222, v222, v246
	v_sub_f32_e32 v221, v221, v246
	v_sub_f32_e32 v220, v220, v246
	v_pk_mul_f32 v[220:221], v[220:221], v[246:247] op_sel:[0,1]
	v_pk_mul_f32 v[222:223], v[222:223], v[246:247] op_sel:[0,1]
	v_pk_fma_f32 v[220:221], v[224:225], v[220:221], v[228:229]
	v_pk_fma_f32 v[222:223], v[226:227], v[222:223], v[230:231]
	v_pk_mul_f32 v[220:221], v[220:221], s[20:21] op_sel_hi:[1,0]
	v_pk_mul_f32 v[222:223], v[222:223], s[20:21] op_sel_hi:[1,0]
	v_pk_fma_f32 v[26:27], v[26:27], v[236:237], v[220:221]
	v_pk_fma_f32 v[28:29], v[28:29], v[238:239], v[222:223]
	global_load_dwordx4 v[224:227], v[248:249], off offset:576
	global_load_dwordx4 v[228:231], v[250:251], off offset:576
	global_load_dwordx4 v[236:239], v[254:255], off offset:576
	v_lshl_add_u64 v[132:133], v[234:235], 0, v[168:169]
	global_load_dwordx4 v[136:139], v[132:133], off offset:576
	v_lshl_add_u64 v[130:131], v[234:235], 0, v[172:173]
	global_load_dwordx4 v[140:143], v[130:131], off offset:576
	v_lshl_add_u64 v[132:133], v[234:235], 0, v[176:177]
	global_load_dwordx4 v[144:147], v[132:133], off offset:576
	v_lshl_add_u64 v[130:131], v[234:235], 0, v[180:181]
	global_load_dwordx4 v[148:151], v[130:131], off offset:576
	v_lshl_add_u64 v[132:133], v[234:235], 0, v[184:185]
	global_load_dwordx4 v[152:155], v[132:133], off offset:576
	v_lshl_add_u64 v[130:131], v[234:235], 0, v[188:189]
	global_load_dwordx4 v[208:211], v[130:131], off offset:576
	v_lshl_add_u64 v[132:133], v[234:235], 0, v[192:193]
	global_load_dwordx4 v[212:215], v[132:133], off offset:576
	v_lshl_add_u64 v[130:131], v[234:235], 0, v[196:197]
	global_load_dwordx4 v[220:223], v[130:131], off offset:576
	v_lshl_add_u64 v[132:133], v[234:235], 0, v[168:169]
	global_store_dwordx4 v[132:133], v[66:69], off offset:512
	v_lshl_add_u64 v[130:131], v[234:235], 0, v[172:173]
	global_store_dwordx4 v[130:131], v[58:61], off offset:512
	v_lshl_add_u64 v[132:133], v[234:235], 0, v[176:177]
	global_store_dwordx4 v[132:133], v[54:57], off offset:512
	v_lshl_add_u64 v[130:131], v[234:235], 0, v[180:181]
	global_store_dwordx4 v[130:131], v[50:53], off offset:512
	v_lshl_add_u64 v[132:133], v[234:235], 0, v[184:185]
	global_store_dwordx4 v[132:133], v[46:49], off offset:512
	v_lshl_add_u64 v[130:131], v[234:235], 0, v[188:189]
	global_store_dwordx4 v[130:131], v[42:45], off offset:512
	v_lshl_add_u64 v[132:133], v[234:235], 0, v[192:193]
	global_store_dwordx4 v[132:133], v[34:37], off offset:512
	v_lshl_add_u64 v[130:131], v[234:235], 0, v[196:197]
	global_store_dwordx4 v[130:131], v[26:29], off offset:512
	s_waitcnt vmcnt(8)
;     DI void operator()(const f32x4 (&acc)[2][2][4][2], const pg8::Unit& u, int wr, int wc, int fr, int fq) const {
;     ...
;             for (int n = 0; n < 2; ++n) {
;                 const int c = col0 + bj * 128 + n * 16;
;                 gv[n] = *(const f32x4*)(gtp + c);
;                 gg[n] = (f32x4){1.f, 1.f, 1.f, 1.f}; bb[n] = (f32x4){0.f, 0.f, 0.f, 0.f};
;                 if (mode) { gg[n] = *(const f32x4*)(lg + c); bb[n] = *(const f32x4*)(lb + c); }
; #pragma unroll
;                 for (int q = 0; q < 8; ++q) { const int rr = rl + (q >> 2) * 128 + (q & 3) * 16; xv[n][q] = *(const f32x4*)(sbase + (size_t)rr * D + c); }
;             }
; #pragma unroll
;             for (int n = 0; n < 2; ++n) {
;                 const int c = col0 + bj * 128 + n * 16;
; #pragma unroll
;                 for (int q = 0; q < 8; ++q) {
;                     const int rr = rl + (q >> 2) * 128 + (q & 3) * 16;
;                     f32x4 x = xv[n][q];
;                     if (mode) { const float mu = stats[2 * (rowt + rr)], rs = stats[2 * (rowt + rr) + 1]; x = (x - mu) * rs * gg[n] + bb[n]; }
;                     *(f32x4*)(dbase + (size_t)rr * D + c) = ALPHA * x + gv[n] * acc[q >> 2][bj][q & 3][n];
	v_sub_f32_e32 v139, v139, v134
	v_sub_f32_e32 v138, v138, v134
	v_sub_f32_e32 v137, v137, v134
	v_sub_f32_e32 v136, v136, v134
	v_pk_mul_f32 v[136:137], v[136:137], v[134:135] op_sel:[0,1]
	v_pk_mul_f32 v[138:139], v[138:139], v[134:135] op_sel:[0,1]
	v_pk_fma_f32 v[136:137], v[224:225], v[136:137], v[228:229]
	v_pk_fma_f32 v[138:139], v[226:227], v[138:139], v[230:231]
	v_pk_mul_f32 v[136:137], v[136:137], s[20:21] op_sel_hi:[1,0]
	v_pk_mul_f32 v[138:139], v[138:139], s[20:21] op_sel_hi:[1,0]
	v_pk_fma_f32 v[38:39], v[38:39], v[236:237], v[136:137]
	v_pk_fma_f32 v[40:41], v[40:41], v[238:239], v[138:139]
	v_sub_f32_e32 v143, v143, v156
	v_sub_f32_e32 v142, v142, v156
	v_sub_f32_e32 v141, v141, v156
	v_sub_f32_e32 v140, v140, v156
	v_pk_mul_f32 v[140:141], v[140:141], v[156:157] op_sel:[0,1]
	v_pk_mul_f32 v[142:143], v[142:143], v[156:157] op_sel:[0,1]
	v_pk_fma_f32 v[140:141], v[224:225], v[140:141], v[228:229]
	v_pk_fma_f32 v[142:143], v[226:227], v[142:143], v[230:231]
	v_pk_mul_f32 v[140:141], v[140:141], s[20:21] op_sel_hi:[1,0]
	v_pk_mul_f32 v[142:143], v[142:143], s[20:21] op_sel_hi:[1,0]
	v_pk_fma_f32 v[30:31], v[30:31], v[236:237], v[140:141]
	v_pk_fma_f32 v[32:33], v[32:33], v[238:239], v[142:143]
	v_sub_f32_e32 v147, v147, v206
	v_sub_f32_e32 v146, v146, v206
	v_sub_f32_e32 v145, v145, v206
	v_sub_f32_e32 v144, v144, v206
	v_pk_mul_f32 v[144:145], v[144:145], v[206:207] op_sel:[0,1]
	v_pk_mul_f32 v[146:147], v[146:147], v[206:207] op_sel:[0,1]
	v_pk_fma_f32 v[144:145], v[224:225], v[144:145], v[228:229]
	v_pk_fma_f32 v[146:147], v[226:227], v[146:147], v[230:231]
	v_pk_mul_f32 v[144:145], v[144:145], s[20:21] op_sel_hi:[1,0]
	v_pk_mul_f32 v[146:147], v[146:147], s[20:21] op_sel_hi:[1,0]
	v_pk_fma_f32 v[22:23], v[22:23], v[236:237], v[144:145]
	v_pk_fma_f32 v[24:25], v[24:25], v[238:239], v[146:147]
	v_sub_f32_e32 v151, v151, v218
	v_sub_f32_e32 v150, v150, v218
	v_sub_f32_e32 v149, v149, v218
	v_sub_f32_e32 v148, v148, v218
	v_pk_mul_f32 v[148:149], v[148:149], v[218:219] op_sel:[0,1]
	v_pk_mul_f32 v[150:151], v[150:151], v[218:219] op_sel:[0,1]
	v_pk_fma_f32 v[148:149], v[224:225], v[148:149], v[228:229]
	v_pk_fma_f32 v[150:151], v[226:227], v[150:151], v[230:231]
	v_pk_mul_f32 v[148:149], v[148:149], s[20:21] op_sel_hi:[1,0]
	v_pk_mul_f32 v[150:151], v[150:151], s[20:21] op_sel_hi:[1,0]
	v_pk_fma_f32 v[18:19], v[18:19], v[236:237], v[148:149]
	v_pk_fma_f32 v[20:21], v[20:21], v[238:239], v[150:151]
	v_sub_f32_e32 v155, v155, v232
	v_sub_f32_e32 v154, v154, v232
	v_sub_f32_e32 v153, v153, v232
	v_sub_f32_e32 v152, v152, v232
	v_pk_mul_f32 v[152:153], v[152:153], v[232:233] op_sel:[0,1]
	v_pk_mul_f32 v[154:155], v[154:155], v[232:233] op_sel:[0,1]
	v_pk_fma_f32 v[152:153], v[224:225], v[152:153], v[228:229]
	v_pk_fma_f32 v[154:155], v[226:227], v[154:155], v[230:231]
	v_pk_mul_f32 v[152:153], v[152:153], s[20:21] op_sel_hi:[1,0]
	v_pk_mul_f32 v[154:155], v[154:155], s[20:21] op_sel_hi:[1,0]
	v_pk_fma_f32 v[14:15], v[14:15], v[236:237], v[152:153]
	v_pk_fma_f32 v[16:17], v[16:17], v[238:239], v[154:155]
	v_sub_f32_e32 v211, v211, v240
	v_sub_f32_e32 v210, v210, v240
	v_sub_f32_e32 v209, v209, v240
	v_sub_f32_e32 v208, v208, v240
	v_pk_mul_f32 v[208:209], v[208:209], v[240:241] op_sel:[0,1]
	v_pk_mul_f32 v[210:211], v[210:211], v[240:241] op_sel:[0,1]
	v_pk_fma_f32 v[208:209], v[224:225], v[208:209], v[228:229]
	v_pk_fma_f32 v[210:211], v[226:227], v[210:211], v[230:231]
	v_pk_mul_f32 v[208:209], v[208:209], s[20:21] op_sel_hi:[1,0]
	v_pk_mul_f32 v[210:211], v[210:211], s[20:21] op_sel_hi:[1,0]
	v_pk_fma_f32 v[10:11], v[10:11], v[236:237], v[208:209]
	v_pk_fma_f32 v[12:13], v[12:13], v[238:239], v[210:211]
	v_sub_f32_e32 v215, v215, v242
	v_sub_f32_e32 v214, v214, v242
	v_sub_f32_e32 v213, v213, v242
	v_sub_f32_e32 v212, v212, v242
	v_pk_mul_f32 v[212:213], v[212:213], v[242:243] op_sel:[0,1]
	v_pk_mul_f32 v[214:215], v[214:215], v[242:243] op_sel:[0,1]
	v_pk_fma_f32 v[212:213], v[224:225], v[212:213], v[228:229]
	v_pk_fma_f32 v[214:215], v[226:227], v[214:215], v[230:231]
	v_pk_mul_f32 v[212:213], v[212:213], s[20:21] op_sel_hi:[1,0]
	v_pk_mul_f32 v[214:215], v[214:215], s[20:21] op_sel_hi:[1,0]
	v_pk_fma_f32 v[6:7], v[6:7], v[236:237], v[212:213]
	v_pk_fma_f32 v[8:9], v[8:9], v[238:239], v[214:215]
	v_sub_f32_e32 v223, v223, v246
	v_sub_f32_e32 v222, v222, v246
	v_sub_f32_e32 v221, v221, v246
	v_sub_f32_e32 v220, v220, v246
	v_pk_mul_f32 v[220:221], v[220:221], v[246:247] op_sel:[0,1]
	v_pk_mul_f32 v[222:223], v[222:223], v[246:247] op_sel:[0,1]
	v_pk_fma_f32 v[220:221], v[224:225], v[220:221], v[228:229]
	v_pk_fma_f32 v[222:223], v[226:227], v[222:223], v[230:231]
	v_pk_mul_f32 v[220:221], v[220:221], s[20:21] op_sel_hi:[1,0]
	v_pk_mul_f32 v[222:223], v[222:223], s[20:21] op_sel_hi:[1,0]
	v_pk_fma_f32 v[2:3], v[2:3], v[236:237], v[220:221]
	v_pk_fma_f32 v[4:5], v[4:5], v[238:239], v[222:223]
	v_lshl_add_u64 v[132:133], v[234:235], 0, v[168:169]
	global_store_dwordx4 v[132:133], v[38:41], off offset:576
	v_lshl_add_u64 v[130:131], v[234:235], 0, v[172:173]
	global_store_dwordx4 v[130:131], v[30:33], off offset:576
	v_lshl_add_u64 v[132:133], v[234:235], 0, v[176:177]
	global_store_dwordx4 v[132:133], v[22:25], off offset:576
	v_lshl_add_u64 v[130:131], v[234:235], 0, v[180:181]
	global_store_dwordx4 v[130:131], v[18:21], off offset:576
	v_lshl_add_u64 v[132:133], v[234:235], 0, v[184:185]
	global_store_dwordx4 v[132:133], v[14:17], off offset:576
	v_lshl_add_u64 v[130:131], v[234:235], 0, v[188:189]
	global_store_dwordx4 v[130:131], v[10:13], off offset:576
	v_lshl_add_u64 v[132:133], v[234:235], 0, v[192:193]
	global_store_dwordx4 v[132:133], v[6:9], off offset:576
	v_lshl_add_u64 v[130:131], v[234:235], 0, v[196:197]
	global_store_dwordx4 v[130:131], v[2:5], off offset:576
	v_and_b32_e32 v254, 0x3ff, v0
	s_cbranch_vccz .LBB0_1287
	s_waitcnt vmcnt(0)
	s_cmpk_gt_u32 s21, 0xff
	s_cbranch_scc1 .LBB0_1296
	s_barrier

; #define PG8_STAGE(bufoff, gbase, voff) do { _Pragma("unroll") for (int _i = 0; _i < 2; ++_i) \
;         __builtin_amdgcn_global_load_lds((const unsigned*)((const char*)(gbase) + (voff)[_i]), (LAS unsigned*)(lds + (bufoff) + ldsw + _i * 8192), 16, 0, 0); } while (0)
; #define PG8_LDA(dst, b, h) do { _Pragma("unroll") for (int m = 0; m < 4; ++m) _Pragma("unroll") for (int k = 0; k < 2; ++k) dst[m][k] = *(const LAS bf16x8*)(lds + PG8_SA(b, h) + aoff + m * 2048 + k * 1024); } while (0)
; #define PG8_LDB(dst, b, h) do { _Pragma("unroll") for (int n = 0; n < 2; ++n) _Pragma("unroll") for (int k = 0; k < 2; ++k) dst[n][k] = *(const LAS bf16x8*)(lds + PG8_SB(b, h) + boff + n * 2048 + k * 1024); } while (0)
; #define PG8_MMA(ai, bj, At, Bt) do { __builtin_amdgcn_s_setprio(1); _Pragma("unroll") for (int m = 0; m < 4; ++m) _Pragma("unroll") for (int n = 0; n < 2; ++n) _Pragma("unroll") for (int k = 0; k < 2; ++k) \
;         acc[ai][bj][m][n] = __builtin_amdgcn_mfma_f32_16x16x32_bf16(Bt[n][k], At[m][k], acc[ai][bj][m][n], 0, 0, 0); __builtin_amdgcn_s_setprio(0); } while (0)
; #define PG8_WAIT_V(n) asm volatile("s_waitcnt vmcnt(" #n ")" ::: "memory")
; #define PG8_WAIT_L(n) asm volatile("s_waitcnt lgkmcnt(" #n ")" ::: "memory")
; #define PG8_BAR __builtin_amdgcn_s_barrier()
; #define PG8_SCHED __builtin_amdgcn_sched_barrier(0)
; template <class Epi>
; DI void gemm_phase(LAS unsigned char* lds, const Gemm g, const StaticOrder& S, const Epi& E) {
;     ...
;             PG8_LDB(B0, 0, 0); PG8_SCHED; PG8_LDA(At, 0, 0); PG8_STAGE(PG8_SA(1, 1), a1 + hstepA, voffA);
;             PG8_WAIT_L(8); PG8_BAR; PG8_WAIT_L(0); PG8_MMA(0, 0, At, B0); PG8_BAR; PG8_SCHED;
;             PG8_LDB(B1, 0, 1); PG8_STAGE(PG8_SB(0, 0), b2, voffB);
;             PG8_BAR; PG8_WAIT_L(0); PG8_MMA(0, 1, At, B1); PG8_BAR;
;             PG8_LDA(At, 0, 1); PG8_STAGE(PG8_SA(0, 0), a2, voffA);
;             PG8_BAR; PG8_WAIT_L(0); PG8_MMA(1, 0, At, B0); PG8_BAR; PG8_SCHED;
;             PG8_STAGE(PG8_SB(0, 1), b2 + hstepB, voffB);
;             PG8_WAIT_V(6); PG8_BAR; PG8_MMA(1, 1, At, B1); PG8_BAR;
.LBB0_1969:
	ds_read_b128 v[130:133], v171
	ds_read_b128 v[134:137], v171 offset:1024
	ds_read_b128 v[138:141], v171 offset:2048
	ds_read_b128 v[142:145], v171 offset:3072
	s_add_u32 s28, s6, 0xffdf0080
	s_addc_u32 s29, s7, -1
	s_cmp_eq_u32 s69, 28
	s_cselect_b32 s31, s25, s29
	s_cselect_b32 s30, s24, s28
	s_cselect_b32 s29, s23, s68
	s_cselect_b32 s28, s66, s67
	v_lshl_add_u64 v[214:215], s[6:7], 0, v[198:199]
	s_add_i32 m0, s39, 0xc000
	ds_read_b128 v[146:149], v175
	ds_read_b128 v[150:153], v175 offset:1024
	ds_read_b128 v[154:157], v175 offset:2048
	ds_read_b128 v[206:209], v175 offset:3072
	ds_read_b128 v[210:213], v175 offset:4096
	ds_read_b128 v[218:221], v175 offset:5120
	ds_read_b128 v[222:225], v175 offset:6144
	ds_read_b128 v[226:229], v175 offset:7168
	global_load_lds_dwordx4 v[214:215], off
	v_lshl_add_u64 v[214:215], s[6:7], 0, v[200:201]
	s_add_i32 m0, s39, 0xe000
	s_nop 0
	global_load_lds_dwordx4 v[214:215], off
	ds_read_b128 v[230:233], v179
	ds_read_b128 v[234:237], v179 offset:1024
	ds_read_b128 v[238:241], v179 offset:2048
	ds_read_b128 v[242:245], v179 offset:3072
	s_waitcnt lgkmcnt(0)
	s_waitcnt vmcnt(8)
	s_barrier
	s_setprio 1
	v_mfma_f32_16x16x32_bf16 v[126:129], v[130:133], v[146:149], v[126:129]
	v_mfma_f32_16x16x32_bf16 v[102:105], v[138:141], v[146:149], v[102:105]
	v_mfma_f32_16x16x32_bf16 v[122:125], v[130:133], v[154:157], v[122:125]
	v_mfma_f32_16x16x32_bf16 v[94:97], v[138:141], v[154:157], v[94:97]
	v_mfma_f32_16x16x32_bf16 v[118:121], v[130:133], v[210:213], v[118:121]
	v_mfma_f32_16x16x32_bf16 v[86:89], v[138:141], v[210:213], v[86:89]
	v_mfma_f32_16x16x32_bf16 v[114:117], v[130:133], v[222:225], v[114:117]
	v_mfma_f32_16x16x32_bf16 v[82:85], v[138:141], v[222:225], v[82:85]
	v_mfma_f32_16x16x32_bf16 v[126:129], v[134:137], v[150:153], v[126:129]
	v_mfma_f32_16x16x32_bf16 v[102:105], v[142:145], v[150:153], v[102:105]
	v_mfma_f32_16x16x32_bf16 v[122:125], v[134:137], v[206:209], v[122:125]
	v_mfma_f32_16x16x32_bf16 v[94:97], v[142:145], v[206:209], v[94:97]
	v_mfma_f32_16x16x32_bf16 v[118:121], v[134:137], v[218:221], v[118:121]
	v_mfma_f32_16x16x32_bf16 v[86:89], v[142:145], v[218:221], v[86:89]
	v_mfma_f32_16x16x32_bf16 v[114:117], v[134:137], v[226:229], v[114:117]
	v_mfma_f32_16x16x32_bf16 v[82:85], v[142:145], v[226:229], v[82:85]
	v_mfma_f32_16x16x32_bf16 v[62:65], v[230:233], v[146:149], v[62:65]
	v_mfma_f32_16x16x32_bf16 v[38:41], v[238:241], v[146:149], v[38:41]
	v_mfma_f32_16x16x32_bf16 v[58:61], v[230:233], v[154:157], v[58:61]
	v_mfma_f32_16x16x32_bf16 v[30:33], v[238:241], v[154:157], v[30:33]
	v_mfma_f32_16x16x32_bf16 v[54:57], v[230:233], v[210:213], v[54:57]
	v_mfma_f32_16x16x32_bf16 v[22:25], v[238:241], v[210:213], v[22:25]
	v_mfma_f32_16x16x32_bf16 v[50:53], v[230:233], v[222:225], v[50:53]
	v_mfma_f32_16x16x32_bf16 v[18:21], v[238:241], v[222:225], v[18:21]
	v_mfma_f32_16x16x32_bf16 v[62:65], v[234:237], v[150:153], v[62:65]
	v_mfma_f32_16x16x32_bf16 v[38:41], v[242:245], v[150:153], v[38:41]
	v_mfma_f32_16x16x32_bf16 v[58:61], v[234:237], v[206:209], v[58:61]
	v_mfma_f32_16x16x32_bf16 v[30:33], v[242:245], v[206:209], v[30:33]
	v_mfma_f32_16x16x32_bf16 v[54:57], v[234:237], v[218:221], v[54:57]
	v_mfma_f32_16x16x32_bf16 v[22:25], v[242:245], v[218:221], v[22:25]
	v_mfma_f32_16x16x32_bf16 v[50:53], v[234:237], v[226:229], v[50:53]
	v_mfma_f32_16x16x32_bf16 v[18:21], v[242:245], v[226:229], v[18:21]
	s_setprio 0
	s_barrier
	s_add_i32 s70, s60, s38
	v_lshl_add_u64 v[214:215], s[28:29], 0, v[160:161]
	s_mov_b32 m0, s70
	s_nop 0
	global_load_lds_dwordx4 v[214:215], off
	v_lshl_add_u64 v[216:217], s[28:29], 0, v[164:165]
	s_add_i32 m0, s70, 0x2000
	s_nop 0
	global_load_lds_dwordx4 v[216:217], off
	s_mov_b32 m0, s39
	v_lshl_add_u64 v[246:247], s[30:31], 0, v[158:159]
	ds_read_b128 v[146:149], v175 offset:16384
	ds_read_b128 v[150:153], v175 offset:17408
	ds_read_b128 v[154:157], v175 offset:18432
	ds_read_b128 v[206:209], v175 offset:19456
	ds_read_b128 v[210:213], v175 offset:20480
	ds_read_b128 v[218:221], v175 offset:21504
	ds_read_b128 v[222:225], v175 offset:22528
	ds_read_b128 v[226:229], v175 offset:23552
	global_load_lds_dwordx4 v[246:247], off
	v_lshl_add_u64 v[248:249], s[30:31], 0, v[162:163]
	s_mov_b32 m0, s48
	s_nop 0
	global_load_lds_dwordx4 v[248:249], off
	s_add_u32 s70, s28, 0x80000
	s_addc_u32 s71, s29, 0
	s_add_i32 s72, s61, s38
	v_lshl_add_u64 v[252:253], s[70:71], 0, v[160:161]
	s_mov_b32 m0, s72
	s_nop 0
	global_load_lds_dwordx4 v[252:253], off
	v_lshl_add_u64 v[252:253], s[70:71], 0, v[164:165]
	s_add_i32 m0, s72, 0x2000
	s_nop 0
	global_load_lds_dwordx4 v[252:253], off
	s_waitcnt lgkmcnt(0)
	s_waitcnt vmcnt(8)
	s_barrier
; #define PG8_STAGE(bufoff, gbase, voff) do { _Pragma("unroll") for (int _i = 0; _i < 2; ++_i) \
;         __builtin_amdgcn_global_load_lds((const unsigned*)((const char*)(gbase) + (voff)[_i]), (LAS unsigned*)(lds + (bufoff) + ldsw + _i * 8192), 16, 0, 0); } while (0)
; #define PG8_LDA(dst, b, h) do { _Pragma("unroll") for (int m = 0; m < 4; ++m) _Pragma("unroll") for (int k = 0; k < 2; ++k) dst[m][k] = *(const LAS bf16x8*)(lds + PG8_SA(b, h) + aoff + m * 2048 + k * 1024); } while (0)
; #define PG8_LDB(dst, b, h) do { _Pragma("unroll") for (int n = 0; n < 2; ++n) _Pragma("unroll") for (int k = 0; k < 2; ++k) dst[n][k] = *(const LAS bf16x8*)(lds + PG8_SB(b, h) + boff + n * 2048 + k * 1024); } while (0)
; #define PG8_MMA(ai, bj, At, Bt) do { __builtin_amdgcn_s_setprio(1); _Pragma("unroll") for (int m = 0; m < 4; ++m) _Pragma("unroll") for (int n = 0; n < 2; ++n) _Pragma("unroll") for (int k = 0; k < 2; ++k) \
;         acc[ai][bj][m][n] = __builtin_amdgcn_mfma_f32_16x16x32_bf16(Bt[n][k], At[m][k], acc[ai][bj][m][n], 0, 0, 0); __builtin_amdgcn_s_setprio(0); } while (0)
; #define PG8_WAIT_V(n) asm volatile("s_waitcnt vmcnt(" #n ")" ::: "memory")
; #define PG8_WAIT_L(n) asm volatile("s_waitcnt lgkmcnt(" #n ")" ::: "memory")
; #define PG8_BAR __builtin_amdgcn_s_barrier()
; #define PG8_SCHED __builtin_amdgcn_sched_barrier(0)
; template <class Epi>
; DI void gemm_phase(LAS unsigned char* lds, const Gemm g, const StaticOrder& S, const Epi& E) {
;     ...
;             PG8_BAR; PG8_WAIT_L(0); PG8_MMA(0, 1, At, B1); PG8_BAR;
;             PG8_LDA(At, 0, 1); PG8_STAGE(PG8_SA(0, 0), a2, voffA);
;             PG8_BAR; PG8_WAIT_L(0); PG8_MMA(1, 0, At, B0); PG8_BAR; PG8_SCHED;
;             PG8_STAGE(PG8_SB(0, 1), b2 + hstepB, voffB);
;             PG8_WAIT_V(6); PG8_BAR; PG8_MMA(1, 1, At, B1); PG8_BAR;
;             PG8_LDB(B0, 1, 0); PG8_SCHED; PG8_LDA(At, 1, 0); PG8_STAGE(PG8_SA(0, 1), a2 + hstepA, voffA);
;             PG8_WAIT_L(8); PG8_BAR; PG8_WAIT_L(0); PG8_MMA(0, 0, At, B0); PG8_BAR; PG8_SCHED;
;             PG8_LDB(B1, 1, 1); PG8_STAGE(PG8_SB(1, 0), b3, voffB);
;             PG8_BAR; PG8_WAIT_L(0); PG8_MMA(0, 1, At, B1); PG8_BAR;
	s_setprio 1
	v_mfma_f32_16x16x32_bf16 v[110:113], v[130:133], v[146:149], v[110:113]
	v_mfma_f32_16x16x32_bf16 v[78:81], v[138:141], v[146:149], v[78:81]
	v_mfma_f32_16x16x32_bf16 v[106:109], v[130:133], v[154:157], v[106:109]
	v_mfma_f32_16x16x32_bf16 v[74:77], v[138:141], v[154:157], v[74:77]
	v_mfma_f32_16x16x32_bf16 v[98:101], v[130:133], v[210:213], v[98:101]
	v_mfma_f32_16x16x32_bf16 v[70:73], v[138:141], v[210:213], v[70:73]
	v_mfma_f32_16x16x32_bf16 v[90:93], v[130:133], v[222:225], v[90:93]
	v_mfma_f32_16x16x32_bf16 v[66:69], v[138:141], v[222:225], v[66:69]
	v_mfma_f32_16x16x32_bf16 v[110:113], v[134:137], v[150:153], v[110:113]
	v_mfma_f32_16x16x32_bf16 v[78:81], v[142:145], v[150:153], v[78:81]
	v_mfma_f32_16x16x32_bf16 v[106:109], v[134:137], v[206:209], v[106:109]
	v_mfma_f32_16x16x32_bf16 v[74:77], v[142:145], v[206:209], v[74:77]
	v_mfma_f32_16x16x32_bf16 v[98:101], v[134:137], v[218:221], v[98:101]
	v_mfma_f32_16x16x32_bf16 v[70:73], v[142:145], v[218:221], v[70:73]
	v_mfma_f32_16x16x32_bf16 v[90:93], v[134:137], v[226:229], v[90:93]
	v_mfma_f32_16x16x32_bf16 v[66:69], v[142:145], v[226:229], v[66:69]
	v_mfma_f32_16x16x32_bf16 v[46:49], v[230:233], v[146:149], v[46:49]
	v_mfma_f32_16x16x32_bf16 v[14:17], v[238:241], v[146:149], v[14:17]
	v_mfma_f32_16x16x32_bf16 v[42:45], v[230:233], v[154:157], v[42:45]
	v_mfma_f32_16x16x32_bf16 v[10:13], v[238:241], v[154:157], v[10:13]
	v_mfma_f32_16x16x32_bf16 v[34:37], v[230:233], v[210:213], v[34:37]
	v_mfma_f32_16x16x32_bf16 v[6:9], v[238:241], v[210:213], v[6:9]
	v_mfma_f32_16x16x32_bf16 v[26:29], v[230:233], v[222:225], v[26:29]
	v_mfma_f32_16x16x32_bf16 v[2:5], v[238:241], v[222:225], v[2:5]
	v_mfma_f32_16x16x32_bf16 v[46:49], v[234:237], v[150:153], v[46:49]
	v_mfma_f32_16x16x32_bf16 v[14:17], v[242:245], v[150:153], v[14:17]
	v_mfma_f32_16x16x32_bf16 v[42:45], v[234:237], v[206:209], v[42:45]
	v_mfma_f32_16x16x32_bf16 v[10:13], v[242:245], v[206:209], v[10:13]
	v_mfma_f32_16x16x32_bf16 v[34:37], v[234:237], v[218:221], v[34:37]
	v_mfma_f32_16x16x32_bf16 v[6:9], v[242:245], v[218:221], v[6:9]
	v_mfma_f32_16x16x32_bf16 v[26:29], v[234:237], v[226:229], v[26:29]
	v_mfma_f32_16x16x32_bf16 v[2:5], v[242:245], v[226:229], v[2:5]
	s_setprio 0
	s_add_i32 s70, 0, 0x18000
	v_add_u32_e32 v142, s70, v1
	s_barrier
	ds_read_b128 v[130:133], v142
	ds_read_b128 v[134:137], v142 offset:1024
	ds_read_b128 v[138:141], v142 offset:2048
	ds_read_b128 v[142:145], v142 offset:3072
	s_add_u32 s30, s30, 0x210000
	s_addc_u32 s31, s31, 0
	s_mov_b32 m0, s49
	v_lshl_add_u64 v[230:231], s[30:31], 0, v[158:159]
	ds_read_b128 v[146:149], v175 offset:32768
	ds_read_b128 v[150:153], v175 offset:33792
	ds_read_b128 v[154:157], v175 offset:34816
	ds_read_b128 v[206:209], v175 offset:35840
	ds_read_b128 v[210:213], v175 offset:36864
	ds_read_b128 v[218:221], v175 offset:37888
	ds_read_b128 v[222:225], v175 offset:38912
	ds_read_b128 v[226:229], v175 offset:39936
	global_load_lds_dwordx4 v[230:231], off
	v_lshl_add_u64 v[230:231], s[30:31], 0, v[162:163]
	s_mov_b32 m0, s50
	s_nop 0
	global_load_lds_dwordx4 v[230:231], off
	s_add_i32 s30, 0, 0x1c000
	v_add_u32_e32 v187, s30, v1
	ds_read_b128 v[230:233], v187
	ds_read_b128 v[234:237], v187 offset:1024
	ds_read_b128 v[238:241], v187 offset:2048
	ds_read_b128 v[242:245], v187 offset:3072
	s_waitcnt lgkmcnt(0)
	s_waitcnt vmcnt(8)
	s_barrier
	s_setprio 1
	v_mfma_f32_16x16x32_bf16 v[126:129], v[130:133], v[146:149], v[126:129]
	v_mfma_f32_16x16x32_bf16 v[102:105], v[138:141], v[146:149], v[102:105]
	v_mfma_f32_16x16x32_bf16 v[122:125], v[130:133], v[154:157], v[122:125]
	v_mfma_f32_16x16x32_bf16 v[94:97], v[138:141], v[154:157], v[94:97]
	v_mfma_f32_16x16x32_bf16 v[118:121], v[130:133], v[210:213], v[118:121]
	v_mfma_f32_16x16x32_bf16 v[86:89], v[138:141], v[210:213], v[86:89]
	v_mfma_f32_16x16x32_bf16 v[114:117], v[130:133], v[222:225], v[114:117]
	v_mfma_f32_16x16x32_bf16 v[82:85], v[138:141], v[222:225], v[82:85]
	v_mfma_f32_16x16x32_bf16 v[126:129], v[134:137], v[150:153], v[126:129]
	v_mfma_f32_16x16x32_bf16 v[102:105], v[142:145], v[150:153], v[102:105]
	v_mfma_f32_16x16x32_bf16 v[122:125], v[134:137], v[206:209], v[122:125]
	v_mfma_f32_16x16x32_bf16 v[94:97], v[142:145], v[206:209], v[94:97]
	v_mfma_f32_16x16x32_bf16 v[118:121], v[134:137], v[218:221], v[118:121]
	v_mfma_f32_16x16x32_bf16 v[86:89], v[142:145], v[218:221], v[86:89]
	v_mfma_f32_16x16x32_bf16 v[114:117], v[134:137], v[226:229], v[114:117]
	v_mfma_f32_16x16x32_bf16 v[82:85], v[142:145], v[226:229], v[82:85]
	v_mfma_f32_16x16x32_bf16 v[62:65], v[230:233], v[146:149], v[62:65]
	v_mfma_f32_16x16x32_bf16 v[38:41], v[238:241], v[146:149], v[38:41]
	v_mfma_f32_16x16x32_bf16 v[58:61], v[230:233], v[154:157], v[58:61]
	v_mfma_f32_16x16x32_bf16 v[30:33], v[238:241], v[154:157], v[30:33]
	v_mfma_f32_16x16x32_bf16 v[54:57], v[230:233], v[210:213], v[54:57]
	v_mfma_f32_16x16x32_bf16 v[22:25], v[238:241], v[210:213], v[22:25]
	v_mfma_f32_16x16x32_bf16 v[50:53], v[230:233], v[222:225], v[50:53]
	v_mfma_f32_16x16x32_bf16 v[18:21], v[238:241], v[222:225], v[18:21]
	v_mfma_f32_16x16x32_bf16 v[62:65], v[234:237], v[150:153], v[62:65]
	v_mfma_f32_16x16x32_bf16 v[38:41], v[242:245], v[150:153], v[38:41]
	v_mfma_f32_16x16x32_bf16 v[58:61], v[234:237], v[206:209], v[58:61]
	v_mfma_f32_16x16x32_bf16 v[30:33], v[242:245], v[206:209], v[30:33]
	v_mfma_f32_16x16x32_bf16 v[54:57], v[234:237], v[218:221], v[54:57]
	v_mfma_f32_16x16x32_bf16 v[22:25], v[242:245], v[218:221], v[22:25]
	v_mfma_f32_16x16x32_bf16 v[50:53], v[234:237], v[226:229], v[50:53]
	v_mfma_f32_16x16x32_bf16 v[18:21], v[242:245], v[226:229], v[18:21]
	s_setprio 0
	s_barrier
; #define PG8_STAGE(bufoff, gbase, voff) do { _Pragma("unroll") for (int _i = 0; _i < 2; ++_i) \
;         __builtin_amdgcn_global_load_lds((const unsigned*)((const char*)(gbase) + (voff)[_i]), (LAS unsigned*)(lds + (bufoff) + ldsw + _i * 8192), 16, 0, 0); } while (0)
; #define PG8_LDA(dst, b, h) do { _Pragma("unroll") for (int m = 0; m < 4; ++m) _Pragma("unroll") for (int k = 0; k < 2; ++k) dst[m][k] = *(const LAS bf16x8*)(lds + PG8_SA(b, h) + aoff + m * 2048 + k * 1024); } while (0)
; #define PG8_WAIT_V(n) asm volatile("s_waitcnt vmcnt(" #n ")" ::: "memory")
; #define PG8_WAIT_L(n) asm volatile("s_waitcnt lgkmcnt(" #n ")" ::: "memory")
; #define PG8_BAR __builtin_amdgcn_s_barrier()
; template <class Epi>
; DI void gemm_phase(LAS unsigned char* lds, const Gemm g, const StaticOrder& S, const Epi& E) {
;     ...
;             PG8_BAR; PG8_WAIT_L(0); PG8_MMA(0, 1, At, B1); PG8_BAR;
;             PG8_LDA(At, 1, 1); PG8_STAGE(PG8_SA(1, 0), a3, voffA);
;             PG8_BAR; PG8_WAIT_L(0); PG8_MMA(1, 0, At, B0); PG8_BAR; PG8_SCHED;
;             PG8_STAGE(PG8_SB(1, 1), b3 + hstepB, voffB);
;             PG8_WAIT_V(6); PG8_BAR; PG8_MMA(1, 1, At, B1); PG8_BAR;
;     DI void operator()(const f32x4 (&acc)[2][2][4][2], const pg8::Unit& u, int wr, int wc, int fr, int fq) const {
;         const int rowt = row_base + u.pm * 256, col0 = u.pn * 256 + wc * 32 + 4 * fq, rl = wr * 64 + fr;
;         const int cd = cond_of_row(rowt);
;         const float* gtp = gt0 + (size_t)cd * 6144;
;         float* dbase = rowt < TL ? out + (size_t)rowt * D : ctxv + (size_t)(rowt - TL) * D;
;         const float* sbase = mode ? (const float*)dbase : (rowt < TL ? xin + (size_t)rowt * D : cin + (size_t)(rowt - TL) * D);
; #pragma unroll
;         for (int bj = 0; bj < 2; ++bj) {
;             f32x4 gv[2], gg[2], bb[2], xv[2][8];
; #pragma unroll
;             for (int n = 0; n < 2; ++n) {
;                 const int c = col0 + bj * 128 + n * 16;
;                 gv[n] = *(const f32x4*)(gtp + c);
;                 gg[n] = (f32x4){1.f, 1.f, 1.f, 1.f}; bb[n] = (f32x4){0.f, 0.f, 0.f, 0.f};
;                 if (mode) { gg[n] = *(const f32x4*)(lg + c); bb[n] = *(const f32x4*)(lb + c); }
; #pragma unroll
;                 for (int q = 0; q < 8; ++q) { const int rr = rl + (q >> 2) * 128 + (q & 3) * 16; xv[n][q] = *(const f32x4*)(sbase + (size_t)rr * D + c); }
	s_add_i32 s31, s70, s38
	v_lshl_add_u64 v[214:215], v[214:215], 0, s[18:19]
	s_mov_b32 m0, s31
	s_nop 0
	global_load_lds_dwordx4 v[214:215], off
	v_lshl_add_u64 v[214:215], v[216:217], 0, s[18:19]
	s_add_i32 m0, s31, 0x2000
	s_nop 0
	global_load_lds_dwordx4 v[214:215], off
	s_mov_b32 m0, s57
	v_lshl_add_u64 v[214:215], v[246:247], 0, s[18:19]
	ds_read_b128 v[146:149], v175 offset:49152
	ds_read_b128 v[150:153], v175 offset:50176
	ds_read_b128 v[154:157], v175 offset:51200
	ds_read_b128 v[206:209], v175 offset:52224
	ds_read_b128 v[210:213], v175 offset:53248
	ds_read_b128 v[218:221], v175 offset:54272
	ds_read_b128 v[222:225], v175 offset:55296
	ds_read_b128 v[226:229], v175 offset:56320
	global_load_lds_dwordx4 v[214:215], off
	v_lshl_add_u64 v[214:215], v[248:249], 0, s[18:19]
	s_mov_b32 m0, s58
	s_nop 0
	global_load_lds_dwordx4 v[214:215], off
	s_add_u32 s28, s28, 0x80080
	s_addc_u32 s29, s29, 0
	s_add_i32 s30, s30, s38
	v_lshl_add_u64 v[252:253], s[28:29], 0, v[160:161]
	s_mov_b32 m0, s30
	s_nop 0
	global_load_lds_dwordx4 v[252:253], off
	v_lshl_add_u64 v[252:253], s[28:29], 0, v[164:165]
	s_add_i32 m0, s30, 0x2000
	s_nop 0
	global_load_lds_dwordx4 v[252:253], off
	s_waitcnt lgkmcnt(0)
	s_waitcnt vmcnt(8)
	s_barrier
	s_setprio 1
	v_mfma_f32_16x16x32_bf16 v[110:113], v[130:133], v[146:149], v[110:113]
	v_mfma_f32_16x16x32_bf16 v[78:81], v[138:141], v[146:149], v[78:81]
	v_mfma_f32_16x16x32_bf16 v[106:109], v[130:133], v[154:157], v[106:109]
	v_mfma_f32_16x16x32_bf16 v[74:77], v[138:141], v[154:157], v[74:77]
	v_mfma_f32_16x16x32_bf16 v[98:101], v[130:133], v[210:213], v[98:101]
	v_mfma_f32_16x16x32_bf16 v[70:73], v[138:141], v[210:213], v[70:73]
	v_mfma_f32_16x16x32_bf16 v[90:93], v[130:133], v[222:225], v[90:93]
	v_mfma_f32_16x16x32_bf16 v[66:69], v[138:141], v[222:225], v[66:69]
	v_mfma_f32_16x16x32_bf16 v[110:113], v[134:137], v[150:153], v[110:113]
	v_mfma_f32_16x16x32_bf16 v[78:81], v[142:145], v[150:153], v[78:81]
	v_mfma_f32_16x16x32_bf16 v[106:109], v[134:137], v[206:209], v[106:109]
	v_mfma_f32_16x16x32_bf16 v[74:77], v[142:145], v[206:209], v[74:77]
	v_mfma_f32_16x16x32_bf16 v[98:101], v[134:137], v[218:221], v[98:101]
	v_mfma_f32_16x16x32_bf16 v[70:73], v[142:145], v[218:221], v[70:73]
	v_mfma_f32_16x16x32_bf16 v[90:93], v[134:137], v[226:229], v[90:93]
	v_mfma_f32_16x16x32_bf16 v[66:69], v[142:145], v[226:229], v[66:69]
	v_mfma_f32_16x16x32_bf16 v[46:49], v[230:233], v[146:149], v[46:49]
	v_mfma_f32_16x16x32_bf16 v[14:17], v[238:241], v[146:149], v[14:17]
	v_mfma_f32_16x16x32_bf16 v[42:45], v[230:233], v[154:157], v[42:45]
	v_mfma_f32_16x16x32_bf16 v[10:13], v[238:241], v[154:157], v[10:13]
	v_mfma_f32_16x16x32_bf16 v[34:37], v[230:233], v[210:213], v[34:37]
	v_mfma_f32_16x16x32_bf16 v[6:9], v[238:241], v[210:213], v[6:9]
	v_mfma_f32_16x16x32_bf16 v[26:29], v[230:233], v[222:225], v[26:29]
	v_mfma_f32_16x16x32_bf16 v[2:5], v[238:241], v[222:225], v[2:5]
	v_mfma_f32_16x16x32_bf16 v[46:49], v[234:237], v[150:153], v[46:49]
	v_mfma_f32_16x16x32_bf16 v[14:17], v[242:245], v[150:153], v[14:17]
	v_mfma_f32_16x16x32_bf16 v[42:45], v[234:237], v[206:209], v[42:45]
	v_mfma_f32_16x16x32_bf16 v[10:13], v[242:245], v[206:209], v[10:13]
	v_mfma_f32_16x16x32_bf16 v[34:37], v[234:237], v[218:221], v[34:37]
	v_mfma_f32_16x16x32_bf16 v[6:9], v[242:245], v[218:221], v[6:9]
	v_mfma_f32_16x16x32_bf16 v[26:29], v[234:237], v[226:229], v[26:29]
	v_mfma_f32_16x16x32_bf16 v[2:5], v[242:245], v[226:229], v[2:5]
	s_setprio 0
	s_add_i32 s69, s69, 2
	s_add_u32 s6, s6, 0x100
	s_addc_u32 s7, s7, 0
	s_add_u32 s67, s67, 0x100
	s_addc_u32 s68, s68, 0
	s_cmp_gt_u32 s69, 29
	s_barrier
	s_cbranch_scc0 .LBB0_1969
	s_lshl_b32 s6, s64, 8
	v_sub_co_u32_e32 v130, vcc, s6, v183
	s_and_b64 s[28:29], vcc, exec
	s_cselect_b32 s7, s62, 0x3000
	s_cmp_gt_i32 s64, 63
	s_cselect_b32 s7, s7, 0
	s_lshl_b32 s7, s7, 2
	s_add_u32 s28, s55, s7
	s_addc_u32 s29, s56, 0
	s_ashr_i32 s7, s6, 31
	s_cmpk_lt_i32 s64, 0x80
	v_mov_b32_e32 v131, s7
	s_cselect_b64 vcc, -1, 0
	v_mov_b32_e32 v132, s6
	v_lshl_or_b32 v228, s65, 8, v167
	v_cndmask_b32_e32 v131, 0, v131, vcc
	v_cndmask_b32_e32 v130, v130, v132, vcc
	s_cselect_b32 s31, s9, s54
	s_cselect_b32 s30, s8, s53
	v_lshlrev_b64 v[130:131], 13, v[130:131]
	v_ashrrev_i32_e32 v229, 31, v228
	v_lshl_add_u64 v[130:131], s[30:31], 0, v[130:131]
	v_lshlrev_b64 v[132:133], 2, v[228:229]
	v_lshl_add_u64 v[246:247], s[14:15], 0, v[132:133]
	v_lshl_add_u64 v[248:249], s[16:17], 0, v[132:133]
	v_lshl_add_u64 v[250:251], s[28:29], 0, v[132:133]
	v_lshl_add_u64 v[232:233], v[130:131], 0, v[132:133]
	v_or_b32_e32 v130, 16, v228
	v_ashrrev_i32_e32 v131, 31, v130
	v_lshlrev_b64 v[130:131], 2, v[130:131]
	v_lshl_add_u64 v[132:133], s[14:15], 0, v[130:131]
	s_nop 0
	s_mov_b32 s65, s22
	s_mov_b64 s[28:29], s[26:27]
	s_mov_b64 s[30:31], s[24:25]
	s_mov_b32 s64, s63
	s_and_b64 vcc, exec, s[4:5]
	v_add_lshl_u32 v252, s6, v166, 1
	v_ashrrev_i32_e32 v253, 31, v252
	v_lshl_add_u64 v[252:253], v[252:253], 2, s[10:11]
	global_load_dwordx2 v[134:135], v[252:253], off
	v_add_lshl_u32 v252, s6, v170, 1
	v_ashrrev_i32_e32 v253, 31, v252
	v_lshl_add_u64 v[252:253], v[252:253], 2, s[10:11]
	global_load_dwordx2 v[156:157], v[252:253], off
	v_add_lshl_u32 v252, s6, v174, 1
	v_ashrrev_i32_e32 v253, 31, v252
	v_lshl_add_u64 v[252:253], v[252:253], 2, s[10:11]
	global_load_dwordx2 v[206:207], v[252:253], off
	v_add_lshl_u32 v252, s6, v178, 1
	v_ashrrev_i32_e32 v253, 31, v252
	v_lshl_add_u64 v[252:253], v[252:253], 2, s[10:11]
	global_load_dwordx2 v[230:231], v[252:253], off
	v_add_lshl_u32 v252, s6, v182, 1
	v_ashrrev_i32_e32 v253, 31, v252
	v_lshl_add_u64 v[252:253], v[252:253], 2, s[10:11]
;     DI void operator()(const f32x4 (&acc)[2][2][4][2], const pg8::Unit& u, int wr, int wc, int fr, int fq) const {
;     ...
;             for (int n = 0; n < 2; ++n) {
;                 const int c = col0 + bj * 128 + n * 16;
;                 gv[n] = *(const f32x4*)(gtp + c);
;                 gg[n] = (f32x4){1.f, 1.f, 1.f, 1.f}; bb[n] = (f32x4){0.f, 0.f, 0.f, 0.f};
;                 if (mode) { gg[n] = *(const f32x4*)(lg + c); bb[n] = *(const f32x4*)(lb + c); }
; #pragma unroll
;                 for (int q = 0; q < 8; ++q) { const int rr = rl + (q >> 2) * 128 + (q & 3) * 16; xv[n][q] = *(const f32x4*)(sbase + (size_t)rr * D + c); }
;             }
; #pragma unroll
;             for (int n = 0; n < 2; ++n) {
;                 const int c = col0 + bj * 128 + n * 16;
; #pragma unroll
;                 for (int q = 0; q < 8; ++q) {
;                     const int rr = rl + (q >> 2) * 128 + (q & 3) * 16;
;                     f32x4 x = xv[n][q];
;                     if (mode) { const float mu = stats[2 * (rowt + rr)], rs = stats[2 * (rowt + rr) + 1]; x = (x - mu) * rs * gg[n] + bb[n]; }
;                     *(f32x4*)(dbase + (size_t)rr * D + c) = ALPHA * x + gv[n] * acc[q >> 2][bj][q & 3][n];
	global_load_dwordx2 v[234:235], v[252:253], off
	v_add_lshl_u32 v252, s6, v186, 1
	v_ashrrev_i32_e32 v253, 31, v252
	v_lshl_add_u64 v[252:253], v[252:253], 2, s[10:11]
	global_load_dwordx2 v[240:241], v[252:253], off
	v_add_lshl_u32 v252, s6, v190, 1
	v_ashrrev_i32_e32 v253, 31, v252
	v_lshl_add_u64 v[252:253], v[252:253], 2, s[10:11]
	global_load_dwordx2 v[242:243], v[252:253], off
	v_add_lshl_u32 v252, s6, v194, 1
	v_ashrrev_i32_e32 v253, 31, v252
	v_lshl_add_u64 v[252:253], v[252:253], 2, s[10:11]
	global_load_dwordx2 v[244:245], v[252:253], off
	global_load_dwordx4 v[220:223], v[246:247], off
	global_load_dwordx4 v[224:227], v[248:249], off
	global_load_dwordx4 v[236:239], v[250:251], off
	v_lshl_add_u64 v[130:131], v[232:233], 0, v[168:169]
	global_load_dwordx4 v[136:139], v[130:131], off
	v_lshl_add_u64 v[252:253], v[232:233], 0, v[172:173]
	global_load_dwordx4 v[140:143], v[252:253], off
	v_lshl_add_u64 v[130:131], v[232:233], 0, v[176:177]
	global_load_dwordx4 v[144:147], v[130:131], off
	v_lshl_add_u64 v[252:253], v[232:233], 0, v[180:181]
	global_load_dwordx4 v[148:151], v[252:253], off
	v_lshl_add_u64 v[130:131], v[232:233], 0, v[184:185]
	global_load_dwordx4 v[152:155], v[130:131], off
	v_lshl_add_u64 v[252:253], v[232:233], 0, v[188:189]
	global_load_dwordx4 v[208:211], v[252:253], off
	v_lshl_add_u64 v[130:131], v[232:233], 0, v[192:193]
	global_load_dwordx4 v[212:215], v[130:131], off
	v_lshl_add_u64 v[252:253], v[232:233], 0, v[196:197]
	global_load_dwordx4 v[216:219], v[252:253], off
	s_waitcnt vmcnt(0)
	v_sub_f32_e32 v139, v139, v134
	v_sub_f32_e32 v138, v138, v134
	v_sub_f32_e32 v137, v137, v134
	v_sub_f32_e32 v136, v136, v134
	v_pk_mul_f32 v[136:137], v[136:137], v[134:135] op_sel:[0,1]
	v_pk_mul_f32 v[138:139], v[138:139], v[134:135] op_sel:[0,1]
	v_pk_fma_f32 v[136:137], v[220:221], v[136:137], v[224:225]
	v_pk_fma_f32 v[138:139], v[222:223], v[138:139], v[226:227]
	v_pk_mul_f32 v[136:137], v[136:137], s[20:21] op_sel_hi:[1,0]
	v_pk_mul_f32 v[138:139], v[138:139], s[20:21] op_sel_hi:[1,0]
	v_pk_fma_f32 v[126:127], v[126:127], v[236:237], v[136:137]
	v_pk_fma_f32 v[128:129], v[128:129], v[238:239], v[138:139]
	v_sub_f32_e32 v143, v143, v156
	v_sub_f32_e32 v142, v142, v156
	v_sub_f32_e32 v141, v141, v156
	v_sub_f32_e32 v140, v140, v156
	v_pk_mul_f32 v[140:141], v[140:141], v[156:157] op_sel:[0,1]
	v_pk_mul_f32 v[142:143], v[142:143], v[156:157] op_sel:[0,1]
	v_pk_fma_f32 v[140:141], v[220:221], v[140:141], v[224:225]
	v_pk_fma_f32 v[142:143], v[222:223], v[142:143], v[226:227]
	v_pk_mul_f32 v[140:141], v[140:141], s[20:21] op_sel_hi:[1,0]
	v_pk_mul_f32 v[142:143], v[142:143], s[20:21] op_sel_hi:[1,0]
	v_pk_fma_f32 v[122:123], v[122:123], v[236:237], v[140:141]
	v_pk_fma_f32 v[124:125], v[124:125], v[238:239], v[142:143]
	v_sub_f32_e32 v147, v147, v206
	v_sub_f32_e32 v146, v146, v206
	v_sub_f32_e32 v145, v145, v206
	v_sub_f32_e32 v144, v144, v206
	v_pk_mul_f32 v[144:145], v[144:145], v[206:207] op_sel:[0,1]
	v_pk_mul_f32 v[146:147], v[146:147], v[206:207] op_sel:[0,1]
	v_pk_fma_f32 v[144:145], v[220:221], v[144:145], v[224:225]
	v_pk_fma_f32 v[146:147], v[222:223], v[146:147], v[226:227]
	v_pk_mul_f32 v[144:145], v[144:145], s[20:21] op_sel_hi:[1,0]
	v_pk_mul_f32 v[146:147], v[146:147], s[20:21] op_sel_hi:[1,0]
	v_pk_fma_f32 v[118:119], v[118:119], v[236:237], v[144:145]
	v_pk_fma_f32 v[120:121], v[120:121], v[238:239], v[146:147]
	v_sub_f32_e32 v151, v151, v230
	v_sub_f32_e32 v150, v150, v230
	v_sub_f32_e32 v149, v149, v230
	v_sub_f32_e32 v148, v148, v230
	v_pk_mul_f32 v[148:149], v[148:149], v[230:231] op_sel:[0,1]
	v_pk_mul_f32 v[150:151], v[150:151], v[230:231] op_sel:[0,1]
	v_pk_fma_f32 v[148:149], v[220:221], v[148:149], v[224:225]
	v_pk_fma_f32 v[150:151], v[222:223], v[150:151], v[226:227]
	v_pk_mul_f32 v[148:149], v[148:149], s[20:21] op_sel_hi:[1,0]
	v_pk_mul_f32 v[150:151], v[150:151], s[20:21] op_sel_hi:[1,0]
	v_pk_fma_f32 v[114:115], v[114:115], v[236:237], v[148:149]
	v_pk_fma_f32 v[116:117], v[116:117], v[238:239], v[150:151]
	v_sub_f32_e32 v155, v155, v234
	v_sub_f32_e32 v154, v154, v234
	v_sub_f32_e32 v153, v153, v234
	v_sub_f32_e32 v152, v152, v234
	v_pk_mul_f32 v[152:153], v[152:153], v[234:235] op_sel:[0,1]
	v_pk_mul_f32 v[154:155], v[154:155], v[234:235] op_sel:[0,1]
	v_pk_fma_f32 v[152:153], v[220:221], v[152:153], v[224:225]
	v_pk_fma_f32 v[154:155], v[222:223], v[154:155], v[226:227]
	v_pk_mul_f32 v[152:153], v[152:153], s[20:21] op_sel_hi:[1,0]
	v_pk_mul_f32 v[154:155], v[154:155], s[20:21] op_sel_hi:[1,0]
	v_pk_fma_f32 v[110:111], v[110:111], v[236:237], v[152:153]
	v_pk_fma_f32 v[112:113], v[112:113], v[238:239], v[154:155]
	v_sub_f32_e32 v211, v211, v240
	v_sub_f32_e32 v210, v210, v240
	v_sub_f32_e32 v209, v209, v240
	v_sub_f32_e32 v208, v208, v240
	v_pk_mul_f32 v[208:209], v[208:209], v[240:241] op_sel:[0,1]
	v_pk_mul_f32 v[210:211], v[210:211], v[240:241] op_sel:[0,1]
	v_pk_fma_f32 v[208:209], v[220:221], v[208:209], v[224:225]
	v_pk_fma_f32 v[210:211], v[222:223], v[210:211], v[226:227]
	v_pk_mul_f32 v[208:209], v[208:209], s[20:21] op_sel_hi:[1,0]
	v_pk_mul_f32 v[210:211], v[210:211], s[20:21] op_sel_hi:[1,0]
	v_pk_fma_f32 v[106:107], v[106:107], v[236:237], v[208:209]
	v_pk_fma_f32 v[108:109], v[108:109], v[238:239], v[210:211]
	v_sub_f32_e32 v215, v215, v242
	v_sub_f32_e32 v214, v214, v242
	v_sub_f32_e32 v213, v213, v242
	v_sub_f32_e32 v212, v212, v242
	v_pk_mul_f32 v[212:213], v[212:213], v[242:243] op_sel:[0,1]
	v_pk_mul_f32 v[214:215], v[214:215], v[242:243] op_sel:[0,1]
	v_pk_fma_f32 v[212:213], v[220:221], v[212:213], v[224:225]
	v_pk_fma_f32 v[214:215], v[222:223], v[214:215], v[226:227]
;     DI void operator()(const f32x4 (&acc)[2][2][4][2], const pg8::Unit& u, int wr, int wc, int fr, int fq) const {
;     ...
;             for (int n = 0; n < 2; ++n) {
;                 const int c = col0 + bj * 128 + n * 16;
;                 gv[n] = *(const f32x4*)(gtp + c);
;                 gg[n] = (f32x4){1.f, 1.f, 1.f, 1.f}; bb[n] = (f32x4){0.f, 0.f, 0.f, 0.f};
;                 if (mode) { gg[n] = *(const f32x4*)(lg + c); bb[n] = *(const f32x4*)(lb + c); }
; #pragma unroll
;                 for (int q = 0; q < 8; ++q) { const int rr = rl + (q >> 2) * 128 + (q & 3) * 16; xv[n][q] = *(const f32x4*)(sbase + (size_t)rr * D + c); }
;             }
; #pragma unroll
;             for (int n = 0; n < 2; ++n) {
;                 const int c = col0 + bj * 128 + n * 16;
; #pragma unroll
;                 for (int q = 0; q < 8; ++q) {
;                     const int rr = rl + (q >> 2) * 128 + (q & 3) * 16;
;                     f32x4 x = xv[n][q];
;                     if (mode) { const float mu = stats[2 * (rowt + rr)], rs = stats[2 * (rowt + rr) + 1]; x = (x - mu) * rs * gg[n] + bb[n]; }
;                     *(f32x4*)(dbase + (size_t)rr * D + c) = ALPHA * x + gv[n] * acc[q >> 2][bj][q & 3][n];
	v_pk_mul_f32 v[212:213], v[212:213], s[20:21] op_sel_hi:[1,0]
	v_pk_mul_f32 v[214:215], v[214:215], s[20:21] op_sel_hi:[1,0]
	v_pk_fma_f32 v[98:99], v[98:99], v[236:237], v[212:213]
	v_pk_fma_f32 v[100:101], v[100:101], v[238:239], v[214:215]
	v_sub_f32_e32 v219, v219, v244
	v_sub_f32_e32 v218, v218, v244
	v_sub_f32_e32 v217, v217, v244
	v_sub_f32_e32 v216, v216, v244
	v_pk_mul_f32 v[216:217], v[216:217], v[244:245] op_sel:[0,1]
	v_pk_mul_f32 v[218:219], v[218:219], v[244:245] op_sel:[0,1]
	v_pk_fma_f32 v[216:217], v[220:221], v[216:217], v[224:225]
	v_pk_fma_f32 v[218:219], v[222:223], v[218:219], v[226:227]
	v_pk_mul_f32 v[216:217], v[216:217], s[20:21] op_sel_hi:[1,0]
	v_pk_mul_f32 v[218:219], v[218:219], s[20:21] op_sel_hi:[1,0]
	v_pk_fma_f32 v[90:91], v[90:91], v[236:237], v[216:217]
	v_pk_fma_f32 v[92:93], v[92:93], v[238:239], v[218:219]
	global_load_dwordx4 v[220:223], v[246:247], off offset:64
	global_load_dwordx4 v[224:227], v[248:249], off offset:64
	global_load_dwordx4 v[236:239], v[250:251], off offset:64
	v_lshl_add_u64 v[130:131], v[232:233], 0, v[168:169]
	global_load_dwordx4 v[136:139], v[130:131], off offset:64
	v_lshl_add_u64 v[252:253], v[232:233], 0, v[172:173]
	global_load_dwordx4 v[140:143], v[252:253], off offset:64
	v_lshl_add_u64 v[130:131], v[232:233], 0, v[176:177]
	global_load_dwordx4 v[144:147], v[130:131], off offset:64
	v_lshl_add_u64 v[252:253], v[232:233], 0, v[180:181]
	global_load_dwordx4 v[148:151], v[252:253], off offset:64
	v_lshl_add_u64 v[130:131], v[232:233], 0, v[184:185]
	global_load_dwordx4 v[152:155], v[130:131], off offset:64
	v_lshl_add_u64 v[252:253], v[232:233], 0, v[188:189]
	global_load_dwordx4 v[208:211], v[252:253], off offset:64
	v_lshl_add_u64 v[130:131], v[232:233], 0, v[192:193]
	global_load_dwordx4 v[212:215], v[130:131], off offset:64
	v_lshl_add_u64 v[252:253], v[232:233], 0, v[196:197]
	global_load_dwordx4 v[216:219], v[252:253], off offset:64
	v_lshl_add_u64 v[130:131], v[232:233], 0, v[168:169]
	global_store_dwordx4 v[130:131], v[126:129], off
	v_lshl_add_u64 v[252:253], v[232:233], 0, v[172:173]
	global_store_dwordx4 v[252:253], v[122:125], off
	v_lshl_add_u64 v[130:131], v[232:233], 0, v[176:177]
	global_store_dwordx4 v[130:131], v[118:121], off
	v_lshl_add_u64 v[252:253], v[232:233], 0, v[180:181]
	global_store_dwordx4 v[252:253], v[114:117], off
	v_lshl_add_u64 v[130:131], v[232:233], 0, v[184:185]
	global_store_dwordx4 v[130:131], v[110:113], off
	v_lshl_add_u64 v[252:253], v[232:233], 0, v[188:189]
	global_store_dwordx4 v[252:253], v[106:109], off
	v_lshl_add_u64 v[130:131], v[232:233], 0, v[192:193]
	global_store_dwordx4 v[130:131], v[98:101], off
	v_lshl_add_u64 v[252:253], v[232:233], 0, v[196:197]
	global_store_dwordx4 v[252:253], v[90:93], off
	s_waitcnt vmcnt(8)
	v_sub_f32_e32 v139, v139, v134
	v_sub_f32_e32 v138, v138, v134
	v_sub_f32_e32 v137, v137, v134
	v_sub_f32_e32 v136, v136, v134
	v_pk_mul_f32 v[136:137], v[136:137], v[134:135] op_sel:[0,1]
	v_pk_mul_f32 v[138:139], v[138:139], v[134:135] op_sel:[0,1]
	v_pk_fma_f32 v[136:137], v[220:221], v[136:137], v[224:225]
	v_pk_fma_f32 v[138:139], v[222:223], v[138:139], v[226:227]
	v_pk_mul_f32 v[136:137], v[136:137], s[20:21] op_sel_hi:[1,0]
	v_pk_mul_f32 v[138:139], v[138:139], s[20:21] op_sel_hi:[1,0]
	v_pk_fma_f32 v[102:103], v[102:103], v[236:237], v[136:137]
	v_pk_fma_f32 v[104:105], v[104:105], v[238:239], v[138:139]
	v_sub_f32_e32 v143, v143, v156
	v_sub_f32_e32 v142, v142, v156
	v_sub_f32_e32 v141, v141, v156
	v_sub_f32_e32 v140, v140, v156
	v_pk_mul_f32 v[140:141], v[140:141], v[156:157] op_sel:[0,1]
	v_pk_mul_f32 v[142:143], v[142:143], v[156:157] op_sel:[0,1]
	v_pk_fma_f32 v[140:141], v[220:221], v[140:141], v[224:225]
	v_pk_fma_f32 v[142:143], v[222:223], v[142:143], v[226:227]
	v_pk_mul_f32 v[140:141], v[140:141], s[20:21] op_sel_hi:[1,0]
	v_pk_mul_f32 v[142:143], v[142:143], s[20:21] op_sel_hi:[1,0]
	v_pk_fma_f32 v[94:95], v[94:95], v[236:237], v[140:141]
	v_pk_fma_f32 v[96:97], v[96:97], v[238:239], v[142:143]
	v_sub_f32_e32 v147, v147, v206
	v_sub_f32_e32 v146, v146, v206
	v_sub_f32_e32 v145, v145, v206
	v_sub_f32_e32 v144, v144, v206
	v_pk_mul_f32 v[144:145], v[144:145], v[206:207] op_sel:[0,1]
	v_pk_mul_f32 v[146:147], v[146:147], v[206:207] op_sel:[0,1]
	v_pk_fma_f32 v[144:145], v[220:221], v[144:145], v[224:225]
	v_pk_fma_f32 v[146:147], v[222:223], v[146:147], v[226:227]
	v_pk_mul_f32 v[144:145], v[144:145], s[20:21] op_sel_hi:[1,0]
	v_pk_mul_f32 v[146:147], v[146:147], s[20:21] op_sel_hi:[1,0]
	v_pk_fma_f32 v[86:87], v[86:87], v[236:237], v[144:145]
	v_pk_fma_f32 v[88:89], v[88:89], v[238:239], v[146:147]
	v_sub_f32_e32 v151, v151, v230
	v_sub_f32_e32 v150, v150, v230
	v_sub_f32_e32 v149, v149, v230
	v_sub_f32_e32 v148, v148, v230
	v_pk_mul_f32 v[148:149], v[148:149], v[230:231] op_sel:[0,1]
	v_pk_mul_f32 v[150:151], v[150:151], v[230:231] op_sel:[0,1]
	v_pk_fma_f32 v[148:149], v[220:221], v[148:149], v[224:225]
	v_pk_fma_f32 v[150:151], v[222:223], v[150:151], v[226:227]
	v_pk_mul_f32 v[148:149], v[148:149], s[20:21] op_sel_hi:[1,0]
	v_pk_mul_f32 v[150:151], v[150:151], s[20:21] op_sel_hi:[1,0]
	v_pk_fma_f32 v[82:83], v[82:83], v[236:237], v[148:149]
	v_pk_fma_f32 v[84:85], v[84:85], v[238:239], v[150:151]
	v_sub_f32_e32 v155, v155, v234
	v_sub_f32_e32 v154, v154, v234
	v_sub_f32_e32 v153, v153, v234
	v_sub_f32_e32 v152, v152, v234
	v_pk_mul_f32 v[152:153], v[152:153], v[234:235] op_sel:[0,1]
	v_pk_mul_f32 v[154:155], v[154:155], v[234:235] op_sel:[0,1]
	v_pk_fma_f32 v[152:153], v[220:221], v[152:153], v[224:225]
	v_pk_fma_f32 v[154:155], v[222:223], v[154:155], v[226:227]
;     DI void operator()(const f32x4 (&acc)[2][2][4][2], const pg8::Unit& u, int wr, int wc, int fr, int fq) const {
;     ...
;             for (int n = 0; n < 2; ++n) {
;                 const int c = col0 + bj * 128 + n * 16;
;                 gv[n] = *(const f32x4*)(gtp + c);
;                 gg[n] = (f32x4){1.f, 1.f, 1.f, 1.f}; bb[n] = (f32x4){0.f, 0.f, 0.f, 0.f};
;                 if (mode) { gg[n] = *(const f32x4*)(lg + c); bb[n] = *(const f32x4*)(lb + c); }
; #pragma unroll
;                 for (int q = 0; q < 8; ++q) { const int rr = rl + (q >> 2) * 128 + (q & 3) * 16; xv[n][q] = *(const f32x4*)(sbase + (size_t)rr * D + c); }
;             }
; #pragma unroll
;             for (int n = 0; n < 2; ++n) {
;                 const int c = col0 + bj * 128 + n * 16;
; #pragma unroll
;                 for (int q = 0; q < 8; ++q) {
;                     const int rr = rl + (q >> 2) * 128 + (q & 3) * 16;
;                     f32x4 x = xv[n][q];
;                     if (mode) { const float mu = stats[2 * (rowt + rr)], rs = stats[2 * (rowt + rr) + 1]; x = (x - mu) * rs * gg[n] + bb[n]; }
;                     *(f32x4*)(dbase + (size_t)rr * D + c) = ALPHA * x + gv[n] * acc[q >> 2][bj][q & 3][n];
	v_pk_mul_f32 v[152:153], v[152:153], s[20:21] op_sel_hi:[1,0]
	v_pk_mul_f32 v[154:155], v[154:155], s[20:21] op_sel_hi:[1,0]
	v_pk_fma_f32 v[78:79], v[78:79], v[236:237], v[152:153]
	v_pk_fma_f32 v[80:81], v[80:81], v[238:239], v[154:155]
	v_sub_f32_e32 v211, v211, v240
	v_sub_f32_e32 v210, v210, v240
	v_sub_f32_e32 v209, v209, v240
	v_sub_f32_e32 v208, v208, v240
	v_pk_mul_f32 v[208:209], v[208:209], v[240:241] op_sel:[0,1]
	v_pk_mul_f32 v[210:211], v[210:211], v[240:241] op_sel:[0,1]
	v_pk_fma_f32 v[208:209], v[220:221], v[208:209], v[224:225]
	v_pk_fma_f32 v[210:211], v[222:223], v[210:211], v[226:227]
	v_pk_mul_f32 v[208:209], v[208:209], s[20:21] op_sel_hi:[1,0]
	v_pk_mul_f32 v[210:211], v[210:211], s[20:21] op_sel_hi:[1,0]
	v_pk_fma_f32 v[74:75], v[74:75], v[236:237], v[208:209]
	v_pk_fma_f32 v[76:77], v[76:77], v[238:239], v[210:211]
	v_sub_f32_e32 v215, v215, v242
	v_sub_f32_e32 v214, v214, v242
	v_sub_f32_e32 v213, v213, v242
	v_sub_f32_e32 v212, v212, v242
	v_pk_mul_f32 v[212:213], v[212:213], v[242:243] op_sel:[0,1]
	v_pk_mul_f32 v[214:215], v[214:215], v[242:243] op_sel:[0,1]
	v_pk_fma_f32 v[212:213], v[220:221], v[212:213], v[224:225]
	v_pk_fma_f32 v[214:215], v[222:223], v[214:215], v[226:227]
	v_pk_mul_f32 v[212:213], v[212:213], s[20:21] op_sel_hi:[1,0]
	v_pk_mul_f32 v[214:215], v[214:215], s[20:21] op_sel_hi:[1,0]
	v_pk_fma_f32 v[70:71], v[70:71], v[236:237], v[212:213]
	v_pk_fma_f32 v[72:73], v[72:73], v[238:239], v[214:215]
	v_sub_f32_e32 v219, v219, v244
	v_sub_f32_e32 v218, v218, v244
	v_sub_f32_e32 v217, v217, v244
	v_sub_f32_e32 v216, v216, v244
	v_pk_mul_f32 v[216:217], v[216:217], v[244:245] op_sel:[0,1]
	v_pk_mul_f32 v[218:219], v[218:219], v[244:245] op_sel:[0,1]
	v_pk_fma_f32 v[216:217], v[220:221], v[216:217], v[224:225]
	v_pk_fma_f32 v[218:219], v[222:223], v[218:219], v[226:227]
	v_pk_mul_f32 v[216:217], v[216:217], s[20:21] op_sel_hi:[1,0]
	v_pk_mul_f32 v[218:219], v[218:219], s[20:21] op_sel_hi:[1,0]
	v_pk_fma_f32 v[66:67], v[66:67], v[236:237], v[216:217]
	v_pk_fma_f32 v[68:69], v[68:69], v[238:239], v[218:219]
	global_load_dwordx4 v[220:223], v[246:247], off offset:512
	global_load_dwordx4 v[224:227], v[248:249], off offset:512
	global_load_dwordx4 v[236:239], v[250:251], off offset:512
	v_lshl_add_u64 v[130:131], v[232:233], 0, v[168:169]
	global_load_dwordx4 v[136:139], v[130:131], off offset:512
	v_lshl_add_u64 v[252:253], v[232:233], 0, v[172:173]
	global_load_dwordx4 v[140:143], v[252:253], off offset:512
	v_lshl_add_u64 v[130:131], v[232:233], 0, v[176:177]
	global_load_dwordx4 v[144:147], v[130:131], off offset:512
	v_lshl_add_u64 v[252:253], v[232:233], 0, v[180:181]
	global_load_dwordx4 v[148:151], v[252:253], off offset:512
	v_lshl_add_u64 v[130:131], v[232:233], 0, v[184:185]
	global_load_dwordx4 v[152:155], v[130:131], off offset:512
	v_lshl_add_u64 v[252:253], v[232:233], 0, v[188:189]
	global_load_dwordx4 v[208:211], v[252:253], off offset:512
	v_lshl_add_u64 v[130:131], v[232:233], 0, v[192:193]
	global_load_dwordx4 v[212:215], v[130:131], off offset:512
	v_lshl_add_u64 v[252:253], v[232:233], 0, v[196:197]
	global_load_dwordx4 v[216:219], v[252:253], off offset:512
	v_lshl_add_u64 v[130:131], v[232:233], 0, v[168:169]
	global_store_dwordx4 v[130:131], v[102:105], off offset:64
	v_lshl_add_u64 v[252:253], v[232:233], 0, v[172:173]
	global_store_dwordx4 v[252:253], v[94:97], off offset:64
	v_lshl_add_u64 v[130:131], v[232:233], 0, v[176:177]
	global_store_dwordx4 v[130:131], v[86:89], off offset:64
	v_lshl_add_u64 v[252:253], v[232:233], 0, v[180:181]
	global_store_dwordx4 v[252:253], v[82:85], off offset:64
	v_lshl_add_u64 v[130:131], v[232:233], 0, v[184:185]
	global_store_dwordx4 v[130:131], v[78:81], off offset:64
	v_lshl_add_u64 v[252:253], v[232:233], 0, v[188:189]
	global_store_dwordx4 v[252:253], v[74:77], off offset:64
	v_lshl_add_u64 v[130:131], v[232:233], 0, v[192:193]
	global_store_dwordx4 v[130:131], v[70:73], off offset:64
	v_lshl_add_u64 v[252:253], v[232:233], 0, v[196:197]
	global_store_dwordx4 v[252:253], v[66:69], off offset:64
	s_waitcnt vmcnt(8)
	v_sub_f32_e32 v139, v139, v134
	v_sub_f32_e32 v138, v138, v134
	v_sub_f32_e32 v137, v137, v134
	v_sub_f32_e32 v136, v136, v134
	v_pk_mul_f32 v[136:137], v[136:137], v[134:135] op_sel:[0,1]
	v_pk_mul_f32 v[138:139], v[138:139], v[134:135] op_sel:[0,1]
	v_pk_fma_f32 v[136:137], v[220:221], v[136:137], v[224:225]
	v_pk_fma_f32 v[138:139], v[222:223], v[138:139], v[226:227]
	v_pk_mul_f32 v[136:137], v[136:137], s[20:21] op_sel_hi:[1,0]
	v_pk_mul_f32 v[138:139], v[138:139], s[20:21] op_sel_hi:[1,0]
	v_pk_fma_f32 v[62:63], v[62:63], v[236:237], v[136:137]
	v_pk_fma_f32 v[64:65], v[64:65], v[238:239], v[138:139]
	v_sub_f32_e32 v143, v143, v156
	v_sub_f32_e32 v142, v142, v156
	v_sub_f32_e32 v141, v141, v156
	v_sub_f32_e32 v140, v140, v156
	v_pk_mul_f32 v[140:141], v[140:141], v[156:157] op_sel:[0,1]
	v_pk_mul_f32 v[142:143], v[142:143], v[156:157] op_sel:[0,1]
	v_pk_fma_f32 v[140:141], v[220:221], v[140:141], v[224:225]
	v_pk_fma_f32 v[142:143], v[222:223], v[142:143], v[226:227]
	v_pk_mul_f32 v[140:141], v[140:141], s[20:21] op_sel_hi:[1,0]
	v_pk_mul_f32 v[142:143], v[142:143], s[20:21] op_sel_hi:[1,0]
	v_pk_fma_f32 v[58:59], v[58:59], v[236:237], v[140:141]
	v_pk_fma_f32 v[60:61], v[60:61], v[238:239], v[142:143]
	v_sub_f32_e32 v147, v147, v206
	v_sub_f32_e32 v146, v146, v206
	v_sub_f32_e32 v145, v145, v206
	v_sub_f32_e32 v144, v144, v206
	v_pk_mul_f32 v[144:145], v[144:145], v[206:207] op_sel:[0,1]
	v_pk_mul_f32 v[146:147], v[146:147], v[206:207] op_sel:[0,1]
	v_pk_fma_f32 v[144:145], v[220:221], v[144:145], v[224:225]
;     DI void operator()(const f32x4 (&acc)[2][2][4][2], const pg8::Unit& u, int wr, int wc, int fr, int fq) const {
;     ...
;             for (int n = 0; n < 2; ++n) {
;                 const int c = col0 + bj * 128 + n * 16;
;                 gv[n] = *(const f32x4*)(gtp + c);
;                 gg[n] = (f32x4){1.f, 1.f, 1.f, 1.f}; bb[n] = (f32x4){0.f, 0.f, 0.f, 0.f};
;                 if (mode) { gg[n] = *(const f32x4*)(lg + c); bb[n] = *(const f32x4*)(lb + c); }
; #pragma unroll
;                 for (int q = 0; q < 8; ++q) { const int rr = rl + (q >> 2) * 128 + (q & 3) * 16; xv[n][q] = *(const f32x4*)(sbase + (size_t)rr * D + c); }
;             }
; #pragma unroll
;             for (int n = 0; n < 2; ++n) {
;                 const int c = col0 + bj * 128 + n * 16;
; #pragma unroll
;                 for (int q = 0; q < 8; ++q) {
;                     const int rr = rl + (q >> 2) * 128 + (q & 3) * 16;
;                     f32x4 x = xv[n][q];
;                     if (mode) { const float mu = stats[2 * (rowt + rr)], rs = stats[2 * (rowt + rr) + 1]; x = (x - mu) * rs * gg[n] + bb[n]; }
;                     *(f32x4*)(dbase + (size_t)rr * D + c) = ALPHA * x + gv[n] * acc[q >> 2][bj][q & 3][n];
	v_pk_fma_f32 v[146:147], v[222:223], v[146:147], v[226:227]
	v_pk_mul_f32 v[144:145], v[144:145], s[20:21] op_sel_hi:[1,0]
	v_pk_mul_f32 v[146:147], v[146:147], s[20:21] op_sel_hi:[1,0]
	v_pk_fma_f32 v[54:55], v[54:55], v[236:237], v[144:145]
	v_pk_fma_f32 v[56:57], v[56:57], v[238:239], v[146:147]
	v_sub_f32_e32 v151, v151, v230
	v_sub_f32_e32 v150, v150, v230
	v_sub_f32_e32 v149, v149, v230
	v_sub_f32_e32 v148, v148, v230
	v_pk_mul_f32 v[148:149], v[148:149], v[230:231] op_sel:[0,1]
	v_pk_mul_f32 v[150:151], v[150:151], v[230:231] op_sel:[0,1]
	v_pk_fma_f32 v[148:149], v[220:221], v[148:149], v[224:225]
	v_pk_fma_f32 v[150:151], v[222:223], v[150:151], v[226:227]
	v_pk_mul_f32 v[148:149], v[148:149], s[20:21] op_sel_hi:[1,0]
	v_pk_mul_f32 v[150:151], v[150:151], s[20:21] op_sel_hi:[1,0]
	v_pk_fma_f32 v[50:51], v[50:51], v[236:237], v[148:149]
	v_pk_fma_f32 v[52:53], v[52:53], v[238:239], v[150:151]
	v_sub_f32_e32 v155, v155, v234
	v_sub_f32_e32 v154, v154, v234
	v_sub_f32_e32 v153, v153, v234
	v_sub_f32_e32 v152, v152, v234
	v_pk_mul_f32 v[152:153], v[152:153], v[234:235] op_sel:[0,1]
	v_pk_mul_f32 v[154:155], v[154:155], v[234:235] op_sel:[0,1]
	v_pk_fma_f32 v[152:153], v[220:221], v[152:153], v[224:225]
	v_pk_fma_f32 v[154:155], v[222:223], v[154:155], v[226:227]
	v_pk_mul_f32 v[152:153], v[152:153], s[20:21] op_sel_hi:[1,0]
	v_pk_mul_f32 v[154:155], v[154:155], s[20:21] op_sel_hi:[1,0]
	v_pk_fma_f32 v[46:47], v[46:47], v[236:237], v[152:153]
	v_pk_fma_f32 v[48:49], v[48:49], v[238:239], v[154:155]
	v_sub_f32_e32 v211, v211, v240
	v_sub_f32_e32 v210, v210, v240
	v_sub_f32_e32 v209, v209, v240
	v_sub_f32_e32 v208, v208, v240
	v_pk_mul_f32 v[208:209], v[208:209], v[240:241] op_sel:[0,1]
	v_pk_mul_f32 v[210:211], v[210:211], v[240:241] op_sel:[0,1]
	v_pk_fma_f32 v[208:209], v[220:221], v[208:209], v[224:225]
	v_pk_fma_f32 v[210:211], v[222:223], v[210:211], v[226:227]
	v_pk_mul_f32 v[208:209], v[208:209], s[20:21] op_sel_hi:[1,0]
	v_pk_mul_f32 v[210:211], v[210:211], s[20:21] op_sel_hi:[1,0]
	v_pk_fma_f32 v[42:43], v[42:43], v[236:237], v[208:209]
	v_pk_fma_f32 v[44:45], v[44:45], v[238:239], v[210:211]
	v_sub_f32_e32 v215, v215, v242
	v_sub_f32_e32 v214, v214, v242
	v_sub_f32_e32 v213, v213, v242
	v_sub_f32_e32 v212, v212, v242
	v_pk_mul_f32 v[212:213], v[212:213], v[242:243] op_sel:[0,1]
	v_pk_mul_f32 v[214:215], v[214:215], v[242:243] op_sel:[0,1]
	v_pk_fma_f32 v[212:213], v[220:221], v[212:213], v[224:225]
	v_pk_fma_f32 v[214:215], v[222:223], v[214:215], v[226:227]
	v_pk_mul_f32 v[212:213], v[212:213], s[20:21] op_sel_hi:[1,0]
	v_pk_mul_f32 v[214:215], v[214:215], s[20:21] op_sel_hi:[1,0]
	v_pk_fma_f32 v[34:35], v[34:35], v[236:237], v[212:213]
	v_pk_fma_f32 v[36:37], v[36:37], v[238:239], v[214:215]
	v_sub_f32_e32 v219, v219, v244
	v_sub_f32_e32 v218, v218, v244
	v_sub_f32_e32 v217, v217, v244
	v_sub_f32_e32 v216, v216, v244
	v_pk_mul_f32 v[216:217], v[216:217], v[244:245] op_sel:[0,1]
	v_pk_mul_f32 v[218:219], v[218:219], v[244:245] op_sel:[0,1]
	v_pk_fma_f32 v[216:217], v[220:221], v[216:217], v[224:225]
	v_pk_fma_f32 v[218:219], v[222:223], v[218:219], v[226:227]
	v_pk_mul_f32 v[216:217], v[216:217], s[20:21] op_sel_hi:[1,0]
	v_pk_mul_f32 v[218:219], v[218:219], s[20:21] op_sel_hi:[1,0]
	v_pk_fma_f32 v[26:27], v[26:27], v[236:237], v[216:217]
	v_pk_fma_f32 v[28:29], v[28:29], v[238:239], v[218:219]
	global_load_dwordx4 v[220:223], v[246:247], off offset:576
	global_load_dwordx4 v[224:227], v[248:249], off offset:576
	global_load_dwordx4 v[236:239], v[250:251], off offset:576
	v_lshl_add_u64 v[130:131], v[232:233], 0, v[168:169]
	global_load_dwordx4 v[136:139], v[130:131], off offset:576
	v_lshl_add_u64 v[252:253], v[232:233], 0, v[172:173]
	global_load_dwordx4 v[140:143], v[252:253], off offset:576
	v_lshl_add_u64 v[130:131], v[232:233], 0, v[176:177]
	global_load_dwordx4 v[144:147], v[130:131], off offset:576
	v_lshl_add_u64 v[252:253], v[232:233], 0, v[180:181]
	global_load_dwordx4 v[148:151], v[252:253], off offset:576
	v_lshl_add_u64 v[130:131], v[232:233], 0, v[184:185]
	global_load_dwordx4 v[152:155], v[130:131], off offset:576
	v_lshl_add_u64 v[252:253], v[232:233], 0, v[188:189]
	global_load_dwordx4 v[208:211], v[252:253], off offset:576
	v_lshl_add_u64 v[130:131], v[232:233], 0, v[192:193]
	global_load_dwordx4 v[212:215], v[130:131], off offset:576
	v_lshl_add_u64 v[252:253], v[232:233], 0, v[196:197]
	global_load_dwordx4 v[216:219], v[252:253], off offset:576
	v_lshl_add_u64 v[130:131], v[232:233], 0, v[168:169]
	global_store_dwordx4 v[130:131], v[62:65], off offset:512
	v_lshl_add_u64 v[252:253], v[232:233], 0, v[172:173]
	global_store_dwordx4 v[252:253], v[58:61], off offset:512
	v_lshl_add_u64 v[130:131], v[232:233], 0, v[176:177]
	global_store_dwordx4 v[130:131], v[54:57], off offset:512
	v_lshl_add_u64 v[252:253], v[232:233], 0, v[180:181]
	global_store_dwordx4 v[252:253], v[50:53], off offset:512
	v_lshl_add_u64 v[130:131], v[232:233], 0, v[184:185]
	global_store_dwordx4 v[130:131], v[46:49], off offset:512
	v_lshl_add_u64 v[252:253], v[232:233], 0, v[188:189]
	global_store_dwordx4 v[252:253], v[42:45], off offset:512
	v_lshl_add_u64 v[130:131], v[232:233], 0, v[192:193]
	global_store_dwordx4 v[130:131], v[34:37], off offset:512
	v_lshl_add_u64 v[252:253], v[232:233], 0, v[196:197]
	global_store_dwordx4 v[252:253], v[26:29], off offset:512
	s_waitcnt vmcnt(8)
;     DI void operator()(const f32x4 (&acc)[2][2][4][2], const pg8::Unit& u, int wr, int wc, int fr, int fq) const {
;     ...
;             for (int n = 0; n < 2; ++n) {
;                 const int c = col0 + bj * 128 + n * 16;
;                 gv[n] = *(const f32x4*)(gtp + c);
;                 gg[n] = (f32x4){1.f, 1.f, 1.f, 1.f}; bb[n] = (f32x4){0.f, 0.f, 0.f, 0.f};
;                 if (mode) { gg[n] = *(const f32x4*)(lg + c); bb[n] = *(const f32x4*)(lb + c); }
; #pragma unroll
;                 for (int q = 0; q < 8; ++q) { const int rr = rl + (q >> 2) * 128 + (q & 3) * 16; xv[n][q] = *(const f32x4*)(sbase + (size_t)rr * D + c); }
;             }
; #pragma unroll
;             for (int n = 0; n < 2; ++n) {
;                 const int c = col0 + bj * 128 + n * 16;
; #pragma unroll
;                 for (int q = 0; q < 8; ++q) {
;                     const int rr = rl + (q >> 2) * 128 + (q & 3) * 16;
;                     f32x4 x = xv[n][q];
;                     if (mode) { const float mu = stats[2 * (rowt + rr)], rs = stats[2 * (rowt + rr) + 1]; x = (x - mu) * rs * gg[n] + bb[n]; }
;                     *(f32x4*)(dbase + (size_t)rr * D + c) = ALPHA * x + gv[n] * acc[q >> 2][bj][q & 3][n];
	v_sub_f32_e32 v139, v139, v134
	v_sub_f32_e32 v138, v138, v134
	v_sub_f32_e32 v137, v137, v134
	v_sub_f32_e32 v136, v136, v134
	v_pk_mul_f32 v[136:137], v[136:137], v[134:135] op_sel:[0,1]
	v_pk_mul_f32 v[138:139], v[138:139], v[134:135] op_sel:[0,1]
	v_pk_fma_f32 v[136:137], v[220:221], v[136:137], v[224:225]
	v_pk_fma_f32 v[138:139], v[222:223], v[138:139], v[226:227]
	v_pk_mul_f32 v[136:137], v[136:137], s[20:21] op_sel_hi:[1,0]
	v_pk_mul_f32 v[138:139], v[138:139], s[20:21] op_sel_hi:[1,0]
	v_pk_fma_f32 v[38:39], v[38:39], v[236:237], v[136:137]
	v_pk_fma_f32 v[40:41], v[40:41], v[238:239], v[138:139]
	v_sub_f32_e32 v143, v143, v156
	v_sub_f32_e32 v142, v142, v156
	v_sub_f32_e32 v141, v141, v156
	v_sub_f32_e32 v140, v140, v156
	v_pk_mul_f32 v[140:141], v[140:141], v[156:157] op_sel:[0,1]
	v_pk_mul_f32 v[142:143], v[142:143], v[156:157] op_sel:[0,1]
	v_pk_fma_f32 v[140:141], v[220:221], v[140:141], v[224:225]
	v_pk_fma_f32 v[142:143], v[222:223], v[142:143], v[226:227]
	v_pk_mul_f32 v[140:141], v[140:141], s[20:21] op_sel_hi:[1,0]
	v_pk_mul_f32 v[142:143], v[142:143], s[20:21] op_sel_hi:[1,0]
	v_pk_fma_f32 v[30:31], v[30:31], v[236:237], v[140:141]
	v_pk_fma_f32 v[32:33], v[32:33], v[238:239], v[142:143]
	v_sub_f32_e32 v147, v147, v206
	v_sub_f32_e32 v146, v146, v206
	v_sub_f32_e32 v145, v145, v206
	v_sub_f32_e32 v144, v144, v206
	v_pk_mul_f32 v[144:145], v[144:145], v[206:207] op_sel:[0,1]
	v_pk_mul_f32 v[146:147], v[146:147], v[206:207] op_sel:[0,1]
	v_pk_fma_f32 v[144:145], v[220:221], v[144:145], v[224:225]
	v_pk_fma_f32 v[146:147], v[222:223], v[146:147], v[226:227]
	v_pk_mul_f32 v[144:145], v[144:145], s[20:21] op_sel_hi:[1,0]
	v_pk_mul_f32 v[146:147], v[146:147], s[20:21] op_sel_hi:[1,0]
	v_pk_fma_f32 v[22:23], v[22:23], v[236:237], v[144:145]
	v_pk_fma_f32 v[24:25], v[24:25], v[238:239], v[146:147]
	v_sub_f32_e32 v151, v151, v230
	v_sub_f32_e32 v150, v150, v230
	v_sub_f32_e32 v149, v149, v230
	v_sub_f32_e32 v148, v148, v230
	v_pk_mul_f32 v[148:149], v[148:149], v[230:231] op_sel:[0,1]
	v_pk_mul_f32 v[150:151], v[150:151], v[230:231] op_sel:[0,1]
	v_pk_fma_f32 v[148:149], v[220:221], v[148:149], v[224:225]
	v_pk_fma_f32 v[150:151], v[222:223], v[150:151], v[226:227]
	v_pk_mul_f32 v[148:149], v[148:149], s[20:21] op_sel_hi:[1,0]
	v_pk_mul_f32 v[150:151], v[150:151], s[20:21] op_sel_hi:[1,0]
	v_pk_fma_f32 v[18:19], v[18:19], v[236:237], v[148:149]
	v_pk_fma_f32 v[20:21], v[20:21], v[238:239], v[150:151]
	v_sub_f32_e32 v155, v155, v234
	v_sub_f32_e32 v154, v154, v234
	v_sub_f32_e32 v153, v153, v234
	v_sub_f32_e32 v152, v152, v234
	v_pk_mul_f32 v[152:153], v[152:153], v[234:235] op_sel:[0,1]
	v_pk_mul_f32 v[154:155], v[154:155], v[234:235] op_sel:[0,1]
	v_pk_fma_f32 v[152:153], v[220:221], v[152:153], v[224:225]
	v_pk_fma_f32 v[154:155], v[222:223], v[154:155], v[226:227]
	v_pk_mul_f32 v[152:153], v[152:153], s[20:21] op_sel_hi:[1,0]
	v_pk_mul_f32 v[154:155], v[154:155], s[20:21] op_sel_hi:[1,0]
	v_pk_fma_f32 v[14:15], v[14:15], v[236:237], v[152:153]
	v_pk_fma_f32 v[16:17], v[16:17], v[238:239], v[154:155]
	v_sub_f32_e32 v211, v211, v240
	v_sub_f32_e32 v210, v210, v240
	v_sub_f32_e32 v209, v209, v240
	v_sub_f32_e32 v208, v208, v240
	v_pk_mul_f32 v[208:209], v[208:209], v[240:241] op_sel:[0,1]
	v_pk_mul_f32 v[210:211], v[210:211], v[240:241] op_sel:[0,1]
	v_pk_fma_f32 v[208:209], v[220:221], v[208:209], v[224:225]
	v_pk_fma_f32 v[210:211], v[222:223], v[210:211], v[226:227]
	v_pk_mul_f32 v[208:209], v[208:209], s[20:21] op_sel_hi:[1,0]
	v_pk_mul_f32 v[210:211], v[210:211], s[20:21] op_sel_hi:[1,0]
	v_pk_fma_f32 v[10:11], v[10:11], v[236:237], v[208:209]
	v_pk_fma_f32 v[12:13], v[12:13], v[238:239], v[210:211]
	v_sub_f32_e32 v215, v215, v242
	v_sub_f32_e32 v214, v214, v242
	v_sub_f32_e32 v213, v213, v242
	v_sub_f32_e32 v212, v212, v242
	v_pk_mul_f32 v[212:213], v[212:213], v[242:243] op_sel:[0,1]
	v_pk_mul_f32 v[214:215], v[214:215], v[242:243] op_sel:[0,1]
	v_pk_fma_f32 v[212:213], v[220:221], v[212:213], v[224:225]
	v_pk_fma_f32 v[214:215], v[222:223], v[214:215], v[226:227]
	v_pk_mul_f32 v[212:213], v[212:213], s[20:21] op_sel_hi:[1,0]
	v_pk_mul_f32 v[214:215], v[214:215], s[20:21] op_sel_hi:[1,0]
	v_pk_fma_f32 v[6:7], v[6:7], v[236:237], v[212:213]
	v_pk_fma_f32 v[8:9], v[8:9], v[238:239], v[214:215]
	v_sub_f32_e32 v219, v219, v244
	v_sub_f32_e32 v218, v218, v244
	v_sub_f32_e32 v217, v217, v244
	v_sub_f32_e32 v216, v216, v244
	v_pk_mul_f32 v[216:217], v[216:217], v[244:245] op_sel:[0,1]
	v_pk_mul_f32 v[218:219], v[218:219], v[244:245] op_sel:[0,1]
	v_pk_fma_f32 v[216:217], v[220:221], v[216:217], v[224:225]
	v_pk_fma_f32 v[218:219], v[222:223], v[218:219], v[226:227]
	v_pk_mul_f32 v[216:217], v[216:217], s[20:21] op_sel_hi:[1,0]
	v_pk_mul_f32 v[218:219], v[218:219], s[20:21] op_sel_hi:[1,0]
	v_pk_fma_f32 v[2:3], v[2:3], v[236:237], v[216:217]
	v_pk_fma_f32 v[4:5], v[4:5], v[238:239], v[218:219]
	v_lshl_add_u64 v[130:131], v[232:233], 0, v[168:169]
	global_store_dwordx4 v[130:131], v[38:41], off offset:576
	v_lshl_add_u64 v[252:253], v[232:233], 0, v[172:173]
	global_store_dwordx4 v[252:253], v[30:33], off offset:576
	v_lshl_add_u64 v[130:131], v[232:233], 0, v[176:177]
	global_store_dwordx4 v[130:131], v[22:25], off offset:576
	v_lshl_add_u64 v[252:253], v[232:233], 0, v[180:181]
	global_store_dwordx4 v[252:253], v[18:21], off offset:576
	v_lshl_add_u64 v[130:131], v[232:233], 0, v[184:185]
	global_store_dwordx4 v[130:131], v[14:17], off offset:576
	v_lshl_add_u64 v[252:253], v[232:233], 0, v[188:189]
	global_store_dwordx4 v[252:253], v[10:13], off offset:576
	v_lshl_add_u64 v[130:131], v[232:233], 0, v[192:193]
	global_store_dwordx4 v[130:131], v[6:9], off offset:576
	v_lshl_add_u64 v[252:253], v[232:233], 0, v[196:197]
	global_store_dwordx4 v[252:253], v[2:5], off offset:576
	s_cbranch_vccz .LBB0_1964
	s_waitcnt vmcnt(0)
	s_cmpk_gt_u32 s21, 0xff
	s_cbranch_scc1 .LBB0_1973
	s_barrier

; #define PG8_STAGE(bufoff, gbase, voff) do { _Pragma("unroll") for (int _i = 0; _i < 2; ++_i) \
;         __builtin_amdgcn_global_load_lds((const unsigned*)((const char*)(gbase) + (voff)[_i]), (LAS unsigned*)(lds + (bufoff) + ldsw + _i * 8192), 16, 0, 0); } while (0)
; #define PG8_LDA(dst, b, h) do { _Pragma("unroll") for (int m = 0; m < 4; ++m) _Pragma("unroll") for (int k = 0; k < 2; ++k) dst[m][k] = *(const LAS bf16x8*)(lds + PG8_SA(b, h) + aoff + m * 2048 + k * 1024); } while (0)
; #define PG8_LDB(dst, b, h) do { _Pragma("unroll") for (int n = 0; n < 2; ++n) _Pragma("unroll") for (int k = 0; k < 2; ++k) dst[n][k] = *(const LAS bf16x8*)(lds + PG8_SB(b, h) + boff + n * 2048 + k * 1024); } while (0)
; #define PG8_MMA(ai, bj, At, Bt) do { __builtin_amdgcn_s_setprio(1); _Pragma("unroll") for (int m = 0; m < 4; ++m) _Pragma("unroll") for (int n = 0; n < 2; ++n) _Pragma("unroll") for (int k = 0; k < 2; ++k) \
;         acc[ai][bj][m][n] = __builtin_amdgcn_mfma_f32_16x16x32_bf16(Bt[n][k], At[m][k], acc[ai][bj][m][n], 0, 0, 0); __builtin_amdgcn_s_setprio(0); } while (0)
; #define PG8_WAIT_L(n) asm volatile("s_waitcnt lgkmcnt(" #n ")" ::: "memory")
; #define PG8_BAR __builtin_amdgcn_s_barrier()
; #define PG8_SCHED __builtin_amdgcn_sched_barrier(0)
; template <class Epi>
; DI void gemm_phase(LAS unsigned char* lds, const Gemm g, const StaticOrder& S, const Epi& E) {
;     ...
;             PG8_LDB(B0, 0, 0); PG8_SCHED; PG8_LDA(At, 0, 0); PG8_STAGE(PG8_SA(1, 1), a1 + hstepA, voffA);
;             PG8_WAIT_L(8); PG8_BAR; PG8_WAIT_L(0); PG8_MMA(0, 0, At, B0); PG8_BAR; PG8_SCHED;
;             PG8_LDB(B1, 0, 1); PG8_STAGE(PG8_SB(0, 0), b2, voffB);
;             PG8_BAR; PG8_WAIT_L(0); PG8_MMA(0, 1, At, B1); PG8_BAR;
;             PG8_LDA(At, 0, 1); PG8_STAGE(PG8_SA(0, 0), a2, voffA);
;             PG8_BAR; PG8_WAIT_L(0); PG8_MMA(1, 0, At, B0); PG8_BAR; PG8_SCHED;
.LBB0_2305:
	ds_read_b128 v[130:133], v171
	ds_read_b128 v[134:137], v171 offset:1024
	ds_read_b128 v[138:141], v171 offset:2048
	ds_read_b128 v[142:145], v171 offset:3072
	s_add_u32 s28, s6, 0xffefc080
	s_addc_u32 s29, s7, -1
	s_cmp_eq_u32 s69, 28
	s_cselect_b32 s31, s25, s29
	s_cselect_b32 s30, s24, s28
	s_cselect_b32 s29, s23, s68
	s_cselect_b32 s28, s66, s67
	v_lshl_add_u64 v[214:215], s[6:7], 0, v[198:199]
	s_add_i32 m0, s39, 0xc000
	ds_read_b128 v[146:149], v175
	ds_read_b128 v[150:153], v175 offset:1024
	ds_read_b128 v[154:157], v175 offset:2048
	ds_read_b128 v[206:209], v175 offset:3072
	ds_read_b128 v[210:213], v175 offset:4096
	ds_read_b128 v[218:221], v175 offset:5120
	ds_read_b128 v[222:225], v175 offset:6144
	ds_read_b128 v[226:229], v175 offset:7168
	global_load_lds_dwordx4 v[214:215], off
	v_lshl_add_u64 v[214:215], s[6:7], 0, v[200:201]
	s_add_i32 m0, s39, 0xe000
	s_nop 0
	global_load_lds_dwordx4 v[214:215], off
	ds_read_b128 v[230:233], v179
	ds_read_b128 v[234:237], v179 offset:1024
	ds_read_b128 v[238:241], v179 offset:2048
	ds_read_b128 v[242:245], v179 offset:3072
	s_waitcnt lgkmcnt(0)
	s_waitcnt vmcnt(8)
	s_barrier
	s_setprio 1
	v_mfma_f32_16x16x32_bf16 v[126:129], v[130:133], v[146:149], v[126:129]
	v_mfma_f32_16x16x32_bf16 v[102:105], v[138:141], v[146:149], v[102:105]
	v_mfma_f32_16x16x32_bf16 v[122:125], v[130:133], v[154:157], v[122:125]
	v_mfma_f32_16x16x32_bf16 v[94:97], v[138:141], v[154:157], v[94:97]
	v_mfma_f32_16x16x32_bf16 v[118:121], v[130:133], v[210:213], v[118:121]
	v_mfma_f32_16x16x32_bf16 v[86:89], v[138:141], v[210:213], v[86:89]
	v_mfma_f32_16x16x32_bf16 v[114:117], v[130:133], v[222:225], v[114:117]
	v_mfma_f32_16x16x32_bf16 v[82:85], v[138:141], v[222:225], v[82:85]
	v_mfma_f32_16x16x32_bf16 v[126:129], v[134:137], v[150:153], v[126:129]
	v_mfma_f32_16x16x32_bf16 v[102:105], v[142:145], v[150:153], v[102:105]
	v_mfma_f32_16x16x32_bf16 v[122:125], v[134:137], v[206:209], v[122:125]
	v_mfma_f32_16x16x32_bf16 v[94:97], v[142:145], v[206:209], v[94:97]
	v_mfma_f32_16x16x32_bf16 v[118:121], v[134:137], v[218:221], v[118:121]
	v_mfma_f32_16x16x32_bf16 v[86:89], v[142:145], v[218:221], v[86:89]
	v_mfma_f32_16x16x32_bf16 v[114:117], v[134:137], v[226:229], v[114:117]
	v_mfma_f32_16x16x32_bf16 v[82:85], v[142:145], v[226:229], v[82:85]
	v_mfma_f32_16x16x32_bf16 v[62:65], v[230:233], v[146:149], v[62:65]
	v_mfma_f32_16x16x32_bf16 v[38:41], v[238:241], v[146:149], v[38:41]
	v_mfma_f32_16x16x32_bf16 v[58:61], v[230:233], v[154:157], v[58:61]
	v_mfma_f32_16x16x32_bf16 v[30:33], v[238:241], v[154:157], v[30:33]
	v_mfma_f32_16x16x32_bf16 v[54:57], v[230:233], v[210:213], v[54:57]
	v_mfma_f32_16x16x32_bf16 v[22:25], v[238:241], v[210:213], v[22:25]
	v_mfma_f32_16x16x32_bf16 v[50:53], v[230:233], v[222:225], v[50:53]
	v_mfma_f32_16x16x32_bf16 v[18:21], v[238:241], v[222:225], v[18:21]
	v_mfma_f32_16x16x32_bf16 v[62:65], v[234:237], v[150:153], v[62:65]
	v_mfma_f32_16x16x32_bf16 v[38:41], v[242:245], v[150:153], v[38:41]
	v_mfma_f32_16x16x32_bf16 v[58:61], v[234:237], v[206:209], v[58:61]
	v_mfma_f32_16x16x32_bf16 v[30:33], v[242:245], v[206:209], v[30:33]
	v_mfma_f32_16x16x32_bf16 v[54:57], v[234:237], v[218:221], v[54:57]
	v_mfma_f32_16x16x32_bf16 v[22:25], v[242:245], v[218:221], v[22:25]
	v_mfma_f32_16x16x32_bf16 v[50:53], v[234:237], v[226:229], v[50:53]
	v_mfma_f32_16x16x32_bf16 v[18:21], v[242:245], v[226:229], v[18:21]
	s_setprio 0
	s_barrier
	s_add_i32 s70, s60, s38
	v_lshl_add_u64 v[214:215], s[28:29], 0, v[160:161]
	s_mov_b32 m0, s70
	s_nop 0
	global_load_lds_dwordx4 v[214:215], off
	v_lshl_add_u64 v[216:217], s[28:29], 0, v[164:165]
	s_add_i32 m0, s70, 0x2000
	s_nop 0
	global_load_lds_dwordx4 v[216:217], off
	s_mov_b32 m0, s39
	v_lshl_add_u64 v[246:247], s[30:31], 0, v[158:159]
	ds_read_b128 v[146:149], v175 offset:16384
	ds_read_b128 v[150:153], v175 offset:17408
	ds_read_b128 v[154:157], v175 offset:18432
	ds_read_b128 v[206:209], v175 offset:19456
	ds_read_b128 v[210:213], v175 offset:20480
	ds_read_b128 v[218:221], v175 offset:21504
	ds_read_b128 v[222:225], v175 offset:22528
	ds_read_b128 v[226:229], v175 offset:23552
	global_load_lds_dwordx4 v[246:247], off
	v_lshl_add_u64 v[248:249], s[30:31], 0, v[162:163]
	s_mov_b32 m0, s48
	s_nop 0
	global_load_lds_dwordx4 v[248:249], off
	s_add_u32 s70, s28, 0x80000
	s_addc_u32 s71, s29, 0
	s_add_i32 s72, s61, s38
	v_lshl_add_u64 v[252:253], s[70:71], 0, v[160:161]
	s_mov_b32 m0, s72
	s_nop 0
	global_load_lds_dwordx4 v[252:253], off
	v_lshl_add_u64 v[252:253], s[70:71], 0, v[164:165]
	s_add_i32 m0, s72, 0x2000
	s_nop 0
	global_load_lds_dwordx4 v[252:253], off
	s_waitcnt lgkmcnt(0)
	s_waitcnt vmcnt(8)
	s_barrier
; #define PG8_STAGE(bufoff, gbase, voff) do { _Pragma("unroll") for (int _i = 0; _i < 2; ++_i) \
;         __builtin_amdgcn_global_load_lds((const unsigned*)((const char*)(gbase) + (voff)[_i]), (LAS unsigned*)(lds + (bufoff) + ldsw + _i * 8192), 16, 0, 0); } while (0)
; #define PG8_LDA(dst, b, h) do { _Pragma("unroll") for (int m = 0; m < 4; ++m) _Pragma("unroll") for (int k = 0; k < 2; ++k) dst[m][k] = *(const LAS bf16x8*)(lds + PG8_SA(b, h) + aoff + m * 2048 + k * 1024); } while (0)
; #define PG8_LDB(dst, b, h) do { _Pragma("unroll") for (int n = 0; n < 2; ++n) _Pragma("unroll") for (int k = 0; k < 2; ++k) dst[n][k] = *(const LAS bf16x8*)(lds + PG8_SB(b, h) + boff + n * 2048 + k * 1024); } while (0)
; #define PG8_MMA(ai, bj, At, Bt) do { __builtin_amdgcn_s_setprio(1); _Pragma("unroll") for (int m = 0; m < 4; ++m) _Pragma("unroll") for (int n = 0; n < 2; ++n) _Pragma("unroll") for (int k = 0; k < 2; ++k) \
;         acc[ai][bj][m][n] = __builtin_amdgcn_mfma_f32_16x16x32_bf16(Bt[n][k], At[m][k], acc[ai][bj][m][n], 0, 0, 0); __builtin_amdgcn_s_setprio(0); } while (0)
; #define PG8_WAIT_V(n) asm volatile("s_waitcnt vmcnt(" #n ")" ::: "memory")
; #define PG8_WAIT_L(n) asm volatile("s_waitcnt lgkmcnt(" #n ")" ::: "memory")
; #define PG8_BAR __builtin_amdgcn_s_barrier()
; #define PG8_SCHED __builtin_amdgcn_sched_barrier(0)
; template <class Epi>
; DI void gemm_phase(LAS unsigned char* lds, const Gemm g, const StaticOrder& S, const Epi& E) {
;     ...
;             PG8_BAR; PG8_WAIT_L(0); PG8_MMA(0, 1, At, B1); PG8_BAR;
;             PG8_LDA(At, 0, 1); PG8_STAGE(PG8_SA(0, 0), a2, voffA);
;             PG8_BAR; PG8_WAIT_L(0); PG8_MMA(1, 0, At, B0); PG8_BAR; PG8_SCHED;
;             PG8_STAGE(PG8_SB(0, 1), b2 + hstepB, voffB);
;             PG8_WAIT_V(6); PG8_BAR; PG8_MMA(1, 1, At, B1); PG8_BAR;
;             PG8_LDB(B0, 1, 0); PG8_SCHED; PG8_LDA(At, 1, 0); PG8_STAGE(PG8_SA(0, 1), a2 + hstepA, voffA);
;             PG8_WAIT_L(8); PG8_BAR; PG8_WAIT_L(0); PG8_MMA(0, 0, At, B0); PG8_BAR; PG8_SCHED;
;             PG8_LDB(B1, 1, 1); PG8_STAGE(PG8_SB(1, 0), b3, voffB);
;             PG8_BAR; PG8_WAIT_L(0); PG8_MMA(0, 1, At, B1); PG8_BAR;
	s_setprio 1
	v_mfma_f32_16x16x32_bf16 v[110:113], v[130:133], v[146:149], v[110:113]
	v_mfma_f32_16x16x32_bf16 v[78:81], v[138:141], v[146:149], v[78:81]
	v_mfma_f32_16x16x32_bf16 v[106:109], v[130:133], v[154:157], v[106:109]
	v_mfma_f32_16x16x32_bf16 v[74:77], v[138:141], v[154:157], v[74:77]
	v_mfma_f32_16x16x32_bf16 v[98:101], v[130:133], v[210:213], v[98:101]
	v_mfma_f32_16x16x32_bf16 v[70:73], v[138:141], v[210:213], v[70:73]
	v_mfma_f32_16x16x32_bf16 v[90:93], v[130:133], v[222:225], v[90:93]
	v_mfma_f32_16x16x32_bf16 v[66:69], v[138:141], v[222:225], v[66:69]
	v_mfma_f32_16x16x32_bf16 v[110:113], v[134:137], v[150:153], v[110:113]
	v_mfma_f32_16x16x32_bf16 v[78:81], v[142:145], v[150:153], v[78:81]
	v_mfma_f32_16x16x32_bf16 v[106:109], v[134:137], v[206:209], v[106:109]
	v_mfma_f32_16x16x32_bf16 v[74:77], v[142:145], v[206:209], v[74:77]
	v_mfma_f32_16x16x32_bf16 v[98:101], v[134:137], v[218:221], v[98:101]
	v_mfma_f32_16x16x32_bf16 v[70:73], v[142:145], v[218:221], v[70:73]
	v_mfma_f32_16x16x32_bf16 v[90:93], v[134:137], v[226:229], v[90:93]
	v_mfma_f32_16x16x32_bf16 v[66:69], v[142:145], v[226:229], v[66:69]
	v_mfma_f32_16x16x32_bf16 v[46:49], v[230:233], v[146:149], v[46:49]
	v_mfma_f32_16x16x32_bf16 v[14:17], v[238:241], v[146:149], v[14:17]
	v_mfma_f32_16x16x32_bf16 v[42:45], v[230:233], v[154:157], v[42:45]
	v_mfma_f32_16x16x32_bf16 v[10:13], v[238:241], v[154:157], v[10:13]
	v_mfma_f32_16x16x32_bf16 v[34:37], v[230:233], v[210:213], v[34:37]
	v_mfma_f32_16x16x32_bf16 v[6:9], v[238:241], v[210:213], v[6:9]
	v_mfma_f32_16x16x32_bf16 v[26:29], v[230:233], v[222:225], v[26:29]
	v_mfma_f32_16x16x32_bf16 v[2:5], v[238:241], v[222:225], v[2:5]
	v_mfma_f32_16x16x32_bf16 v[46:49], v[234:237], v[150:153], v[46:49]
	v_mfma_f32_16x16x32_bf16 v[14:17], v[242:245], v[150:153], v[14:17]
	v_mfma_f32_16x16x32_bf16 v[42:45], v[234:237], v[206:209], v[42:45]
	v_mfma_f32_16x16x32_bf16 v[10:13], v[242:245], v[206:209], v[10:13]
	v_mfma_f32_16x16x32_bf16 v[34:37], v[234:237], v[218:221], v[34:37]
	v_mfma_f32_16x16x32_bf16 v[6:9], v[242:245], v[218:221], v[6:9]
	v_mfma_f32_16x16x32_bf16 v[26:29], v[234:237], v[226:229], v[26:29]
	v_mfma_f32_16x16x32_bf16 v[2:5], v[242:245], v[226:229], v[2:5]
	s_setprio 0
	s_add_i32 s70, 0, 0x18000
	v_add_u32_e32 v142, s70, v1
	s_barrier
	ds_read_b128 v[130:133], v142
	ds_read_b128 v[134:137], v142 offset:1024
	ds_read_b128 v[138:141], v142 offset:2048
	ds_read_b128 v[142:145], v142 offset:3072
	s_add_u32 s30, s30, 0x104000
	s_addc_u32 s31, s31, 0
	s_mov_b32 m0, s49
	v_lshl_add_u64 v[230:231], s[30:31], 0, v[158:159]
	ds_read_b128 v[146:149], v175 offset:32768
	ds_read_b128 v[150:153], v175 offset:33792
	ds_read_b128 v[154:157], v175 offset:34816
	ds_read_b128 v[206:209], v175 offset:35840
	ds_read_b128 v[210:213], v175 offset:36864
	ds_read_b128 v[218:221], v175 offset:37888
	ds_read_b128 v[222:225], v175 offset:38912
	ds_read_b128 v[226:229], v175 offset:39936
	global_load_lds_dwordx4 v[230:231], off
	v_lshl_add_u64 v[230:231], s[30:31], 0, v[162:163]
	s_mov_b32 m0, s50
	s_nop 0
	global_load_lds_dwordx4 v[230:231], off
	s_add_i32 s30, 0, 0x1c000
	v_add_u32_e32 v187, s30, v1
	ds_read_b128 v[230:233], v187
	ds_read_b128 v[234:237], v187 offset:1024
	ds_read_b128 v[238:241], v187 offset:2048
	ds_read_b128 v[242:245], v187 offset:3072
	s_waitcnt lgkmcnt(0)
	s_waitcnt vmcnt(8)
	s_barrier
	s_setprio 1
	v_mfma_f32_16x16x32_bf16 v[126:129], v[130:133], v[146:149], v[126:129]
	v_mfma_f32_16x16x32_bf16 v[102:105], v[138:141], v[146:149], v[102:105]
	v_mfma_f32_16x16x32_bf16 v[122:125], v[130:133], v[154:157], v[122:125]
	v_mfma_f32_16x16x32_bf16 v[94:97], v[138:141], v[154:157], v[94:97]
	v_mfma_f32_16x16x32_bf16 v[118:121], v[130:133], v[210:213], v[118:121]
	v_mfma_f32_16x16x32_bf16 v[86:89], v[138:141], v[210:213], v[86:89]
	v_mfma_f32_16x16x32_bf16 v[114:117], v[130:133], v[222:225], v[114:117]
	v_mfma_f32_16x16x32_bf16 v[82:85], v[138:141], v[222:225], v[82:85]
	v_mfma_f32_16x16x32_bf16 v[126:129], v[134:137], v[150:153], v[126:129]
	v_mfma_f32_16x16x32_bf16 v[102:105], v[142:145], v[150:153], v[102:105]
	v_mfma_f32_16x16x32_bf16 v[122:125], v[134:137], v[206:209], v[122:125]
	v_mfma_f32_16x16x32_bf16 v[94:97], v[142:145], v[206:209], v[94:97]
	v_mfma_f32_16x16x32_bf16 v[118:121], v[134:137], v[218:221], v[118:121]
	v_mfma_f32_16x16x32_bf16 v[86:89], v[142:145], v[218:221], v[86:89]
	v_mfma_f32_16x16x32_bf16 v[114:117], v[134:137], v[226:229], v[114:117]
	v_mfma_f32_16x16x32_bf16 v[82:85], v[142:145], v[226:229], v[82:85]
	v_mfma_f32_16x16x32_bf16 v[62:65], v[230:233], v[146:149], v[62:65]
	v_mfma_f32_16x16x32_bf16 v[38:41], v[238:241], v[146:149], v[38:41]
	v_mfma_f32_16x16x32_bf16 v[58:61], v[230:233], v[154:157], v[58:61]
	v_mfma_f32_16x16x32_bf16 v[30:33], v[238:241], v[154:157], v[30:33]
	v_mfma_f32_16x16x32_bf16 v[54:57], v[230:233], v[210:213], v[54:57]
	v_mfma_f32_16x16x32_bf16 v[22:25], v[238:241], v[210:213], v[22:25]
	v_mfma_f32_16x16x32_bf16 v[50:53], v[230:233], v[222:225], v[50:53]
	v_mfma_f32_16x16x32_bf16 v[18:21], v[238:241], v[222:225], v[18:21]
	v_mfma_f32_16x16x32_bf16 v[62:65], v[234:237], v[150:153], v[62:65]
	v_mfma_f32_16x16x32_bf16 v[38:41], v[242:245], v[150:153], v[38:41]
	v_mfma_f32_16x16x32_bf16 v[58:61], v[234:237], v[206:209], v[58:61]
	v_mfma_f32_16x16x32_bf16 v[30:33], v[242:245], v[206:209], v[30:33]
	v_mfma_f32_16x16x32_bf16 v[54:57], v[234:237], v[218:221], v[54:57]
	v_mfma_f32_16x16x32_bf16 v[22:25], v[242:245], v[218:221], v[22:25]
	v_mfma_f32_16x16x32_bf16 v[50:53], v[234:237], v[226:229], v[50:53]
	v_mfma_f32_16x16x32_bf16 v[18:21], v[242:245], v[226:229], v[18:21]
	s_setprio 0
	s_barrier
; #define PG8_STAGE(bufoff, gbase, voff) do { _Pragma("unroll") for (int _i = 0; _i < 2; ++_i) \
;         __builtin_amdgcn_global_load_lds((const unsigned*)((const char*)(gbase) + (voff)[_i]), (LAS unsigned*)(lds + (bufoff) + ldsw + _i * 8192), 16, 0, 0); } while (0)
; #define PG8_LDA(dst, b, h) do { _Pragma("unroll") for (int m = 0; m < 4; ++m) _Pragma("unroll") for (int k = 0; k < 2; ++k) dst[m][k] = *(const LAS bf16x8*)(lds + PG8_SA(b, h) + aoff + m * 2048 + k * 1024); } while (0)
; #define PG8_WAIT_V(n) asm volatile("s_waitcnt vmcnt(" #n ")" ::: "memory")
; #define PG8_WAIT_L(n) asm volatile("s_waitcnt lgkmcnt(" #n ")" ::: "memory")
; #define PG8_BAR __builtin_amdgcn_s_barrier()
; template <class Epi>
; DI void gemm_phase(LAS unsigned char* lds, const Gemm g, const StaticOrder& S, const Epi& E) {
;     ...
;             PG8_BAR; PG8_WAIT_L(0); PG8_MMA(0, 1, At, B1); PG8_BAR;
;             PG8_LDA(At, 1, 1); PG8_STAGE(PG8_SA(1, 0), a3, voffA);
;             PG8_BAR; PG8_WAIT_L(0); PG8_MMA(1, 0, At, B0); PG8_BAR; PG8_SCHED;
;             PG8_STAGE(PG8_SB(1, 1), b3 + hstepB, voffB);
;             PG8_WAIT_V(6); PG8_BAR; PG8_MMA(1, 1, At, B1); PG8_BAR;
;     DI void operator()(const f32x4 (&acc)[2][2][4][2], const pg8::Unit& u, int wr, int wc, int fr, int fq) const {
;         const int rowt = row_base + u.pm * 256, col0 = u.pn * 256 + wc * 32 + 4 * fq, rl = wr * 64 + fr;
;         const int cd = cond_of_row(rowt);
;         const float* gtp = gt0 + (size_t)cd * 6144;
;         float* dbase = rowt < TL ? out + (size_t)rowt * D : ctxv + (size_t)(rowt - TL) * D;
;         const float* sbase = mode ? (const float*)dbase : (rowt < TL ? xin + (size_t)rowt * D : cin + (size_t)(rowt - TL) * D);
; #pragma unroll
;         for (int bj = 0; bj < 2; ++bj) {
;             f32x4 gv[2], gg[2], bb[2], xv[2][8];
; #pragma unroll
;             for (int n = 0; n < 2; ++n) {
;                 const int c = col0 + bj * 128 + n * 16;
;                 gv[n] = *(const f32x4*)(gtp + c);
;                 gg[n] = (f32x4){1.f, 1.f, 1.f, 1.f}; bb[n] = (f32x4){0.f, 0.f, 0.f, 0.f};
;                 if (mode) { gg[n] = *(const f32x4*)(lg + c); bb[n] = *(const f32x4*)(lb + c); }
; #pragma unroll
;                 for (int q = 0; q < 8; ++q) { const int rr = rl + (q >> 2) * 128 + (q & 3) * 16; xv[n][q] = *(const f32x4*)(sbase + (size_t)rr * D + c); }
	s_add_i32 s31, s70, s38
	v_lshl_add_u64 v[214:215], v[214:215], 0, s[18:19]
	s_mov_b32 m0, s31
	s_nop 0
	global_load_lds_dwordx4 v[214:215], off
	v_lshl_add_u64 v[214:215], v[216:217], 0, s[18:19]
	s_add_i32 m0, s31, 0x2000
	s_nop 0
	global_load_lds_dwordx4 v[214:215], off
	s_mov_b32 m0, s57
	v_lshl_add_u64 v[214:215], v[246:247], 0, s[18:19]
	ds_read_b128 v[146:149], v175 offset:49152
	ds_read_b128 v[150:153], v175 offset:50176
	ds_read_b128 v[154:157], v175 offset:51200
	ds_read_b128 v[206:209], v175 offset:52224
	ds_read_b128 v[210:213], v175 offset:53248
	ds_read_b128 v[218:221], v175 offset:54272
	ds_read_b128 v[222:225], v175 offset:55296
	ds_read_b128 v[226:229], v175 offset:56320
	global_load_lds_dwordx4 v[214:215], off
	v_lshl_add_u64 v[214:215], v[248:249], 0, s[18:19]
	s_mov_b32 m0, s58
	s_nop 0
	global_load_lds_dwordx4 v[214:215], off
	s_add_u32 s28, s28, 0x80080
	s_addc_u32 s29, s29, 0
	s_add_i32 s30, s30, s38
	v_lshl_add_u64 v[252:253], s[28:29], 0, v[160:161]
	s_mov_b32 m0, s30
	s_nop 0
	global_load_lds_dwordx4 v[252:253], off
	v_lshl_add_u64 v[252:253], s[28:29], 0, v[164:165]
	s_add_i32 m0, s30, 0x2000
	s_nop 0
	global_load_lds_dwordx4 v[252:253], off
	s_waitcnt lgkmcnt(0)
	s_waitcnt vmcnt(8)
	s_barrier
	s_setprio 1
	v_mfma_f32_16x16x32_bf16 v[110:113], v[130:133], v[146:149], v[110:113]
	v_mfma_f32_16x16x32_bf16 v[78:81], v[138:141], v[146:149], v[78:81]
	v_mfma_f32_16x16x32_bf16 v[106:109], v[130:133], v[154:157], v[106:109]
	v_mfma_f32_16x16x32_bf16 v[74:77], v[138:141], v[154:157], v[74:77]
	v_mfma_f32_16x16x32_bf16 v[98:101], v[130:133], v[210:213], v[98:101]
	v_mfma_f32_16x16x32_bf16 v[70:73], v[138:141], v[210:213], v[70:73]
	v_mfma_f32_16x16x32_bf16 v[90:93], v[130:133], v[222:225], v[90:93]
	v_mfma_f32_16x16x32_bf16 v[66:69], v[138:141], v[222:225], v[66:69]
	v_mfma_f32_16x16x32_bf16 v[110:113], v[134:137], v[150:153], v[110:113]
	v_mfma_f32_16x16x32_bf16 v[78:81], v[142:145], v[150:153], v[78:81]
	v_mfma_f32_16x16x32_bf16 v[106:109], v[134:137], v[206:209], v[106:109]
	v_mfma_f32_16x16x32_bf16 v[74:77], v[142:145], v[206:209], v[74:77]
	v_mfma_f32_16x16x32_bf16 v[98:101], v[134:137], v[218:221], v[98:101]
	v_mfma_f32_16x16x32_bf16 v[70:73], v[142:145], v[218:221], v[70:73]
	v_mfma_f32_16x16x32_bf16 v[90:93], v[134:137], v[226:229], v[90:93]
	v_mfma_f32_16x16x32_bf16 v[66:69], v[142:145], v[226:229], v[66:69]
	v_mfma_f32_16x16x32_bf16 v[46:49], v[230:233], v[146:149], v[46:49]
	v_mfma_f32_16x16x32_bf16 v[14:17], v[238:241], v[146:149], v[14:17]
	v_mfma_f32_16x16x32_bf16 v[42:45], v[230:233], v[154:157], v[42:45]
	v_mfma_f32_16x16x32_bf16 v[10:13], v[238:241], v[154:157], v[10:13]
	v_mfma_f32_16x16x32_bf16 v[34:37], v[230:233], v[210:213], v[34:37]
	v_mfma_f32_16x16x32_bf16 v[6:9], v[238:241], v[210:213], v[6:9]
	v_mfma_f32_16x16x32_bf16 v[26:29], v[230:233], v[222:225], v[26:29]
	v_mfma_f32_16x16x32_bf16 v[2:5], v[238:241], v[222:225], v[2:5]
	v_mfma_f32_16x16x32_bf16 v[46:49], v[234:237], v[150:153], v[46:49]
	v_mfma_f32_16x16x32_bf16 v[14:17], v[242:245], v[150:153], v[14:17]
	v_mfma_f32_16x16x32_bf16 v[42:45], v[234:237], v[206:209], v[42:45]
	v_mfma_f32_16x16x32_bf16 v[10:13], v[242:245], v[206:209], v[10:13]
	v_mfma_f32_16x16x32_bf16 v[34:37], v[234:237], v[218:221], v[34:37]
	v_mfma_f32_16x16x32_bf16 v[6:9], v[242:245], v[218:221], v[6:9]
	v_mfma_f32_16x16x32_bf16 v[26:29], v[234:237], v[226:229], v[26:29]
	v_mfma_f32_16x16x32_bf16 v[2:5], v[242:245], v[226:229], v[2:5]
	s_setprio 0
	s_add_i32 s69, s69, 2
	s_add_u32 s6, s6, 0x100
	s_addc_u32 s7, s7, 0
	s_add_u32 s67, s67, 0x100
	s_addc_u32 s68, s68, 0
	s_cmp_gt_u32 s69, 29
	s_barrier
	s_cbranch_scc0 .LBB0_2305
	s_lshl_b32 s6, s64, 8
	v_sub_co_u32_e32 v130, vcc, s6, v183
	s_and_b64 s[28:29], vcc, exec
	s_cselect_b32 s7, s62, 0x3000
	s_cmp_gt_i32 s64, 63
	s_cselect_b32 s7, s7, 0
	s_lshl_b32 s7, s7, 2
	s_add_u32 s28, s55, s7
	s_addc_u32 s29, s56, 0
	s_ashr_i32 s7, s6, 31
	s_cmpk_lt_i32 s64, 0x80
	v_mov_b32_e32 v131, s7
	s_cselect_b64 vcc, -1, 0
	v_mov_b32_e32 v132, s6
	v_lshl_or_b32 v228, s65, 8, v167
	v_cndmask_b32_e32 v131, 0, v131, vcc
	v_cndmask_b32_e32 v130, v130, v132, vcc
	s_cselect_b32 s31, s9, s54
	s_cselect_b32 s30, s8, s53
	v_lshlrev_b64 v[130:131], 13, v[130:131]
	v_ashrrev_i32_e32 v229, 31, v228
	v_lshl_add_u64 v[130:131], s[30:31], 0, v[130:131]
	v_lshlrev_b64 v[132:133], 2, v[228:229]
	v_lshl_add_u64 v[246:247], s[14:15], 0, v[132:133]
	v_lshl_add_u64 v[248:249], s[16:17], 0, v[132:133]
	v_lshl_add_u64 v[250:251], s[28:29], 0, v[132:133]
	v_lshl_add_u64 v[232:233], v[130:131], 0, v[132:133]
	v_or_b32_e32 v130, 16, v228
	v_ashrrev_i32_e32 v131, 31, v130
	v_lshlrev_b64 v[130:131], 2, v[130:131]
	v_lshl_add_u64 v[132:133], s[14:15], 0, v[130:131]
	s_nop 0
	s_mov_b32 s65, s22
	s_mov_b64 s[28:29], s[26:27]
	s_mov_b64 s[30:31], s[24:25]
	s_mov_b32 s64, s63
	s_and_b64 vcc, exec, s[4:5]
	v_add_lshl_u32 v252, s6, v166, 1
	v_ashrrev_i32_e32 v253, 31, v252
	v_lshl_add_u64 v[252:253], v[252:253], 2, s[10:11]
	global_load_dwordx2 v[134:135], v[252:253], off
	v_add_lshl_u32 v252, s6, v170, 1
	v_ashrrev_i32_e32 v253, 31, v252
	v_lshl_add_u64 v[252:253], v[252:253], 2, s[10:11]
	global_load_dwordx2 v[156:157], v[252:253], off
	v_add_lshl_u32 v252, s6, v174, 1
	v_ashrrev_i32_e32 v253, 31, v252
	v_lshl_add_u64 v[252:253], v[252:253], 2, s[10:11]
	global_load_dwordx2 v[206:207], v[252:253], off
	v_add_lshl_u32 v252, s6, v178, 1
	v_ashrrev_i32_e32 v253, 31, v252
	v_lshl_add_u64 v[252:253], v[252:253], 2, s[10:11]
	global_load_dwordx2 v[230:231], v[252:253], off
	v_add_lshl_u32 v252, s6, v182, 1
	v_ashrrev_i32_e32 v253, 31, v252
	v_lshl_add_u64 v[252:253], v[252:253], 2, s[10:11]
;     DI void operator()(const f32x4 (&acc)[2][2][4][2], const pg8::Unit& u, int wr, int wc, int fr, int fq) const {
;     ...
;             for (int n = 0; n < 2; ++n) {
;                 const int c = col0 + bj * 128 + n * 16;
;                 gv[n] = *(const f32x4*)(gtp + c);
;                 gg[n] = (f32x4){1.f, 1.f, 1.f, 1.f}; bb[n] = (f32x4){0.f, 0.f, 0.f, 0.f};
;                 if (mode) { gg[n] = *(const f32x4*)(lg + c); bb[n] = *(const f32x4*)(lb + c); }
; #pragma unroll
;                 for (int q = 0; q < 8; ++q) { const int rr = rl + (q >> 2) * 128 + (q & 3) * 16; xv[n][q] = *(const f32x4*)(sbase + (size_t)rr * D + c); }
;             }
; #pragma unroll
;             for (int n = 0; n < 2; ++n) {
;                 const int c = col0 + bj * 128 + n * 16;
; #pragma unroll
;                 for (int q = 0; q < 8; ++q) {
;                     const int rr = rl + (q >> 2) * 128 + (q & 3) * 16;
;                     f32x4 x = xv[n][q];
;                     if (mode) { const float mu = stats[2 * (rowt + rr)], rs = stats[2 * (rowt + rr) + 1]; x = (x - mu) * rs * gg[n] + bb[n]; }
;                     *(f32x4*)(dbase + (size_t)rr * D + c) = ALPHA * x + gv[n] * acc[q >> 2][bj][q & 3][n];
	global_load_dwordx2 v[234:235], v[252:253], off
	v_add_lshl_u32 v252, s6, v186, 1
	v_ashrrev_i32_e32 v253, 31, v252
	v_lshl_add_u64 v[252:253], v[252:253], 2, s[10:11]
	global_load_dwordx2 v[240:241], v[252:253], off
	v_add_lshl_u32 v252, s6, v190, 1
	v_ashrrev_i32_e32 v253, 31, v252
	v_lshl_add_u64 v[252:253], v[252:253], 2, s[10:11]
	global_load_dwordx2 v[242:243], v[252:253], off
	v_add_lshl_u32 v252, s6, v194, 1
	v_ashrrev_i32_e32 v253, 31, v252
	v_lshl_add_u64 v[252:253], v[252:253], 2, s[10:11]
	global_load_dwordx2 v[244:245], v[252:253], off
	global_load_dwordx4 v[220:223], v[246:247], off
	global_load_dwordx4 v[224:227], v[248:249], off
	global_load_dwordx4 v[236:239], v[250:251], off
	v_lshl_add_u64 v[130:131], v[232:233], 0, v[168:169]
	global_load_dwordx4 v[136:139], v[130:131], off
	v_lshl_add_u64 v[252:253], v[232:233], 0, v[172:173]
	global_load_dwordx4 v[140:143], v[252:253], off
	v_lshl_add_u64 v[130:131], v[232:233], 0, v[176:177]
	global_load_dwordx4 v[144:147], v[130:131], off
	v_lshl_add_u64 v[252:253], v[232:233], 0, v[180:181]
	global_load_dwordx4 v[148:151], v[252:253], off
	v_lshl_add_u64 v[130:131], v[232:233], 0, v[184:185]
	global_load_dwordx4 v[152:155], v[130:131], off
	v_lshl_add_u64 v[252:253], v[232:233], 0, v[188:189]
	global_load_dwordx4 v[208:211], v[252:253], off
	v_lshl_add_u64 v[130:131], v[232:233], 0, v[192:193]
	global_load_dwordx4 v[212:215], v[130:131], off
	v_lshl_add_u64 v[252:253], v[232:233], 0, v[196:197]
	global_load_dwordx4 v[216:219], v[252:253], off
	s_waitcnt vmcnt(0)
	v_sub_f32_e32 v139, v139, v134
	v_sub_f32_e32 v138, v138, v134
	v_sub_f32_e32 v137, v137, v134
	v_sub_f32_e32 v136, v136, v134
	v_pk_mul_f32 v[136:137], v[136:137], v[134:135] op_sel:[0,1]
	v_pk_mul_f32 v[138:139], v[138:139], v[134:135] op_sel:[0,1]
	v_pk_fma_f32 v[136:137], v[220:221], v[136:137], v[224:225]
	v_pk_fma_f32 v[138:139], v[222:223], v[138:139], v[226:227]
	v_pk_mul_f32 v[136:137], v[136:137], s[20:21] op_sel_hi:[1,0]
	v_pk_mul_f32 v[138:139], v[138:139], s[20:21] op_sel_hi:[1,0]
	v_pk_fma_f32 v[126:127], v[126:127], v[236:237], v[136:137]
	v_pk_fma_f32 v[128:129], v[128:129], v[238:239], v[138:139]
	v_sub_f32_e32 v143, v143, v156
	v_sub_f32_e32 v142, v142, v156
	v_sub_f32_e32 v141, v141, v156
	v_sub_f32_e32 v140, v140, v156
	v_pk_mul_f32 v[140:141], v[140:141], v[156:157] op_sel:[0,1]
	v_pk_mul_f32 v[142:143], v[142:143], v[156:157] op_sel:[0,1]
	v_pk_fma_f32 v[140:141], v[220:221], v[140:141], v[224:225]
	v_pk_fma_f32 v[142:143], v[222:223], v[142:143], v[226:227]
	v_pk_mul_f32 v[140:141], v[140:141], s[20:21] op_sel_hi:[1,0]
	v_pk_mul_f32 v[142:143], v[142:143], s[20:21] op_sel_hi:[1,0]
	v_pk_fma_f32 v[122:123], v[122:123], v[236:237], v[140:141]
	v_pk_fma_f32 v[124:125], v[124:125], v[238:239], v[142:143]
	v_sub_f32_e32 v147, v147, v206
	v_sub_f32_e32 v146, v146, v206
	v_sub_f32_e32 v145, v145, v206
	v_sub_f32_e32 v144, v144, v206
	v_pk_mul_f32 v[144:145], v[144:145], v[206:207] op_sel:[0,1]
	v_pk_mul_f32 v[146:147], v[146:147], v[206:207] op_sel:[0,1]
	v_pk_fma_f32 v[144:145], v[220:221], v[144:145], v[224:225]
	v_pk_fma_f32 v[146:147], v[222:223], v[146:147], v[226:227]
	v_pk_mul_f32 v[144:145], v[144:145], s[20:21] op_sel_hi:[1,0]
	v_pk_mul_f32 v[146:147], v[146:147], s[20:21] op_sel_hi:[1,0]
	v_pk_fma_f32 v[118:119], v[118:119], v[236:237], v[144:145]
	v_pk_fma_f32 v[120:121], v[120:121], v[238:239], v[146:147]
	v_sub_f32_e32 v151, v151, v230
	v_sub_f32_e32 v150, v150, v230
	v_sub_f32_e32 v149, v149, v230
	v_sub_f32_e32 v148, v148, v230
	v_pk_mul_f32 v[148:149], v[148:149], v[230:231] op_sel:[0,1]
	v_pk_mul_f32 v[150:151], v[150:151], v[230:231] op_sel:[0,1]
	v_pk_fma_f32 v[148:149], v[220:221], v[148:149], v[224:225]
	v_pk_fma_f32 v[150:151], v[222:223], v[150:151], v[226:227]
	v_pk_mul_f32 v[148:149], v[148:149], s[20:21] op_sel_hi:[1,0]
	v_pk_mul_f32 v[150:151], v[150:151], s[20:21] op_sel_hi:[1,0]
	v_pk_fma_f32 v[114:115], v[114:115], v[236:237], v[148:149]
	v_pk_fma_f32 v[116:117], v[116:117], v[238:239], v[150:151]
	v_sub_f32_e32 v155, v155, v234
	v_sub_f32_e32 v154, v154, v234
	v_sub_f32_e32 v153, v153, v234
	v_sub_f32_e32 v152, v152, v234
	v_pk_mul_f32 v[152:153], v[152:153], v[234:235] op_sel:[0,1]
	v_pk_mul_f32 v[154:155], v[154:155], v[234:235] op_sel:[0,1]
	v_pk_fma_f32 v[152:153], v[220:221], v[152:153], v[224:225]
	v_pk_fma_f32 v[154:155], v[222:223], v[154:155], v[226:227]
	v_pk_mul_f32 v[152:153], v[152:153], s[20:21] op_sel_hi:[1,0]
	v_pk_mul_f32 v[154:155], v[154:155], s[20:21] op_sel_hi:[1,0]
	v_pk_fma_f32 v[110:111], v[110:111], v[236:237], v[152:153]
	v_pk_fma_f32 v[112:113], v[112:113], v[238:239], v[154:155]
	v_sub_f32_e32 v211, v211, v240
	v_sub_f32_e32 v210, v210, v240
	v_sub_f32_e32 v209, v209, v240
	v_sub_f32_e32 v208, v208, v240
	v_pk_mul_f32 v[208:209], v[208:209], v[240:241] op_sel:[0,1]
	v_pk_mul_f32 v[210:211], v[210:211], v[240:241] op_sel:[0,1]
	v_pk_fma_f32 v[208:209], v[220:221], v[208:209], v[224:225]
	v_pk_fma_f32 v[210:211], v[222:223], v[210:211], v[226:227]
	v_pk_mul_f32 v[208:209], v[208:209], s[20:21] op_sel_hi:[1,0]
	v_pk_mul_f32 v[210:211], v[210:211], s[20:21] op_sel_hi:[1,0]
	v_pk_fma_f32 v[106:107], v[106:107], v[236:237], v[208:209]
	v_pk_fma_f32 v[108:109], v[108:109], v[238:239], v[210:211]
	v_sub_f32_e32 v215, v215, v242
	v_sub_f32_e32 v214, v214, v242
	v_sub_f32_e32 v213, v213, v242
	v_sub_f32_e32 v212, v212, v242
	v_pk_mul_f32 v[212:213], v[212:213], v[242:243] op_sel:[0,1]
	v_pk_mul_f32 v[214:215], v[214:215], v[242:243] op_sel:[0,1]
	v_pk_fma_f32 v[212:213], v[220:221], v[212:213], v[224:225]
	v_pk_fma_f32 v[214:215], v[222:223], v[214:215], v[226:227]
;     DI void operator()(const f32x4 (&acc)[2][2][4][2], const pg8::Unit& u, int wr, int wc, int fr, int fq) const {
;     ...
;         for (int bj = 0; bj < 2; ++bj) {
;             f32x4 gv[2], gg[2], bb[2], xv[2][8];
; #pragma unroll
;             for (int n = 0; n < 2; ++n) {
;                 const int c = col0 + bj * 128 + n * 16;
;                 gv[n] = *(const f32x4*)(gtp + c);
;                 gg[n] = (f32x4){1.f, 1.f, 1.f, 1.f}; bb[n] = (f32x4){0.f, 0.f, 0.f, 0.f};
;                 if (mode) { gg[n] = *(const f32x4*)(lg + c); bb[n] = *(const f32x4*)(lb + c); }
; #pragma unroll
;                 for (int q = 0; q < 8; ++q) { const int rr = rl + (q >> 2) * 128 + (q & 3) * 16; xv[n][q] = *(const f32x4*)(sbase + (size_t)rr * D + c); }
;             }
; #pragma unroll
;             for (int n = 0; n < 2; ++n) {
;                 const int c = col0 + bj * 128 + n * 16;
; #pragma unroll
;                 for (int q = 0; q < 8; ++q) {
;                     const int rr = rl + (q >> 2) * 128 + (q & 3) * 16;
;                     f32x4 x = xv[n][q];
;                     if (mode) { const float mu = stats[2 * (rowt + rr)], rs = stats[2 * (rowt + rr) + 1]; x = (x - mu) * rs * gg[n] + bb[n]; }
;                     *(f32x4*)(dbase + (size_t)rr * D + c) = ALPHA * x + gv[n] * acc[q >> 2][bj][q & 3][n];
;                 }
;             }
	v_pk_mul_f32 v[212:213], v[212:213], s[20:21] op_sel_hi:[1,0]
	v_pk_mul_f32 v[214:215], v[214:215], s[20:21] op_sel_hi:[1,0]
	v_pk_fma_f32 v[98:99], v[98:99], v[236:237], v[212:213]
	v_pk_fma_f32 v[100:101], v[100:101], v[238:239], v[214:215]
	v_sub_f32_e32 v219, v219, v244
	v_sub_f32_e32 v218, v218, v244
	v_sub_f32_e32 v217, v217, v244
	v_sub_f32_e32 v216, v216, v244
	v_pk_mul_f32 v[216:217], v[216:217], v[244:245] op_sel:[0,1]
	v_pk_mul_f32 v[218:219], v[218:219], v[244:245] op_sel:[0,1]
	v_pk_fma_f32 v[216:217], v[220:221], v[216:217], v[224:225]
	v_pk_fma_f32 v[218:219], v[222:223], v[218:219], v[226:227]
	v_pk_mul_f32 v[216:217], v[216:217], s[20:21] op_sel_hi:[1,0]
	v_pk_mul_f32 v[218:219], v[218:219], s[20:21] op_sel_hi:[1,0]
	v_pk_fma_f32 v[90:91], v[90:91], v[236:237], v[216:217]
	v_pk_fma_f32 v[92:93], v[92:93], v[238:239], v[218:219]
	global_load_dwordx4 v[220:223], v[246:247], off offset:64
	global_load_dwordx4 v[224:227], v[248:249], off offset:64
	global_load_dwordx4 v[236:239], v[250:251], off offset:64
	v_lshl_add_u64 v[130:131], v[232:233], 0, v[168:169]
	global_load_dwordx4 v[136:139], v[130:131], off offset:64
	v_lshl_add_u64 v[252:253], v[232:233], 0, v[172:173]
	global_load_dwordx4 v[140:143], v[252:253], off offset:64
	v_lshl_add_u64 v[130:131], v[232:233], 0, v[176:177]
	global_load_dwordx4 v[144:147], v[130:131], off offset:64
	v_lshl_add_u64 v[252:253], v[232:233], 0, v[180:181]
	global_load_dwordx4 v[148:151], v[252:253], off offset:64
	v_lshl_add_u64 v[130:131], v[232:233], 0, v[184:185]
	global_load_dwordx4 v[152:155], v[130:131], off offset:64
	v_lshl_add_u64 v[252:253], v[232:233], 0, v[188:189]
	global_load_dwordx4 v[208:211], v[252:253], off offset:64
	v_lshl_add_u64 v[130:131], v[232:233], 0, v[192:193]
	global_load_dwordx4 v[212:215], v[130:131], off offset:64
	v_lshl_add_u64 v[252:253], v[232:233], 0, v[196:197]
	global_load_dwordx4 v[216:219], v[252:253], off offset:64
	v_lshl_add_u64 v[130:131], v[232:233], 0, v[168:169]
	global_store_dwordx4 v[130:131], v[126:129], off
	v_lshl_add_u64 v[252:253], v[232:233], 0, v[172:173]
	global_store_dwordx4 v[252:253], v[122:125], off
	v_lshl_add_u64 v[130:131], v[232:233], 0, v[176:177]
	global_store_dwordx4 v[130:131], v[118:121], off
	v_lshl_add_u64 v[252:253], v[232:233], 0, v[180:181]
	global_store_dwordx4 v[252:253], v[114:117], off
	v_lshl_add_u64 v[130:131], v[232:233], 0, v[184:185]
	global_store_dwordx4 v[130:131], v[110:113], off
	v_lshl_add_u64 v[252:253], v[232:233], 0, v[188:189]
	global_store_dwordx4 v[252:253], v[106:109], off
	v_lshl_add_u64 v[130:131], v[232:233], 0, v[192:193]
	global_store_dwordx4 v[130:131], v[98:101], off
	v_lshl_add_u64 v[252:253], v[232:233], 0, v[196:197]
	global_store_dwordx4 v[252:253], v[90:93], off
	s_waitcnt vmcnt(8)
	v_sub_f32_e32 v139, v139, v134
	v_sub_f32_e32 v138, v138, v134
	v_sub_f32_e32 v137, v137, v134
	v_sub_f32_e32 v136, v136, v134
	v_pk_mul_f32 v[136:137], v[136:137], v[134:135] op_sel:[0,1]
	v_pk_mul_f32 v[138:139], v[138:139], v[134:135] op_sel:[0,1]
	v_pk_fma_f32 v[136:137], v[220:221], v[136:137], v[224:225]
	v_pk_fma_f32 v[138:139], v[222:223], v[138:139], v[226:227]
	v_pk_mul_f32 v[136:137], v[136:137], s[20:21] op_sel_hi:[1,0]
	v_pk_mul_f32 v[138:139], v[138:139], s[20:21] op_sel_hi:[1,0]
	v_pk_fma_f32 v[102:103], v[102:103], v[236:237], v[136:137]
	v_pk_fma_f32 v[104:105], v[104:105], v[238:239], v[138:139]
	v_sub_f32_e32 v143, v143, v156
	v_sub_f32_e32 v142, v142, v156
	v_sub_f32_e32 v141, v141, v156
	v_sub_f32_e32 v140, v140, v156
	v_pk_mul_f32 v[140:141], v[140:141], v[156:157] op_sel:[0,1]
	v_pk_mul_f32 v[142:143], v[142:143], v[156:157] op_sel:[0,1]
	v_pk_fma_f32 v[140:141], v[220:221], v[140:141], v[224:225]
	v_pk_fma_f32 v[142:143], v[222:223], v[142:143], v[226:227]
	v_pk_mul_f32 v[140:141], v[140:141], s[20:21] op_sel_hi:[1,0]
	v_pk_mul_f32 v[142:143], v[142:143], s[20:21] op_sel_hi:[1,0]
	v_pk_fma_f32 v[94:95], v[94:95], v[236:237], v[140:141]
	v_pk_fma_f32 v[96:97], v[96:97], v[238:239], v[142:143]
	v_sub_f32_e32 v147, v147, v206
	v_sub_f32_e32 v146, v146, v206
	v_sub_f32_e32 v145, v145, v206
	v_sub_f32_e32 v144, v144, v206
	v_pk_mul_f32 v[144:145], v[144:145], v[206:207] op_sel:[0,1]
	v_pk_mul_f32 v[146:147], v[146:147], v[206:207] op_sel:[0,1]
	v_pk_fma_f32 v[144:145], v[220:221], v[144:145], v[224:225]
	v_pk_fma_f32 v[146:147], v[222:223], v[146:147], v[226:227]
	v_pk_mul_f32 v[144:145], v[144:145], s[20:21] op_sel_hi:[1,0]
	v_pk_mul_f32 v[146:147], v[146:147], s[20:21] op_sel_hi:[1,0]
	v_pk_fma_f32 v[86:87], v[86:87], v[236:237], v[144:145]
	v_pk_fma_f32 v[88:89], v[88:89], v[238:239], v[146:147]
	v_sub_f32_e32 v151, v151, v230
	v_sub_f32_e32 v150, v150, v230
	v_sub_f32_e32 v149, v149, v230
	v_sub_f32_e32 v148, v148, v230
	v_pk_mul_f32 v[148:149], v[148:149], v[230:231] op_sel:[0,1]
	v_pk_mul_f32 v[150:151], v[150:151], v[230:231] op_sel:[0,1]
	v_pk_fma_f32 v[148:149], v[220:221], v[148:149], v[224:225]
	v_pk_fma_f32 v[150:151], v[222:223], v[150:151], v[226:227]
	v_pk_mul_f32 v[148:149], v[148:149], s[20:21] op_sel_hi:[1,0]
	v_pk_mul_f32 v[150:151], v[150:151], s[20:21] op_sel_hi:[1,0]
	v_pk_fma_f32 v[82:83], v[82:83], v[236:237], v[148:149]
	v_pk_fma_f32 v[84:85], v[84:85], v[238:239], v[150:151]
	v_sub_f32_e32 v155, v155, v234
	v_sub_f32_e32 v154, v154, v234
	v_sub_f32_e32 v153, v153, v234
	v_sub_f32_e32 v152, v152, v234
	v_pk_mul_f32 v[152:153], v[152:153], v[234:235] op_sel:[0,1]
	v_pk_mul_f32 v[154:155], v[154:155], v[234:235] op_sel:[0,1]
	v_pk_fma_f32 v[152:153], v[220:221], v[152:153], v[224:225]
	v_pk_fma_f32 v[154:155], v[222:223], v[154:155], v[226:227]
;     DI void operator()(const f32x4 (&acc)[2][2][4][2], const pg8::Unit& u, int wr, int wc, int fr, int fq) const {
;     ...
;         for (int bj = 0; bj < 2; ++bj) {
;             f32x4 gv[2], gg[2], bb[2], xv[2][8];
; #pragma unroll
;             for (int n = 0; n < 2; ++n) {
;                 const int c = col0 + bj * 128 + n * 16;
;                 gv[n] = *(const f32x4*)(gtp + c);
;                 gg[n] = (f32x4){1.f, 1.f, 1.f, 1.f}; bb[n] = (f32x4){0.f, 0.f, 0.f, 0.f};
;                 if (mode) { gg[n] = *(const f32x4*)(lg + c); bb[n] = *(const f32x4*)(lb + c); }
; #pragma unroll
;                 for (int q = 0; q < 8; ++q) { const int rr = rl + (q >> 2) * 128 + (q & 3) * 16; xv[n][q] = *(const f32x4*)(sbase + (size_t)rr * D + c); }
;             }
; #pragma unroll
;             for (int n = 0; n < 2; ++n) {
;                 const int c = col0 + bj * 128 + n * 16;
; #pragma unroll
;                 for (int q = 0; q < 8; ++q) {
;                     const int rr = rl + (q >> 2) * 128 + (q & 3) * 16;
;                     f32x4 x = xv[n][q];
;                     if (mode) { const float mu = stats[2 * (rowt + rr)], rs = stats[2 * (rowt + rr) + 1]; x = (x - mu) * rs * gg[n] + bb[n]; }
;                     *(f32x4*)(dbase + (size_t)rr * D + c) = ALPHA * x + gv[n] * acc[q >> 2][bj][q & 3][n];
;                 }
;             }
	v_pk_mul_f32 v[152:153], v[152:153], s[20:21] op_sel_hi:[1,0]
	v_pk_mul_f32 v[154:155], v[154:155], s[20:21] op_sel_hi:[1,0]
	v_pk_fma_f32 v[78:79], v[78:79], v[236:237], v[152:153]
	v_pk_fma_f32 v[80:81], v[80:81], v[238:239], v[154:155]
	v_sub_f32_e32 v211, v211, v240
	v_sub_f32_e32 v210, v210, v240
	v_sub_f32_e32 v209, v209, v240
	v_sub_f32_e32 v208, v208, v240
	v_pk_mul_f32 v[208:209], v[208:209], v[240:241] op_sel:[0,1]
	v_pk_mul_f32 v[210:211], v[210:211], v[240:241] op_sel:[0,1]
	v_pk_fma_f32 v[208:209], v[220:221], v[208:209], v[224:225]
	v_pk_fma_f32 v[210:211], v[222:223], v[210:211], v[226:227]
	v_pk_mul_f32 v[208:209], v[208:209], s[20:21] op_sel_hi:[1,0]
	v_pk_mul_f32 v[210:211], v[210:211], s[20:21] op_sel_hi:[1,0]
	v_pk_fma_f32 v[74:75], v[74:75], v[236:237], v[208:209]
	v_pk_fma_f32 v[76:77], v[76:77], v[238:239], v[210:211]
	v_sub_f32_e32 v215, v215, v242
	v_sub_f32_e32 v214, v214, v242
	v_sub_f32_e32 v213, v213, v242
	v_sub_f32_e32 v212, v212, v242
	v_pk_mul_f32 v[212:213], v[212:213], v[242:243] op_sel:[0,1]
	v_pk_mul_f32 v[214:215], v[214:215], v[242:243] op_sel:[0,1]
	v_pk_fma_f32 v[212:213], v[220:221], v[212:213], v[224:225]
	v_pk_fma_f32 v[214:215], v[222:223], v[214:215], v[226:227]
	v_pk_mul_f32 v[212:213], v[212:213], s[20:21] op_sel_hi:[1,0]
	v_pk_mul_f32 v[214:215], v[214:215], s[20:21] op_sel_hi:[1,0]
	v_pk_fma_f32 v[70:71], v[70:71], v[236:237], v[212:213]
	v_pk_fma_f32 v[72:73], v[72:73], v[238:239], v[214:215]
	v_sub_f32_e32 v219, v219, v244
	v_sub_f32_e32 v218, v218, v244
	v_sub_f32_e32 v217, v217, v244
	v_sub_f32_e32 v216, v216, v244
	v_pk_mul_f32 v[216:217], v[216:217], v[244:245] op_sel:[0,1]
	v_pk_mul_f32 v[218:219], v[218:219], v[244:245] op_sel:[0,1]
	v_pk_fma_f32 v[216:217], v[220:221], v[216:217], v[224:225]
	v_pk_fma_f32 v[218:219], v[222:223], v[218:219], v[226:227]
	v_pk_mul_f32 v[216:217], v[216:217], s[20:21] op_sel_hi:[1,0]
	v_pk_mul_f32 v[218:219], v[218:219], s[20:21] op_sel_hi:[1,0]
	v_pk_fma_f32 v[66:67], v[66:67], v[236:237], v[216:217]
	v_pk_fma_f32 v[68:69], v[68:69], v[238:239], v[218:219]
	global_load_dwordx4 v[220:223], v[246:247], off offset:512
	global_load_dwordx4 v[224:227], v[248:249], off offset:512
	global_load_dwordx4 v[236:239], v[250:251], off offset:512
	v_lshl_add_u64 v[130:131], v[232:233], 0, v[168:169]
	global_load_dwordx4 v[136:139], v[130:131], off offset:512
	v_lshl_add_u64 v[252:253], v[232:233], 0, v[172:173]
	global_load_dwordx4 v[140:143], v[252:253], off offset:512
	v_lshl_add_u64 v[130:131], v[232:233], 0, v[176:177]
	global_load_dwordx4 v[144:147], v[130:131], off offset:512
	v_lshl_add_u64 v[252:253], v[232:233], 0, v[180:181]
	global_load_dwordx4 v[148:151], v[252:253], off offset:512
	v_lshl_add_u64 v[130:131], v[232:233], 0, v[184:185]
	global_load_dwordx4 v[152:155], v[130:131], off offset:512
	v_lshl_add_u64 v[252:253], v[232:233], 0, v[188:189]
	global_load_dwordx4 v[208:211], v[252:253], off offset:512
	v_lshl_add_u64 v[130:131], v[232:233], 0, v[192:193]
	global_load_dwordx4 v[212:215], v[130:131], off offset:512
	v_lshl_add_u64 v[252:253], v[232:233], 0, v[196:197]
	global_load_dwordx4 v[216:219], v[252:253], off offset:512
	v_lshl_add_u64 v[130:131], v[232:233], 0, v[168:169]
	global_store_dwordx4 v[130:131], v[102:105], off offset:64
	v_lshl_add_u64 v[252:253], v[232:233], 0, v[172:173]
	global_store_dwordx4 v[252:253], v[94:97], off offset:64
	v_lshl_add_u64 v[130:131], v[232:233], 0, v[176:177]
	global_store_dwordx4 v[130:131], v[86:89], off offset:64
	v_lshl_add_u64 v[252:253], v[232:233], 0, v[180:181]
	global_store_dwordx4 v[252:253], v[82:85], off offset:64
	v_lshl_add_u64 v[130:131], v[232:233], 0, v[184:185]
	global_store_dwordx4 v[130:131], v[78:81], off offset:64
	v_lshl_add_u64 v[252:253], v[232:233], 0, v[188:189]
	global_store_dwordx4 v[252:253], v[74:77], off offset:64
	v_lshl_add_u64 v[130:131], v[232:233], 0, v[192:193]
	global_store_dwordx4 v[130:131], v[70:73], off offset:64
	v_lshl_add_u64 v[252:253], v[232:233], 0, v[196:197]
	global_store_dwordx4 v[252:253], v[66:69], off offset:64
	s_waitcnt vmcnt(8)
	v_sub_f32_e32 v139, v139, v134
	v_sub_f32_e32 v138, v138, v134
	v_sub_f32_e32 v137, v137, v134
	v_sub_f32_e32 v136, v136, v134
	v_pk_mul_f32 v[136:137], v[136:137], v[134:135] op_sel:[0,1]
	v_pk_mul_f32 v[138:139], v[138:139], v[134:135] op_sel:[0,1]
	v_pk_fma_f32 v[136:137], v[220:221], v[136:137], v[224:225]
	v_pk_fma_f32 v[138:139], v[222:223], v[138:139], v[226:227]
	v_pk_mul_f32 v[136:137], v[136:137], s[20:21] op_sel_hi:[1,0]
	v_pk_mul_f32 v[138:139], v[138:139], s[20:21] op_sel_hi:[1,0]
	v_pk_fma_f32 v[62:63], v[62:63], v[236:237], v[136:137]
	v_pk_fma_f32 v[64:65], v[64:65], v[238:239], v[138:139]
	v_sub_f32_e32 v143, v143, v156
	v_sub_f32_e32 v142, v142, v156
	v_sub_f32_e32 v141, v141, v156
	v_sub_f32_e32 v140, v140, v156
	v_pk_mul_f32 v[140:141], v[140:141], v[156:157] op_sel:[0,1]
	v_pk_mul_f32 v[142:143], v[142:143], v[156:157] op_sel:[0,1]
	v_pk_fma_f32 v[140:141], v[220:221], v[140:141], v[224:225]
	v_pk_fma_f32 v[142:143], v[222:223], v[142:143], v[226:227]
	v_pk_mul_f32 v[140:141], v[140:141], s[20:21] op_sel_hi:[1,0]
	v_pk_mul_f32 v[142:143], v[142:143], s[20:21] op_sel_hi:[1,0]
	v_pk_fma_f32 v[58:59], v[58:59], v[236:237], v[140:141]
	v_pk_fma_f32 v[60:61], v[60:61], v[238:239], v[142:143]
	v_sub_f32_e32 v147, v147, v206
	v_sub_f32_e32 v146, v146, v206
	v_sub_f32_e32 v145, v145, v206
	v_sub_f32_e32 v144, v144, v206
	v_pk_mul_f32 v[144:145], v[144:145], v[206:207] op_sel:[0,1]
	v_pk_mul_f32 v[146:147], v[146:147], v[206:207] op_sel:[0,1]
	v_pk_fma_f32 v[144:145], v[220:221], v[144:145], v[224:225]
;     DI void operator()(const f32x4 (&acc)[2][2][4][2], const pg8::Unit& u, int wr, int wc, int fr, int fq) const {
;     ...
;         for (int bj = 0; bj < 2; ++bj) {
;             f32x4 gv[2], gg[2], bb[2], xv[2][8];
; #pragma unroll
;             for (int n = 0; n < 2; ++n) {
;                 const int c = col0 + bj * 128 + n * 16;
;                 gv[n] = *(const f32x4*)(gtp + c);
;                 gg[n] = (f32x4){1.f, 1.f, 1.f, 1.f}; bb[n] = (f32x4){0.f, 0.f, 0.f, 0.f};
;                 if (mode) { gg[n] = *(const f32x4*)(lg + c); bb[n] = *(const f32x4*)(lb + c); }
; #pragma unroll
;                 for (int q = 0; q < 8; ++q) { const int rr = rl + (q >> 2) * 128 + (q & 3) * 16; xv[n][q] = *(const f32x4*)(sbase + (size_t)rr * D + c); }
;             }
; #pragma unroll
;             for (int n = 0; n < 2; ++n) {
;                 const int c = col0 + bj * 128 + n * 16;
; #pragma unroll
;                 for (int q = 0; q < 8; ++q) {
;                     const int rr = rl + (q >> 2) * 128 + (q & 3) * 16;
;                     f32x4 x = xv[n][q];
;                     if (mode) { const float mu = stats[2 * (rowt + rr)], rs = stats[2 * (rowt + rr) + 1]; x = (x - mu) * rs * gg[n] + bb[n]; }
;                     *(f32x4*)(dbase + (size_t)rr * D + c) = ALPHA * x + gv[n] * acc[q >> 2][bj][q & 3][n];
;                 }
;             }
	v_pk_fma_f32 v[146:147], v[222:223], v[146:147], v[226:227]
	v_pk_mul_f32 v[144:145], v[144:145], s[20:21] op_sel_hi:[1,0]
	v_pk_mul_f32 v[146:147], v[146:147], s[20:21] op_sel_hi:[1,0]
	v_pk_fma_f32 v[54:55], v[54:55], v[236:237], v[144:145]
	v_pk_fma_f32 v[56:57], v[56:57], v[238:239], v[146:147]
	v_sub_f32_e32 v151, v151, v230
	v_sub_f32_e32 v150, v150, v230
	v_sub_f32_e32 v149, v149, v230
	v_sub_f32_e32 v148, v148, v230
	v_pk_mul_f32 v[148:149], v[148:149], v[230:231] op_sel:[0,1]
	v_pk_mul_f32 v[150:151], v[150:151], v[230:231] op_sel:[0,1]
	v_pk_fma_f32 v[148:149], v[220:221], v[148:149], v[224:225]
	v_pk_fma_f32 v[150:151], v[222:223], v[150:151], v[226:227]
	v_pk_mul_f32 v[148:149], v[148:149], s[20:21] op_sel_hi:[1,0]
	v_pk_mul_f32 v[150:151], v[150:151], s[20:21] op_sel_hi:[1,0]
	v_pk_fma_f32 v[50:51], v[50:51], v[236:237], v[148:149]
	v_pk_fma_f32 v[52:53], v[52:53], v[238:239], v[150:151]
	v_sub_f32_e32 v155, v155, v234
	v_sub_f32_e32 v154, v154, v234
	v_sub_f32_e32 v153, v153, v234
	v_sub_f32_e32 v152, v152, v234
	v_pk_mul_f32 v[152:153], v[152:153], v[234:235] op_sel:[0,1]
	v_pk_mul_f32 v[154:155], v[154:155], v[234:235] op_sel:[0,1]
	v_pk_fma_f32 v[152:153], v[220:221], v[152:153], v[224:225]
	v_pk_fma_f32 v[154:155], v[222:223], v[154:155], v[226:227]
	v_pk_mul_f32 v[152:153], v[152:153], s[20:21] op_sel_hi:[1,0]
	v_pk_mul_f32 v[154:155], v[154:155], s[20:21] op_sel_hi:[1,0]
	v_pk_fma_f32 v[46:47], v[46:47], v[236:237], v[152:153]
	v_pk_fma_f32 v[48:49], v[48:49], v[238:239], v[154:155]
	v_sub_f32_e32 v211, v211, v240
	v_sub_f32_e32 v210, v210, v240
	v_sub_f32_e32 v209, v209, v240
	v_sub_f32_e32 v208, v208, v240
	v_pk_mul_f32 v[208:209], v[208:209], v[240:241] op_sel:[0,1]
	v_pk_mul_f32 v[210:211], v[210:211], v[240:241] op_sel:[0,1]
	v_pk_fma_f32 v[208:209], v[220:221], v[208:209], v[224:225]
	v_pk_fma_f32 v[210:211], v[222:223], v[210:211], v[226:227]
	v_pk_mul_f32 v[208:209], v[208:209], s[20:21] op_sel_hi:[1,0]
	v_pk_mul_f32 v[210:211], v[210:211], s[20:21] op_sel_hi:[1,0]
	v_pk_fma_f32 v[42:43], v[42:43], v[236:237], v[208:209]
	v_pk_fma_f32 v[44:45], v[44:45], v[238:239], v[210:211]
	v_sub_f32_e32 v215, v215, v242
	v_sub_f32_e32 v214, v214, v242
	v_sub_f32_e32 v213, v213, v242
	v_sub_f32_e32 v212, v212, v242
	v_pk_mul_f32 v[212:213], v[212:213], v[242:243] op_sel:[0,1]
	v_pk_mul_f32 v[214:215], v[214:215], v[242:243] op_sel:[0,1]
	v_pk_fma_f32 v[212:213], v[220:221], v[212:213], v[224:225]
	v_pk_fma_f32 v[214:215], v[222:223], v[214:215], v[226:227]
	v_pk_mul_f32 v[212:213], v[212:213], s[20:21] op_sel_hi:[1,0]
	v_pk_mul_f32 v[214:215], v[214:215], s[20:21] op_sel_hi:[1,0]
	v_pk_fma_f32 v[34:35], v[34:35], v[236:237], v[212:213]
	v_pk_fma_f32 v[36:37], v[36:37], v[238:239], v[214:215]
	v_sub_f32_e32 v219, v219, v244
	v_sub_f32_e32 v218, v218, v244
	v_sub_f32_e32 v217, v217, v244
	v_sub_f32_e32 v216, v216, v244
	v_pk_mul_f32 v[216:217], v[216:217], v[244:245] op_sel:[0,1]
	v_pk_mul_f32 v[218:219], v[218:219], v[244:245] op_sel:[0,1]
	v_pk_fma_f32 v[216:217], v[220:221], v[216:217], v[224:225]
	v_pk_fma_f32 v[218:219], v[222:223], v[218:219], v[226:227]
	v_pk_mul_f32 v[216:217], v[216:217], s[20:21] op_sel_hi:[1,0]
	v_pk_mul_f32 v[218:219], v[218:219], s[20:21] op_sel_hi:[1,0]
	v_pk_fma_f32 v[26:27], v[26:27], v[236:237], v[216:217]
	v_pk_fma_f32 v[28:29], v[28:29], v[238:239], v[218:219]
	global_load_dwordx4 v[220:223], v[246:247], off offset:576
	global_load_dwordx4 v[224:227], v[248:249], off offset:576
	global_load_dwordx4 v[236:239], v[250:251], off offset:576
	v_lshl_add_u64 v[130:131], v[232:233], 0, v[168:169]
	global_load_dwordx4 v[136:139], v[130:131], off offset:576
	v_lshl_add_u64 v[252:253], v[232:233], 0, v[172:173]
	global_load_dwordx4 v[140:143], v[252:253], off offset:576
	v_lshl_add_u64 v[130:131], v[232:233], 0, v[176:177]
	global_load_dwordx4 v[144:147], v[130:131], off offset:576
	v_lshl_add_u64 v[252:253], v[232:233], 0, v[180:181]
	global_load_dwordx4 v[148:151], v[252:253], off offset:576
	v_lshl_add_u64 v[130:131], v[232:233], 0, v[184:185]
	global_load_dwordx4 v[152:155], v[130:131], off offset:576
	v_lshl_add_u64 v[252:253], v[232:233], 0, v[188:189]
	global_load_dwordx4 v[208:211], v[252:253], off offset:576
	v_lshl_add_u64 v[130:131], v[232:233], 0, v[192:193]
	global_load_dwordx4 v[212:215], v[130:131], off offset:576
	v_lshl_add_u64 v[252:253], v[232:233], 0, v[196:197]
	global_load_dwordx4 v[216:219], v[252:253], off offset:576
	v_lshl_add_u64 v[130:131], v[232:233], 0, v[168:169]
	global_store_dwordx4 v[130:131], v[62:65], off offset:512
	v_lshl_add_u64 v[252:253], v[232:233], 0, v[172:173]
	global_store_dwordx4 v[252:253], v[58:61], off offset:512
	v_lshl_add_u64 v[130:131], v[232:233], 0, v[176:177]
	global_store_dwordx4 v[130:131], v[54:57], off offset:512
	v_lshl_add_u64 v[252:253], v[232:233], 0, v[180:181]
	global_store_dwordx4 v[252:253], v[50:53], off offset:512
	v_lshl_add_u64 v[130:131], v[232:233], 0, v[184:185]
	global_store_dwordx4 v[130:131], v[46:49], off offset:512
	v_lshl_add_u64 v[252:253], v[232:233], 0, v[188:189]
	global_store_dwordx4 v[252:253], v[42:45], off offset:512
	v_lshl_add_u64 v[130:131], v[232:233], 0, v[192:193]
	global_store_dwordx4 v[130:131], v[34:37], off offset:512
	v_lshl_add_u64 v[252:253], v[232:233], 0, v[196:197]
	global_store_dwordx4 v[252:253], v[26:29], off offset:512
	s_waitcnt vmcnt(8)
;     DI void operator()(const f32x4 (&acc)[2][2][4][2], const pg8::Unit& u, int wr, int wc, int fr, int fq) const {
;     ...
;         for (int bj = 0; bj < 2; ++bj) {
;             f32x4 gv[2], gg[2], bb[2], xv[2][8];
; #pragma unroll
;             for (int n = 0; n < 2; ++n) {
;                 const int c = col0 + bj * 128 + n * 16;
;                 gv[n] = *(const f32x4*)(gtp + c);
;                 gg[n] = (f32x4){1.f, 1.f, 1.f, 1.f}; bb[n] = (f32x4){0.f, 0.f, 0.f, 0.f};
;                 if (mode) { gg[n] = *(const f32x4*)(lg + c); bb[n] = *(const f32x4*)(lb + c); }
; #pragma unroll
;                 for (int q = 0; q < 8; ++q) { const int rr = rl + (q >> 2) * 128 + (q & 3) * 16; xv[n][q] = *(const f32x4*)(sbase + (size_t)rr * D + c); }
;             }
; #pragma unroll
;             for (int n = 0; n < 2; ++n) {
;                 const int c = col0 + bj * 128 + n * 16;
; #pragma unroll
;                 for (int q = 0; q < 8; ++q) {
;                     const int rr = rl + (q >> 2) * 128 + (q & 3) * 16;
;                     f32x4 x = xv[n][q];
;                     if (mode) { const float mu = stats[2 * (rowt + rr)], rs = stats[2 * (rowt + rr) + 1]; x = (x - mu) * rs * gg[n] + bb[n]; }
;                     *(f32x4*)(dbase + (size_t)rr * D + c) = ALPHA * x + gv[n] * acc[q >> 2][bj][q & 3][n];
;                 }
;             }
	v_sub_f32_e32 v139, v139, v134
	v_sub_f32_e32 v138, v138, v134
	v_sub_f32_e32 v137, v137, v134
	v_sub_f32_e32 v136, v136, v134
	v_pk_mul_f32 v[136:137], v[136:137], v[134:135] op_sel:[0,1]
	v_pk_mul_f32 v[138:139], v[138:139], v[134:135] op_sel:[0,1]
	v_pk_fma_f32 v[136:137], v[220:221], v[136:137], v[224:225]
	v_pk_fma_f32 v[138:139], v[222:223], v[138:139], v[226:227]
	v_pk_mul_f32 v[136:137], v[136:137], s[20:21] op_sel_hi:[1,0]
	v_pk_mul_f32 v[138:139], v[138:139], s[20:21] op_sel_hi:[1,0]
	v_pk_fma_f32 v[38:39], v[38:39], v[236:237], v[136:137]
	v_pk_fma_f32 v[40:41], v[40:41], v[238:239], v[138:139]
	v_sub_f32_e32 v143, v143, v156
	v_sub_f32_e32 v142, v142, v156
	v_sub_f32_e32 v141, v141, v156
	v_sub_f32_e32 v140, v140, v156
	v_pk_mul_f32 v[140:141], v[140:141], v[156:157] op_sel:[0,1]
	v_pk_mul_f32 v[142:143], v[142:143], v[156:157] op_sel:[0,1]
	v_pk_fma_f32 v[140:141], v[220:221], v[140:141], v[224:225]
	v_pk_fma_f32 v[142:143], v[222:223], v[142:143], v[226:227]
	v_pk_mul_f32 v[140:141], v[140:141], s[20:21] op_sel_hi:[1,0]
	v_pk_mul_f32 v[142:143], v[142:143], s[20:21] op_sel_hi:[1,0]
	v_pk_fma_f32 v[30:31], v[30:31], v[236:237], v[140:141]
	v_pk_fma_f32 v[32:33], v[32:33], v[238:239], v[142:143]
	v_sub_f32_e32 v147, v147, v206
	v_sub_f32_e32 v146, v146, v206
	v_sub_f32_e32 v145, v145, v206
	v_sub_f32_e32 v144, v144, v206
	v_pk_mul_f32 v[144:145], v[144:145], v[206:207] op_sel:[0,1]
	v_pk_mul_f32 v[146:147], v[146:147], v[206:207] op_sel:[0,1]
	v_pk_fma_f32 v[144:145], v[220:221], v[144:145], v[224:225]
	v_pk_fma_f32 v[146:147], v[222:223], v[146:147], v[226:227]
	v_pk_mul_f32 v[144:145], v[144:145], s[20:21] op_sel_hi:[1,0]
	v_pk_mul_f32 v[146:147], v[146:147], s[20:21] op_sel_hi:[1,0]
	v_pk_fma_f32 v[22:23], v[22:23], v[236:237], v[144:145]
	v_pk_fma_f32 v[24:25], v[24:25], v[238:239], v[146:147]
	v_sub_f32_e32 v151, v151, v230
	v_sub_f32_e32 v150, v150, v230
	v_sub_f32_e32 v149, v149, v230
	v_sub_f32_e32 v148, v148, v230
	v_pk_mul_f32 v[148:149], v[148:149], v[230:231] op_sel:[0,1]
	v_pk_mul_f32 v[150:151], v[150:151], v[230:231] op_sel:[0,1]
	v_pk_fma_f32 v[148:149], v[220:221], v[148:149], v[224:225]
	v_pk_fma_f32 v[150:151], v[222:223], v[150:151], v[226:227]
	v_pk_mul_f32 v[148:149], v[148:149], s[20:21] op_sel_hi:[1,0]
	v_pk_mul_f32 v[150:151], v[150:151], s[20:21] op_sel_hi:[1,0]
	v_pk_fma_f32 v[18:19], v[18:19], v[236:237], v[148:149]
	v_pk_fma_f32 v[20:21], v[20:21], v[238:239], v[150:151]
	v_sub_f32_e32 v155, v155, v234
	v_sub_f32_e32 v154, v154, v234
	v_sub_f32_e32 v153, v153, v234
	v_sub_f32_e32 v152, v152, v234
	v_pk_mul_f32 v[152:153], v[152:153], v[234:235] op_sel:[0,1]
	v_pk_mul_f32 v[154:155], v[154:155], v[234:235] op_sel:[0,1]
	v_pk_fma_f32 v[152:153], v[220:221], v[152:153], v[224:225]
	v_pk_fma_f32 v[154:155], v[222:223], v[154:155], v[226:227]
	v_pk_mul_f32 v[152:153], v[152:153], s[20:21] op_sel_hi:[1,0]
	v_pk_mul_f32 v[154:155], v[154:155], s[20:21] op_sel_hi:[1,0]
	v_pk_fma_f32 v[14:15], v[14:15], v[236:237], v[152:153]
	v_pk_fma_f32 v[16:17], v[16:17], v[238:239], v[154:155]
	v_sub_f32_e32 v211, v211, v240
	v_sub_f32_e32 v210, v210, v240
	v_sub_f32_e32 v209, v209, v240
	v_sub_f32_e32 v208, v208, v240
	v_pk_mul_f32 v[208:209], v[208:209], v[240:241] op_sel:[0,1]
	v_pk_mul_f32 v[210:211], v[210:211], v[240:241] op_sel:[0,1]
	v_pk_fma_f32 v[208:209], v[220:221], v[208:209], v[224:225]
	v_pk_fma_f32 v[210:211], v[222:223], v[210:211], v[226:227]
	v_pk_mul_f32 v[208:209], v[208:209], s[20:21] op_sel_hi:[1,0]
	v_pk_mul_f32 v[210:211], v[210:211], s[20:21] op_sel_hi:[1,0]
	v_pk_fma_f32 v[10:11], v[10:11], v[236:237], v[208:209]
	v_pk_fma_f32 v[12:13], v[12:13], v[238:239], v[210:211]
	v_sub_f32_e32 v215, v215, v242
	v_sub_f32_e32 v214, v214, v242
	v_sub_f32_e32 v213, v213, v242
	v_sub_f32_e32 v212, v212, v242
	v_pk_mul_f32 v[212:213], v[212:213], v[242:243] op_sel:[0,1]
	v_pk_mul_f32 v[214:215], v[214:215], v[242:243] op_sel:[0,1]
	v_pk_fma_f32 v[212:213], v[220:221], v[212:213], v[224:225]
	v_pk_fma_f32 v[214:215], v[222:223], v[214:215], v[226:227]
	v_pk_mul_f32 v[212:213], v[212:213], s[20:21] op_sel_hi:[1,0]
	v_pk_mul_f32 v[214:215], v[214:215], s[20:21] op_sel_hi:[1,0]
	v_pk_fma_f32 v[6:7], v[6:7], v[236:237], v[212:213]
	v_pk_fma_f32 v[8:9], v[8:9], v[238:239], v[214:215]
	v_sub_f32_e32 v219, v219, v244
	v_sub_f32_e32 v218, v218, v244
	v_sub_f32_e32 v217, v217, v244
	v_sub_f32_e32 v216, v216, v244
	v_pk_mul_f32 v[216:217], v[216:217], v[244:245] op_sel:[0,1]
	v_pk_mul_f32 v[218:219], v[218:219], v[244:245] op_sel:[0,1]
	v_pk_fma_f32 v[216:217], v[220:221], v[216:217], v[224:225]
	v_pk_fma_f32 v[218:219], v[222:223], v[218:219], v[226:227]
	v_pk_mul_f32 v[216:217], v[216:217], s[20:21] op_sel_hi:[1,0]
	v_pk_mul_f32 v[218:219], v[218:219], s[20:21] op_sel_hi:[1,0]
	v_pk_fma_f32 v[2:3], v[2:3], v[236:237], v[216:217]
	v_pk_fma_f32 v[4:5], v[4:5], v[238:239], v[218:219]
	v_lshl_add_u64 v[130:131], v[232:233], 0, v[168:169]
	global_store_dwordx4 v[130:131], v[38:41], off offset:576
	v_lshl_add_u64 v[252:253], v[232:233], 0, v[172:173]
	global_store_dwordx4 v[252:253], v[30:33], off offset:576
	v_lshl_add_u64 v[130:131], v[232:233], 0, v[176:177]
	global_store_dwordx4 v[130:131], v[22:25], off offset:576
	v_lshl_add_u64 v[252:253], v[232:233], 0, v[180:181]
	global_store_dwordx4 v[252:253], v[18:21], off offset:576
	v_lshl_add_u64 v[130:131], v[232:233], 0, v[184:185]
	global_store_dwordx4 v[130:131], v[14:17], off offset:576
	v_lshl_add_u64 v[252:253], v[232:233], 0, v[188:189]
	global_store_dwordx4 v[252:253], v[10:13], off offset:576
	v_lshl_add_u64 v[130:131], v[232:233], 0, v[192:193]
	global_store_dwordx4 v[130:131], v[6:9], off offset:576
	v_lshl_add_u64 v[252:253], v[232:233], 0, v[196:197]
	global_store_dwordx4 v[252:253], v[2:5], off offset:576
	s_cbranch_vccz .LBB0_2300
	s_waitcnt vmcnt(0)
	s_cmpk_gt_u32 s21, 0xff
	s_cbranch_scc1 .LBB0_2309
	s_barrier
